# v6_nt_x_loads_wt_stores
# speedup vs baseline: 1.0490x; 1.0400x over previous
.LBB0_14:
	v_add_u32_e32 v32, s35, v60
	v_ashrrev_i32_e32 v33, 31, v32
	v_lshl_add_u64 v[34:35], v[32:33], 2, v[56:57]
	v_lshlrev_b64 v[32:33], 11, v[32:33]
	global_load_dwordx4 v[44:47], v[34:35], off nt
	global_load_dwordx4 v[40:43], v[34:35], off offset:16 nt
	v_lshl_add_u64 v[62:63], v[34:35], 0, s[0:1]
	v_add_co_u32_e32 v34, vcc, s26, v34
	v_lshl_add_u64 v[64:65], v[54:55], 0, v[32:33]
	s_nop 0
	v_addc_co_u32_e32 v35, vcc, 0, v35, vcc
	global_load_dwordx4 v[36:39], v[34:35], off nt
	s_nop 0
	global_load_dwordx4 v[32:35], v[62:63], off offset:16 nt
	global_load_dword v50, v[64:65], off nt
	global_load_dword v68, v[64:65], off offset:2048 nt
	global_load_dword v69, v[64:65], off offset:64 nt
	global_load_dword v70, v[64:65], off offset:2112 nt
	global_load_dword v71, v[64:65], off offset:128 nt
	global_load_dword v72, v[64:65], off offset:2176 nt
	global_load_dword v73, v[64:65], off offset:2240 nt
	global_load_dword v74, v[64:65], off offset:192 nt
	v_add_co_u32_e32 v62, vcc, s27, v64
	s_add_i32 s35, s35, 32
	s_nop 0
	v_addc_co_u32_e32 v63, vcc, 0, v65, vcc
	v_add_co_u32_e32 v66, vcc, s28, v64
	s_cmpk_lg_i32 s35, 0x80
	s_nop 0
	v_addc_co_u32_e32 v67, vcc, 0, v65, vcc
	v_add_co_u32_e32 v64, vcc, s29, v64
	s_waitcnt vmcnt(11)
	v_bfe_u32 v94, v45, 16, 1
	v_addc_co_u32_e32 v65, vcc, 0, v65, vcc
	global_load_dword v75, v[64:65], off nt
	global_load_dword v76, v[64:65], off offset:2048 nt
	global_load_dword v77, v[64:65], off offset:64 nt
	global_load_dword v78, v[64:65], off offset:2112 nt
	global_load_dword v79, v[64:65], off offset:128 nt
	global_load_dword v80, v[64:65], off offset:2176 nt
	global_load_dword v81, v[64:65], off offset:2240 nt
	global_load_dword v82, v[66:67], off offset:-4096 nt
	s_nop 0
	global_load_dword v64, v[64:65], off offset:192 nt
	s_nop 0
	global_load_dword v65, v[62:63], off offset:2048 nt
	global_load_dword v83, v[66:67], off nt
	global_load_dword v84, v[66:67], off offset:2048 nt
	global_load_dword v85, v[62:63], off offset:2112 nt
	global_load_dword v86, v[62:63], off offset:64 nt
	global_load_dword v87, v[66:67], off offset:64 nt
	global_load_dword v88, v[66:67], off offset:2112 nt
	global_load_dword v89, v[62:63], off offset:2176 nt
	global_load_dword v90, v[62:63], off offset:128 nt
	global_load_dword v91, v[66:67], off offset:128 nt
	global_load_dword v92, v[66:67], off offset:2176 nt
	global_load_dword v93, v[62:63], off offset:2240 nt
	s_nop 0
	global_load_dword v62, v[62:63], off offset:192 nt
	s_nop 0
	global_load_dword v63, v[66:67], off offset:2240 nt
	s_nop 0
	global_load_dword v66, v[66:67], off offset:192 nt
	v_bfe_u32 v67, v44, 16, 1
	v_bfe_u32 v95, v46, 16, 1
	v_bfe_u32 v97, v47, 16, 1
	s_waitcnt vmcnt(34)
	v_bfe_u32 v98, v40, 16, 1
	v_bfe_u32 v100, v41, 16, 1
	v_bfe_u32 v101, v42, 16, 1
	v_bfe_u32 v102, v43, 16, 1
	v_add3_u32 v44, v44, v67, s24
	v_add3_u32 v45, v45, v94, s24
	v_add3_u32 v46, v46, v95, s24
	v_add3_u32 v47, v47, v97, s24
	v_add3_u32 v40, v40, v98, s24
	v_add3_u32 v41, v41, v100, s24
	v_add3_u32 v42, v42, v101, s24
	v_add3_u32 v43, v43, v102, s24
	s_waitcnt vmcnt(33)
	v_bfe_u32 v67, v36, 16, 1
	v_bfe_u32 v94, v37, 16, 1
	v_bfe_u32 v95, v38, 16, 1
	v_bfe_u32 v97, v39, 16, 1
	s_waitcnt vmcnt(32)
	v_bfe_u32 v98, v32, 16, 1
	v_bfe_u32 v100, v33, 16, 1
	v_bfe_u32 v101, v34, 16, 1
	v_bfe_u32 v102, v35, 16, 1
	s_waitcnt vmcnt(31)
	v_bfe_u32 v103, v50, 16, 1
	s_waitcnt vmcnt(30)
	v_bfe_u32 v104, v68, 16, 1
	s_waitcnt vmcnt(29)
	v_bfe_u32 v105, v69, 16, 1
	s_waitcnt vmcnt(28)
	v_bfe_u32 v106, v70, 16, 1
	s_waitcnt vmcnt(27)
	v_bfe_u32 v107, v71, 16, 1
	s_waitcnt vmcnt(26)
	v_bfe_u32 v108, v72, 16, 1
	s_waitcnt vmcnt(24)
	v_bfe_u32 v109, v74, 16, 1
	v_bfe_u32 v110, v73, 16, 1
	v_add3_u32 v36, v36, v67, s24
	v_add3_u32 v94, v37, v94, s24
	v_add3_u32 v38, v38, v95, s24
	v_add3_u32 v95, v39, v97, s24
	v_add3_u32 v39, v32, v98, s24
	v_add3_u32 v97, v33, v100, s24
	v_add3_u32 v37, v34, v101, s24
	v_add3_u32 v67, v35, v102, s24
	v_lshrrev_b32_e32 v32, 16, v44
	v_perm_b32 v35, v43, v42, s30
	v_lshrrev_b32_e32 v33, 16, v46
	v_lshrrev_b32_e32 v34, 16, v40
	v_add3_u32 v40, v50, v103, s24
	v_add3_u32 v42, v68, v104, s24
	v_add3_u32 v46, v69, v105, s24
	v_add3_u32 v50, v70, v106, s24
	v_add3_u32 v70, v71, v107, s24
	v_add3_u32 v71, v72, v108, s24
	v_add3_u32 v74, v74, v109, s24
	v_add3_u32 v73, v73, v110, s24
	v_and_or_b32 v32, v45, s25, v32
	v_and_or_b32 v33, v47, s25, v33
	v_and_or_b32 v34, v41, s25, v34
	v_lshrrev_b32_e32 v40, 16, v40
	v_lshrrev_b32_e32 v46, 16, v46
	s_waitcnt vmcnt(23)
	v_bfe_u32 v43, v75, 16, 1
	s_waitcnt vmcnt(22)
	v_bfe_u32 v44, v76, 16, 1
	s_waitcnt vmcnt(21)
	v_bfe_u32 v68, v77, 16, 1
	s_waitcnt vmcnt(20)
	v_bfe_u32 v69, v78, 16, 1
	s_waitcnt vmcnt(19)
	v_bfe_u32 v72, v79, 16, 1
	s_waitcnt vmcnt(18)
	v_bfe_u32 v98, v80, 16, 1
	s_waitcnt vmcnt(17)
	v_bfe_u32 v101, v81, 16, 1
	s_waitcnt vmcnt(16)
	v_bfe_u32 v102, v82, 16, 1
	s_waitcnt vmcnt(15)
	v_bfe_u32 v100, v64, 16, 1
	s_waitcnt vmcnt(14)
	v_bfe_u32 v103, v65, 16, 1
	s_waitcnt vmcnt(13)
	v_bfe_u32 v104, v83, 16, 1
	s_waitcnt vmcnt(12)
	v_bfe_u32 v105, v84, 16, 1
	s_waitcnt vmcnt(11)
	v_bfe_u32 v107, v85, 16, 1
	s_waitcnt vmcnt(10)
	v_bfe_u32 v106, v86, 16, 1
	s_waitcnt vmcnt(9)
	v_bfe_u32 v108, v87, 16, 1
	s_waitcnt vmcnt(8)
	v_bfe_u32 v109, v88, 16, 1
	s_waitcnt vmcnt(7)
	v_bfe_u32 v111, v89, 16, 1
	s_waitcnt vmcnt(6)
	v_bfe_u32 v110, v90, 16, 1
	s_waitcnt vmcnt(5)
	v_bfe_u32 v112, v91, 16, 1
	s_waitcnt vmcnt(4)
	v_bfe_u32 v113, v92, 16, 1
	s_waitcnt vmcnt(3)
	v_bfe_u32 v115, v93, 16, 1
	s_waitcnt vmcnt(2)
	v_bfe_u32 v114, v62, 16, 1
	s_waitcnt vmcnt(1)
	v_bfe_u32 v117, v63, 16, 1
	s_waitcnt vmcnt(0)
	v_bfe_u32 v116, v66, 16, 1
	v_add3_u32 v41, v75, v43, s24
	v_add3_u32 v43, v76, v44, s24
	v_add3_u32 v44, v77, v68, s24
	v_add3_u32 v45, v78, v69, s24
	v_add3_u32 v47, v79, v72, s24
	v_add3_u32 v68, v80, v98, s24
	v_lshrrev_b32_e32 v69, 16, v70
	v_add3_u32 v70, v81, v101, s24
	v_lshrrev_b32_e32 v72, 16, v74
	v_add3_u32 v74, v82, v102, s24
	v_add3_u32 v76, v83, v104, s24
	v_add3_u32 v77, v84, v105, s24
	v_add3_u32 v78, v86, v106, s24
	v_add3_u32 v80, v87, v108, s24
	v_add3_u32 v81, v88, v109, s24
	v_add3_u32 v82, v90, v110, s24
	v_add3_u32 v84, v91, v112, s24
	v_add3_u32 v86, v62, v114, s24
	v_add3_u32 v88, v66, v116, s24
	v_add3_u32 v64, v64, v100, s24
	v_add3_u32 v75, v65, v103, s24
	v_add3_u32 v79, v85, v107, s24
	v_add3_u32 v83, v89, v111, s24
	v_add3_u32 v85, v92, v113, s24
	v_add3_u32 v87, v93, v115, s24
	v_add3_u32 v89, v63, v117, s24
	v_lshrrev_b32_e32 v90, 16, v38
	v_lshrrev_b32_e32 v91, 16, v39
	v_and_or_b32 v38, v42, s25, v40
	v_perm_b32 v41, v43, v41, s30
	v_and_or_b32 v42, v50, s25, v46
	v_perm_b32 v45, v45, v44, s30
	v_perm_b32 v65, v68, v47, s30
	v_lshrrev_b32_e32 v39, 16, v74
	v_lshrrev_b32_e32 v40, 16, v76
	v_lshrrev_b32_e32 v43, 16, v78
	v_lshrrev_b32_e32 v44, 16, v80
	v_lshrrev_b32_e32 v46, 16, v82
	v_lshrrev_b32_e32 v47, 16, v84
	v_lshrrev_b32_e32 v50, 16, v86
	v_lshrrev_b32_e32 v68, 16, v88
	v_perm_b32 v37, v67, v37, s30
	v_and_or_b32 v62, v71, s25, v69
	v_and_or_b32 v66, v73, s25, v72
	v_perm_b32 v69, v70, v64, s30
	v_and_or_b32 v39, v75, s25, v39
	v_and_or_b32 v40, v77, s25, v40
	v_and_or_b32 v43, v79, s25, v43
	v_and_or_b32 v44, v81, s25, v44
	v_and_or_b32 v63, v83, s25, v46
	v_and_or_b32 v64, v85, s25, v47
	v_and_or_b32 v67, v87, s25, v50
	v_and_or_b32 v68, v89, s25, v68
	v_lshrrev_b32_e32 v36, 16, v36
	v_mfma_f32_16x16x32_bf16 v[28:31], v[38:41], v[32:35], v[28:31]
	v_mfma_f32_16x16x32_bf16 v[24:27], v[42:45], v[32:35], v[24:27]
	v_mfma_f32_16x16x32_bf16 v[20:23], v[62:65], v[32:35], v[20:23]
	v_mfma_f32_16x16x32_bf16 v[16:19], v[66:69], v[32:35], v[16:19]
	v_and_or_b32 v34, v94, s25, v36
	v_and_or_b32 v35, v95, s25, v90
	v_and_or_b32 v36, v97, s25, v91
	s_nop 1
	v_mfma_f32_16x16x32_bf16 v[12:15], v[38:41], v[34:37], v[12:15]
	v_mfma_f32_16x16x32_bf16 v[8:11], v[42:45], v[34:37], v[8:11]
	v_mfma_f32_16x16x32_bf16 v[4:7], v[62:65], v[34:37], v[4:7]
	v_mfma_f32_16x16x32_bf16 v[0:3], v[66:69], v[34:37], v[0:3]
	s_cbranch_scc1 .LBB0_14
	ds_write_b128 v61, v[28:31]
	ds_write_b128 v61, v[24:27] offset:1024
	ds_write_b128 v61, v[20:23] offset:2048
	ds_write_b128 v61, v[16:19] offset:3072
	ds_write_b128 v61, v[12:15] offset:4096
	ds_write_b128 v61, v[8:11] offset:5120
	ds_write_b128 v61, v[4:7] offset:6144
	ds_write_b128 v61, v[0:3] offset:7168
	s_waitcnt lgkmcnt(0)
	s_barrier
	ds_read_b128 v[0:3], v49
	ds_read_b128 v[4:7], v49 offset:8192
	ds_read_b128 v[8:11], v49 offset:16384
	s_lshl_b64 s[20:21], s[20:21], 19
	s_add_u32 s20, s22, s20
	s_waitcnt lgkmcnt(2)
	v_pk_add_f32 v[2:3], v[2:3], 0 op_sel_hi:[1,0]
	v_pk_add_f32 v[12:13], v[0:1], 0 op_sel_hi:[1,0]
	s_waitcnt lgkmcnt(1)
	v_pk_add_f32 v[6:7], v[2:3], v[6:7]
	ds_read_b128 v[0:3], v49 offset:24576
	v_pk_add_f32 v[12:13], v[12:13], v[4:5]
	s_waitcnt lgkmcnt(1)
	v_pk_add_f32 v[10:11], v[6:7], v[10:11]
	ds_read_b128 v[4:7], v49 offset:32768
	v_pk_add_f32 v[8:9], v[12:13], v[8:9]
	s_waitcnt lgkmcnt(1)
	v_pk_add_f32 v[10:11], v[10:11], v[2:3]
	v_pk_add_f32 v[12:13], v[8:9], v[0:1]
	ds_read_b128 v[0:3], v49 offset:40960
	s_waitcnt lgkmcnt(1)
	v_pk_add_f32 v[14:15], v[10:11], v[6:7]
	ds_read_b128 v[6:9], v49 offset:49152
	v_pk_add_f32 v[4:5], v[12:13], v[4:5]
	ds_read_b128 v[10:13], v49 offset:57344
	s_waitcnt lgkmcnt(2)
	v_pk_add_f32 v[0:1], v[4:5], v[0:1]
	v_add_u32_e32 v4, s34, v58
	s_addc_u32 s21, s23, s21
	s_lshl_b32 s34, s31, 16
	s_and_b32 s34, s34, 0x40000
	s_add_u32 s20, s20, s34
	v_ashrrev_i32_e32 v5, 31, v4
	s_addc_u32 s21, s21, 0
	v_lshlrev_b64 v[4:5], 9, v[4:5]
	s_waitcnt lgkmcnt(1)
	v_pk_add_f32 v[0:1], v[0:1], v[6:7]
	v_lshl_add_u64 v[4:5], s[20:21], 0, v[4:5]
	s_and_b32 s20, s33, 0xc0
	s_waitcnt lgkmcnt(0)
	v_pk_add_f32 v[0:1], v[0:1], v[10:11]
	v_or_b32_e32 v6, s20, v59
	v_pk_add_f32 v[2:3], v[14:15], v[2:3]
	v_lshlrev_b32_e32 v50, 1, v6
	v_bfe_u32 v6, v0, 16, 1
	v_pk_add_f32 v[2:3], v[2:3], v[8:9]
	v_add3_u32 v0, v0, v6, s24
	v_bfe_u32 v6, v1, 16, 1
	v_pk_add_f32 v[2:3], v[2:3], v[12:13]
	v_lshrrev_b32_e32 v0, 16, v0
	v_add3_u32 v1, v1, v6, s24
	v_and_or_b32 v0, v1, s25, v0
	v_bfe_u32 v1, v2, 16, 1
	v_add3_u32 v1, v2, v1, s24
	v_bfe_u32 v2, v3, 16, 1
	v_lshrrev_b32_e32 v1, 16, v1
	v_add3_u32 v2, v3, v2, s24
	s_add_i32 s31, s31, s68
	v_lshl_add_u64 v[4:5], v[4:5], 0, v[50:51]
	v_and_or_b32 v1, v2, s25, v1
	s_cmpk_gt_i32 s31, 0xff
	global_store_dwordx2 v[4:5], v[0:1], off
	s_barrier
	s_cbranch_scc0 .LBB0_13

.LBB0_26:
	v_ashrrev_i32_e32 v0, 5, v96
	s_lshl_b64 s[36:37], s[24:25], 2
	v_add_u32_e32 v18, s58, v0
	v_and_b32_e32 v0, 31, v96
	s_add_u32 s34, s34, s36
	s_addc_u32 s35, s35, s37
	v_lshlrev_b32_e32 v0, 2, v0
	v_mov_b32_e32 v1, 0
	v_ashrrev_i32_e32 v2, 31, v18
	v_lshl_add_u64 v[0:1], s[34:35], 0, v[0:1]
	v_mul_lo_u32 v4, s30, v2
	v_mul_lo_u32 v5, s31, v18
	v_mad_u64_u32 v[2:3], s[34:35], s30, v18, 0
	v_add3_u32 v3, v3, v4, v5
	v_add_u32_e32 v4, 2, v18
	v_ashrrev_i32_e32 v5, 31, v4
	v_mul_lo_u32 v6, s30, v5
	v_mul_lo_u32 v7, s31, v4
	v_mad_u64_u32 v[4:5], s[34:35], s30, v4, 0
	v_add3_u32 v5, v5, v6, v7
	v_add_u32_e32 v6, 4, v18
	v_ashrrev_i32_e32 v7, 31, v6
	v_mul_lo_u32 v8, s30, v7
	v_mul_lo_u32 v9, s31, v6
	v_mad_u64_u32 v[6:7], s[34:35], s30, v6, 0
	v_add3_u32 v7, v7, v8, v9
	v_add_u32_e32 v8, 6, v18
	v_ashrrev_i32_e32 v9, 31, v8
	v_mul_lo_u32 v10, s30, v9
	v_mul_lo_u32 v11, s31, v8
	v_mad_u64_u32 v[8:9], s[34:35], s30, v8, 0
	v_add3_u32 v9, v9, v10, v11
	v_add_u32_e32 v10, 8, v18
	v_ashrrev_i32_e32 v11, 31, v10
	v_mul_lo_u32 v12, s30, v11
	v_mul_lo_u32 v13, s31, v10
	v_mad_u64_u32 v[10:11], s[34:35], s30, v10, 0
	v_add3_u32 v11, v11, v12, v13
	v_add_u32_e32 v12, 10, v18
	v_ashrrev_i32_e32 v13, 31, v12
	v_mul_lo_u32 v14, s30, v13
	v_mul_lo_u32 v15, s31, v12
	v_mad_u64_u32 v[12:13], s[34:35], s30, v12, 0
	v_add3_u32 v13, v13, v14, v15
	v_add_u32_e32 v14, 12, v18
	v_ashrrev_i32_e32 v15, 31, v14
	v_mul_lo_u32 v16, s30, v15
	v_mul_lo_u32 v17, s31, v14
	v_mad_u64_u32 v[14:15], s[34:35], s30, v14, 0
	v_add3_u32 v15, v15, v16, v17
	v_add_u32_e32 v16, 14, v18
	v_ashrrev_i32_e32 v17, 31, v16
	v_mul_lo_u32 v19, s30, v17
	v_mul_lo_u32 v20, s31, v16
	v_mad_u64_u32 v[16:17], s[34:35], s30, v16, 0
	v_lshl_add_u64 v[2:3], v[2:3], 2, v[0:1]
	v_add3_u32 v17, v17, v19, v20
	v_lshl_add_u64 v[4:5], v[4:5], 2, v[0:1]
	v_lshl_add_u64 v[6:7], v[6:7], 2, v[0:1]
	v_lshl_add_u64 v[8:9], v[8:9], 2, v[0:1]
	v_lshl_add_u64 v[10:11], v[10:11], 2, v[0:1]
	v_lshl_add_u64 v[12:13], v[12:13], 2, v[0:1]
	v_lshl_add_u64 v[14:15], v[14:15], 2, v[0:1]
	v_lshl_add_u64 v[16:17], v[16:17], 2, v[0:1]
	global_load_dword v32, v[2:3], off nt
	global_load_dword v33, v[4:5], off nt
	global_load_dword v34, v[6:7], off nt
	global_load_dword v35, v[8:9], off nt
	global_load_dword v36, v[10:11], off nt
	global_load_dword v37, v[12:13], off nt
	global_load_dword v38, v[14:15], off nt
	global_load_dword v39, v[16:17], off nt
	v_add_u32_e32 v2, 16, v18
	v_ashrrev_i32_e32 v3, 31, v2
	v_mul_lo_u32 v4, s30, v3
	v_mul_lo_u32 v5, s31, v2
	v_mad_u64_u32 v[2:3], s[34:35], s30, v2, 0
	v_add3_u32 v3, v3, v4, v5
	v_add_u32_e32 v4, 18, v18
	v_ashrrev_i32_e32 v5, 31, v4
	v_mul_lo_u32 v6, s30, v5
	v_mul_lo_u32 v7, s31, v4
	v_mad_u64_u32 v[4:5], s[34:35], s30, v4, 0
	v_add3_u32 v5, v5, v6, v7
	v_add_u32_e32 v6, 20, v18
	v_ashrrev_i32_e32 v7, 31, v6
	v_mul_lo_u32 v8, s30, v7
	v_mul_lo_u32 v9, s31, v6
	v_mad_u64_u32 v[6:7], s[34:35], s30, v6, 0
	v_add3_u32 v7, v7, v8, v9
	v_add_u32_e32 v8, 22, v18
	v_ashrrev_i32_e32 v9, 31, v8
	v_mul_lo_u32 v10, s30, v9
	v_mul_lo_u32 v11, s31, v8
	v_mad_u64_u32 v[8:9], s[34:35], s30, v8, 0
	v_add3_u32 v9, v9, v10, v11
	v_add_u32_e32 v10, 24, v18
	v_ashrrev_i32_e32 v11, 31, v10
	v_mul_lo_u32 v12, s30, v11
	v_mul_lo_u32 v13, s31, v10
	v_mad_u64_u32 v[10:11], s[34:35], s30, v10, 0
	v_add3_u32 v11, v11, v12, v13
	v_add_u32_e32 v12, 26, v18
	v_ashrrev_i32_e32 v13, 31, v12
	v_mul_lo_u32 v14, s30, v13
	v_mul_lo_u32 v15, s31, v12
	v_mad_u64_u32 v[12:13], s[34:35], s30, v12, 0
	v_add3_u32 v13, v13, v14, v15
	v_add_u32_e32 v14, 28, v18
	v_ashrrev_i32_e32 v15, 31, v14
	v_mul_lo_u32 v16, s30, v15
	v_mul_lo_u32 v17, s31, v14
	v_mad_u64_u32 v[14:15], s[34:35], s30, v14, 0
	v_add3_u32 v15, v15, v16, v17
	v_add_u32_e32 v16, 30, v18
	v_ashrrev_i32_e32 v17, 31, v16
	v_mul_lo_u32 v19, s30, v17
	v_mul_lo_u32 v20, s31, v16
	v_mad_u64_u32 v[16:17], s[34:35], s30, v16, 0
	v_lshl_add_u64 v[2:3], v[2:3], 2, v[0:1]
	v_add3_u32 v17, v17, v19, v20
	v_lshl_add_u64 v[4:5], v[4:5], 2, v[0:1]
	v_lshl_add_u64 v[6:7], v[6:7], 2, v[0:1]
	v_lshl_add_u64 v[8:9], v[8:9], 2, v[0:1]
	v_lshl_add_u64 v[10:11], v[10:11], 2, v[0:1]
	v_lshl_add_u64 v[12:13], v[12:13], 2, v[0:1]
	v_lshl_add_u64 v[14:15], v[14:15], 2, v[0:1]
	v_lshl_add_u64 v[16:17], v[16:17], 2, v[0:1]
	global_load_dword v40, v[2:3], off nt
	global_load_dword v41, v[4:5], off nt
	global_load_dword v42, v[6:7], off nt
	global_load_dword v43, v[8:9], off nt
	global_load_dword v44, v[10:11], off nt
	global_load_dword v45, v[12:13], off nt
	global_load_dword v46, v[14:15], off nt
	global_load_dword v47, v[16:17], off nt
	v_add_u32_e32 v2, 32, v18
	v_ashrrev_i32_e32 v3, 31, v2
	v_mul_lo_u32 v4, s30, v3
	v_mul_lo_u32 v5, s31, v2
	v_mad_u64_u32 v[2:3], s[34:35], s30, v2, 0
	v_add3_u32 v3, v3, v4, v5
	v_add_u32_e32 v4, 34, v18
	v_ashrrev_i32_e32 v5, 31, v4
	v_mul_lo_u32 v6, s30, v5
	v_mul_lo_u32 v7, s31, v4
	v_mad_u64_u32 v[4:5], s[34:35], s30, v4, 0
	v_add3_u32 v5, v5, v6, v7
	v_add_u32_e32 v6, 36, v18
	v_ashrrev_i32_e32 v7, 31, v6
	v_mul_lo_u32 v8, s30, v7
	v_mul_lo_u32 v9, s31, v6
	v_mad_u64_u32 v[6:7], s[34:35], s30, v6, 0
	v_add3_u32 v7, v7, v8, v9
	v_add_u32_e32 v8, 38, v18
	v_ashrrev_i32_e32 v9, 31, v8
	v_mul_lo_u32 v10, s30, v9
	v_mul_lo_u32 v11, s31, v8
	v_mad_u64_u32 v[8:9], s[34:35], s30, v8, 0
	v_add3_u32 v9, v9, v10, v11
	v_add_u32_e32 v10, 40, v18
	v_ashrrev_i32_e32 v11, 31, v10
	v_mul_lo_u32 v12, s30, v11
	v_mul_lo_u32 v13, s31, v10
	v_mad_u64_u32 v[10:11], s[34:35], s30, v10, 0
	v_add3_u32 v11, v11, v12, v13
	v_add_u32_e32 v12, 42, v18
	v_ashrrev_i32_e32 v13, 31, v12
	v_mul_lo_u32 v14, s30, v13
	v_mul_lo_u32 v15, s31, v12
	v_mad_u64_u32 v[12:13], s[34:35], s30, v12, 0
	v_add3_u32 v13, v13, v14, v15
	v_add_u32_e32 v14, 44, v18
	v_ashrrev_i32_e32 v15, 31, v14
	v_mul_lo_u32 v16, s30, v15
	v_mul_lo_u32 v17, s31, v14
	v_mad_u64_u32 v[14:15], s[34:35], s30, v14, 0
	v_add3_u32 v15, v15, v16, v17
	v_add_u32_e32 v16, 46, v18
	v_ashrrev_i32_e32 v17, 31, v16
	v_mul_lo_u32 v19, s30, v17
	v_mul_lo_u32 v20, s31, v16
	v_mad_u64_u32 v[16:17], s[34:35], s30, v16, 0
	v_lshl_add_u64 v[2:3], v[2:3], 2, v[0:1]
	v_add3_u32 v17, v17, v19, v20
	v_lshl_add_u64 v[4:5], v[4:5], 2, v[0:1]
	v_lshl_add_u64 v[6:7], v[6:7], 2, v[0:1]
	v_lshl_add_u64 v[8:9], v[8:9], 2, v[0:1]
	v_lshl_add_u64 v[10:11], v[10:11], 2, v[0:1]
	v_lshl_add_u64 v[12:13], v[12:13], 2, v[0:1]
	v_lshl_add_u64 v[14:15], v[14:15], 2, v[0:1]
	v_lshl_add_u64 v[16:17], v[16:17], 2, v[0:1]
	global_load_dword v48, v[2:3], off nt
	global_load_dword v49, v[4:5], off nt
	global_load_dword v50, v[6:7], off nt
	global_load_dword v51, v[8:9], off nt
	global_load_dword v52, v[10:11], off nt
	global_load_dword v53, v[12:13], off nt
	global_load_dword v54, v[14:15], off nt
	global_load_dword v55, v[16:17], off nt
	v_add_u32_e32 v2, 48, v18
	v_ashrrev_i32_e32 v3, 31, v2
	v_mul_lo_u32 v4, s30, v3
	v_mul_lo_u32 v5, s31, v2
	v_mad_u64_u32 v[2:3], s[34:35], s30, v2, 0
	v_add3_u32 v3, v3, v4, v5
	v_add_u32_e32 v4, 50, v18
	v_ashrrev_i32_e32 v5, 31, v4
	v_mul_lo_u32 v6, s30, v5
	v_mul_lo_u32 v7, s31, v4
	v_mad_u64_u32 v[4:5], s[34:35], s30, v4, 0
	v_add3_u32 v5, v5, v6, v7
	v_add_u32_e32 v6, 52, v18
	v_ashrrev_i32_e32 v7, 31, v6
	v_mul_lo_u32 v8, s30, v7
	v_mul_lo_u32 v9, s31, v6
	v_mad_u64_u32 v[6:7], s[34:35], s30, v6, 0
	v_add3_u32 v7, v7, v8, v9
	v_add_u32_e32 v8, 54, v18
	v_ashrrev_i32_e32 v9, 31, v8
	v_mul_lo_u32 v10, s30, v9
	v_mul_lo_u32 v11, s31, v8
	v_mad_u64_u32 v[8:9], s[34:35], s30, v8, 0
	v_add3_u32 v9, v9, v10, v11
	v_add_u32_e32 v10, 56, v18
	v_ashrrev_i32_e32 v11, 31, v10
	v_mul_lo_u32 v12, s30, v11
	v_mul_lo_u32 v13, s31, v10
	v_mad_u64_u32 v[10:11], s[34:35], s30, v10, 0
	v_add3_u32 v11, v11, v12, v13
	v_add_u32_e32 v12, 58, v18
	v_ashrrev_i32_e32 v13, 31, v12
	v_mul_lo_u32 v14, s30, v13
	v_mul_lo_u32 v15, s31, v12
	v_mad_u64_u32 v[12:13], s[34:35], s30, v12, 0
	v_add3_u32 v13, v13, v14, v15
	v_add_u32_e32 v14, 60, v18
	v_ashrrev_i32_e32 v15, 31, v14
	v_mul_lo_u32 v16, s30, v15
	v_mul_lo_u32 v17, s31, v14
	v_mad_u64_u32 v[14:15], s[34:35], s30, v14, 0
	v_add3_u32 v15, v15, v16, v17
	v_add_u32_e32 v16, 62, v18
	v_ashrrev_i32_e32 v17, 31, v16
	v_mul_lo_u32 v18, s30, v17
	v_mul_lo_u32 v19, s31, v16
	v_mad_u64_u32 v[16:17], s[30:31], s30, v16, 0
	v_lshl_add_u64 v[2:3], v[2:3], 2, v[0:1]
	v_add3_u32 v17, v17, v18, v19
	v_lshl_add_u64 v[4:5], v[4:5], 2, v[0:1]
	v_lshl_add_u64 v[6:7], v[6:7], 2, v[0:1]
	v_lshl_add_u64 v[8:9], v[8:9], 2, v[0:1]
	v_lshl_add_u64 v[10:11], v[10:11], 2, v[0:1]
	v_lshl_add_u64 v[12:13], v[12:13], 2, v[0:1]
	v_lshl_add_u64 v[14:15], v[14:15], 2, v[0:1]
	v_lshl_add_u64 v[0:1], v[16:17], 2, v[0:1]
	global_load_dword v56, v[2:3], off nt
	global_load_dword v57, v[4:5], off nt
	global_load_dword v58, v[6:7], off nt
	global_load_dword v59, v[8:9], off nt
	global_load_dword v60, v[10:11], off nt
	global_load_dword v61, v[12:13], off nt
	global_load_dword v62, v[14:15], off nt
	global_load_dword v63, v[0:1], off nt
	s_andn2_b64 vcc, exec, s[28:29]
	s_cbranch_vccz .LBB0_54
	s_branch .LBB0_113

.LBB0_79:
	s_cmp_eq_u64 s[26:27], 0
	v_add_u32_e32 v7, 0x400, v103
	v_add_u32_e32 v6, 0x800, v103
	v_add_u32_e32 v5, 0xc00, v103
	v_add_u32_e32 v4, 0x1000, v103
	v_add_u32_e32 v3, 0x1400, v103
	v_add_u32_e32 v0, 0x1800, v103
	v_add_u32_e32 v2, 0x1c00, v103
	s_cbranch_scc1 .LBB0_81
	v_add_u32_e32 v8, s58, v97
	v_ashrrev_i32_e32 v9, 31, v8
	v_lshl_add_u64 v[8:9], v[8:9], 2, s[26:27]
	global_load_dword v10, v[8:9], off nt
	global_load_dword v11, v[8:9], off offset:8 nt
	global_load_dword v12, v[8:9], off offset:16 nt
	global_load_dword v13, v[8:9], off offset:24 nt
	global_load_dword v14, v[8:9], off offset:32 nt
	global_load_dword v15, v[8:9], off offset:40 nt
	global_load_dword v16, v[8:9], off offset:48 nt
	global_load_dword v17, v[8:9], off offset:56 nt
	global_load_dword v18, v[8:9], off offset:64 nt
	global_load_dword v19, v[8:9], off offset:72 nt
	global_load_dword v20, v[8:9], off offset:80 nt
	global_load_dword v21, v[8:9], off offset:88 nt
	global_load_dword v22, v[8:9], off offset:96 nt
	global_load_dword v23, v[8:9], off offset:104 nt
	global_load_dword v24, v[8:9], off offset:112 nt
	global_load_dword v25, v[8:9], off offset:120 nt
	global_load_dword v26, v[8:9], off offset:128 nt
	global_load_dword v27, v[8:9], off offset:136 nt
	global_load_dword v28, v[8:9], off offset:144 nt
	global_load_dword v29, v[8:9], off offset:152 nt
	global_load_dword v30, v[8:9], off offset:160 nt
	global_load_dword v31, v[8:9], off offset:168 nt
	global_load_dword v105, v[8:9], off offset:176 nt
	global_load_dword v107, v[8:9], off offset:184 nt
	global_load_dword v109, v[8:9], off offset:192 nt
	global_load_dword v110, v[8:9], off offset:200 nt
	global_load_dword v111, v[8:9], off offset:208 nt
	global_load_dword v112, v[8:9], off offset:216 nt
	global_load_dword v113, v[8:9], off offset:224 nt
	global_load_dword v114, v[8:9], off offset:232 nt
	global_load_dword v115, v[8:9], off offset:240 nt
	s_nop 0
	global_load_dword v8, v[8:9], off offset:248 nt
	s_mov_b64 s[0:1], 0
	s_waitcnt vmcnt(31)
	v_mul_f32_e32 v9, v32, v10
	s_waitcnt vmcnt(30)
	v_mul_f32_e32 v10, v33, v11
	s_waitcnt vmcnt(29)
	v_mul_f32_e32 v11, v34, v12
	s_waitcnt vmcnt(28)
	v_mul_f32_e32 v12, v35, v13
	s_waitcnt vmcnt(27)
	v_mul_f32_e32 v13, v36, v14
	s_waitcnt vmcnt(26)
	v_mul_f32_e32 v14, v37, v15
	s_waitcnt vmcnt(25)
	v_mul_f32_e32 v15, v38, v16
	s_waitcnt vmcnt(24)
	v_mul_f32_e32 v16, v39, v17
	s_waitcnt vmcnt(23)
	v_mul_f32_e32 v17, v40, v18
	s_waitcnt vmcnt(22)
	v_mul_f32_e32 v18, v41, v19
	s_waitcnt vmcnt(21)
	v_mul_f32_e32 v19, v42, v20
	s_waitcnt vmcnt(20)
	v_mul_f32_e32 v20, v43, v21
	s_waitcnt vmcnt(19)
	v_mul_f32_e32 v21, v44, v22
	s_waitcnt vmcnt(18)
	v_mul_f32_e32 v22, v45, v23
	s_waitcnt vmcnt(17)
	v_mul_f32_e32 v23, v46, v24
	s_waitcnt vmcnt(16)
	v_mul_f32_e32 v24, v47, v25
	s_waitcnt vmcnt(15)
	v_mul_f32_e32 v25, v48, v26
	s_waitcnt vmcnt(14)
	v_mul_f32_e32 v26, v49, v27
	s_waitcnt vmcnt(13)
	v_mul_f32_e32 v27, v50, v28
	s_waitcnt vmcnt(12)
	v_mul_f32_e32 v28, v51, v29
	s_waitcnt vmcnt(11)
	v_mul_f32_e32 v29, v52, v30
	s_waitcnt vmcnt(10)
	v_mul_f32_e32 v30, v53, v31
	s_waitcnt vmcnt(9)
	v_mul_f32_e32 v31, v54, v105
	s_waitcnt vmcnt(8)
	v_mul_f32_e32 v105, v55, v107
	s_waitcnt vmcnt(7)
	v_mul_f32_e32 v107, v56, v109
	s_waitcnt vmcnt(6)
	v_mul_f32_e32 v109, v57, v110
	s_waitcnt vmcnt(5)
	v_mul_f32_e32 v110, v58, v111
	s_waitcnt vmcnt(4)
	v_mul_f32_e32 v111, v59, v112
	s_waitcnt vmcnt(3)
	v_mul_f32_e32 v112, v60, v113
	s_waitcnt vmcnt(2)
	v_mul_f32_e32 v113, v61, v114
	s_waitcnt vmcnt(1)
	v_mul_f32_e32 v114, v62, v115
	s_waitcnt vmcnt(0)
	v_mul_f32_e32 v63, v63, v8
	ds_write2_b32 v103, v9, v10 offset1:66
	ds_write2_b32 v103, v11, v12 offset0:132 offset1:198
	ds_write2_b32 v7, v13, v14 offset0:8 offset1:74
	ds_write2_b32 v7, v15, v16 offset0:140 offset1:206
	ds_write2_b32 v6, v17, v18 offset0:16 offset1:82
	ds_write2_b32 v6, v19, v20 offset0:148 offset1:214
	ds_write2_b32 v5, v21, v22 offset0:24 offset1:90
	ds_write2_b32 v5, v23, v24 offset0:156 offset1:222
	ds_write2_b32 v4, v25, v26 offset0:32 offset1:98
	ds_write2_b32 v4, v27, v28 offset0:164 offset1:230
	ds_write2_b32 v3, v29, v30 offset0:40 offset1:106
	ds_write2_b32 v3, v31, v105 offset0:172 offset1:238
	ds_write2_b32 v0, v107, v109 offset0:48 offset1:114
	ds_write2_b32 v0, v110, v111 offset0:180 offset1:246
	ds_write2_b32 v2, v112, v113 offset0:56 offset1:122
	ds_write_b32 v103, v114 offset:7920

.LBB0_111:
	s_lshl_b64 s[44:45], s[28:29], 2
	v_add_u32_e32 v0, s70, v97
	s_add_u32 s42, s42, s44
	s_addc_u32 s43, s43, s45
	v_mov_b32_e32 v109, v1
	v_ashrrev_i32_e32 v4, 31, v0
	v_lshl_add_u64 v[2:3], s[42:43], 0, v[108:109]
	v_mul_lo_u32 v6, s40, v4
	v_mul_lo_u32 v7, s41, v0
	v_mad_u64_u32 v[4:5], s[42:43], s40, v0, 0
	v_add3_u32 v5, v5, v6, v7
	v_add_u32_e32 v6, 2, v0
	v_ashrrev_i32_e32 v7, 31, v6
	v_mul_lo_u32 v8, s40, v7
	v_mul_lo_u32 v9, s41, v6
	v_mad_u64_u32 v[6:7], s[42:43], s40, v6, 0
	v_add3_u32 v7, v7, v8, v9
	v_add_u32_e32 v8, 4, v0
	v_ashrrev_i32_e32 v9, 31, v8
	v_mul_lo_u32 v10, s40, v9
	v_mul_lo_u32 v11, s41, v8
	v_mad_u64_u32 v[8:9], s[42:43], s40, v8, 0
	v_add3_u32 v9, v9, v10, v11
	v_add_u32_e32 v10, 6, v0
	v_ashrrev_i32_e32 v11, 31, v10
	v_mul_lo_u32 v12, s40, v11
	v_mul_lo_u32 v13, s41, v10
	v_mad_u64_u32 v[10:11], s[42:43], s40, v10, 0
	v_add3_u32 v11, v11, v12, v13
	v_add_u32_e32 v12, 8, v0
	v_ashrrev_i32_e32 v13, 31, v12
	v_mul_lo_u32 v14, s40, v13
	v_mul_lo_u32 v15, s41, v12
	v_mad_u64_u32 v[12:13], s[42:43], s40, v12, 0
	v_add3_u32 v13, v13, v14, v15
	v_add_u32_e32 v14, 10, v0
	v_ashrrev_i32_e32 v15, 31, v14
	v_mul_lo_u32 v16, s40, v15
	v_mul_lo_u32 v17, s41, v14
	v_mad_u64_u32 v[14:15], s[42:43], s40, v14, 0
	v_add3_u32 v15, v15, v16, v17
	v_add_u32_e32 v16, 12, v0
	v_ashrrev_i32_e32 v17, 31, v16
	v_mul_lo_u32 v18, s40, v17
	v_mul_lo_u32 v19, s41, v16
	v_mad_u64_u32 v[16:17], s[42:43], s40, v16, 0
	v_add3_u32 v17, v17, v18, v19
	v_add_u32_e32 v18, 14, v0
	v_ashrrev_i32_e32 v19, 31, v18
	v_mul_lo_u32 v20, s40, v19
	v_mul_lo_u32 v21, s41, v18
	v_mad_u64_u32 v[18:19], s[42:43], s40, v18, 0
	v_lshl_add_u64 v[4:5], v[4:5], 2, v[2:3]
	v_add3_u32 v19, v19, v20, v21
	v_lshl_add_u64 v[6:7], v[6:7], 2, v[2:3]
	v_lshl_add_u64 v[8:9], v[8:9], 2, v[2:3]
	v_lshl_add_u64 v[10:11], v[10:11], 2, v[2:3]
	v_lshl_add_u64 v[12:13], v[12:13], 2, v[2:3]
	v_lshl_add_u64 v[14:15], v[14:15], 2, v[2:3]
	v_lshl_add_u64 v[16:17], v[16:17], 2, v[2:3]
	v_lshl_add_u64 v[18:19], v[18:19], 2, v[2:3]
	global_load_dword v64, v[4:5], off nt
	global_load_dword v65, v[6:7], off nt
	global_load_dword v66, v[8:9], off nt
	global_load_dword v67, v[10:11], off nt
	global_load_dword v68, v[12:13], off nt
	global_load_dword v69, v[14:15], off nt
	global_load_dword v70, v[16:17], off nt
	global_load_dword v71, v[18:19], off nt
	v_add_u32_e32 v4, 16, v0
	v_ashrrev_i32_e32 v5, 31, v4
	v_mul_lo_u32 v6, s40, v5
	v_mul_lo_u32 v7, s41, v4
	v_mad_u64_u32 v[4:5], s[42:43], s40, v4, 0
	v_add3_u32 v5, v5, v6, v7
	v_add_u32_e32 v6, 18, v0
	v_ashrrev_i32_e32 v7, 31, v6
	v_mul_lo_u32 v8, s40, v7
	v_mul_lo_u32 v9, s41, v6
	v_mad_u64_u32 v[6:7], s[42:43], s40, v6, 0
	v_add3_u32 v7, v7, v8, v9
	v_add_u32_e32 v8, 20, v0
	v_ashrrev_i32_e32 v9, 31, v8
	v_mul_lo_u32 v10, s40, v9
	v_mul_lo_u32 v11, s41, v8
	v_mad_u64_u32 v[8:9], s[42:43], s40, v8, 0
	v_add3_u32 v9, v9, v10, v11
	v_add_u32_e32 v10, 22, v0
	v_ashrrev_i32_e32 v11, 31, v10
	v_mul_lo_u32 v12, s40, v11
	v_mul_lo_u32 v13, s41, v10
	v_mad_u64_u32 v[10:11], s[42:43], s40, v10, 0
	v_add3_u32 v11, v11, v12, v13
	v_add_u32_e32 v12, 24, v0
	v_ashrrev_i32_e32 v13, 31, v12
	v_mul_lo_u32 v14, s40, v13
	v_mul_lo_u32 v15, s41, v12
	v_mad_u64_u32 v[12:13], s[42:43], s40, v12, 0
	v_add3_u32 v13, v13, v14, v15
	v_add_u32_e32 v14, 26, v0
	v_ashrrev_i32_e32 v15, 31, v14
	v_mul_lo_u32 v16, s40, v15
	v_mul_lo_u32 v17, s41, v14
	v_mad_u64_u32 v[14:15], s[42:43], s40, v14, 0
	v_add3_u32 v15, v15, v16, v17
	v_add_u32_e32 v16, 28, v0
	v_ashrrev_i32_e32 v17, 31, v16
	v_mul_lo_u32 v18, s40, v17
	v_mul_lo_u32 v19, s41, v16
	v_mad_u64_u32 v[16:17], s[42:43], s40, v16, 0
	v_add3_u32 v17, v17, v18, v19
	v_add_u32_e32 v18, 30, v0
	v_ashrrev_i32_e32 v19, 31, v18
	v_mul_lo_u32 v20, s40, v19
	v_mul_lo_u32 v21, s41, v18
	v_mad_u64_u32 v[18:19], s[42:43], s40, v18, 0
	v_lshl_add_u64 v[4:5], v[4:5], 2, v[2:3]
	v_add3_u32 v19, v19, v20, v21
	v_lshl_add_u64 v[6:7], v[6:7], 2, v[2:3]
	v_lshl_add_u64 v[8:9], v[8:9], 2, v[2:3]
	v_lshl_add_u64 v[10:11], v[10:11], 2, v[2:3]
	v_lshl_add_u64 v[12:13], v[12:13], 2, v[2:3]
	v_lshl_add_u64 v[14:15], v[14:15], 2, v[2:3]
	v_lshl_add_u64 v[16:17], v[16:17], 2, v[2:3]
	v_lshl_add_u64 v[18:19], v[18:19], 2, v[2:3]
	global_load_dword v72, v[4:5], off nt
	global_load_dword v73, v[6:7], off nt
	global_load_dword v74, v[8:9], off nt
	global_load_dword v75, v[10:11], off nt
	global_load_dword v76, v[12:13], off nt
	global_load_dword v77, v[14:15], off nt
	global_load_dword v78, v[16:17], off nt
	global_load_dword v79, v[18:19], off nt
	v_add_u32_e32 v4, 32, v0
	v_ashrrev_i32_e32 v5, 31, v4
	v_mul_lo_u32 v6, s40, v5
	v_mul_lo_u32 v7, s41, v4
	v_mad_u64_u32 v[4:5], s[42:43], s40, v4, 0
	v_add3_u32 v5, v5, v6, v7
	v_add_u32_e32 v6, 34, v0
	v_ashrrev_i32_e32 v7, 31, v6
	v_mul_lo_u32 v8, s40, v7
	v_mul_lo_u32 v9, s41, v6
	v_mad_u64_u32 v[6:7], s[42:43], s40, v6, 0
	v_add3_u32 v7, v7, v8, v9
	v_add_u32_e32 v8, 36, v0
	v_ashrrev_i32_e32 v9, 31, v8
	v_mul_lo_u32 v10, s40, v9
	v_mul_lo_u32 v11, s41, v8
	v_mad_u64_u32 v[8:9], s[42:43], s40, v8, 0
	v_add3_u32 v9, v9, v10, v11
	v_add_u32_e32 v10, 38, v0
	v_ashrrev_i32_e32 v11, 31, v10
	v_mul_lo_u32 v12, s40, v11
	v_mul_lo_u32 v13, s41, v10
	v_mad_u64_u32 v[10:11], s[42:43], s40, v10, 0
	v_add3_u32 v11, v11, v12, v13
	v_add_u32_e32 v12, 40, v0
	v_ashrrev_i32_e32 v13, 31, v12
	v_mul_lo_u32 v14, s40, v13
	v_mul_lo_u32 v15, s41, v12
	v_mad_u64_u32 v[12:13], s[42:43], s40, v12, 0
	v_add3_u32 v13, v13, v14, v15
	v_add_u32_e32 v14, 42, v0
	v_ashrrev_i32_e32 v15, 31, v14
	v_mul_lo_u32 v16, s40, v15
	v_mul_lo_u32 v17, s41, v14
	v_mad_u64_u32 v[14:15], s[42:43], s40, v14, 0
	v_add3_u32 v15, v15, v16, v17
	v_add_u32_e32 v16, 44, v0
	v_ashrrev_i32_e32 v17, 31, v16
	v_mul_lo_u32 v18, s40, v17
	v_mul_lo_u32 v19, s41, v16
	v_mad_u64_u32 v[16:17], s[42:43], s40, v16, 0
	v_add3_u32 v17, v17, v18, v19
	v_add_u32_e32 v18, 46, v0
	v_ashrrev_i32_e32 v19, 31, v18
	v_mul_lo_u32 v20, s40, v19
	v_mul_lo_u32 v21, s41, v18
	v_mad_u64_u32 v[18:19], s[42:43], s40, v18, 0
	v_lshl_add_u64 v[4:5], v[4:5], 2, v[2:3]
	v_add3_u32 v19, v19, v20, v21
	v_lshl_add_u64 v[6:7], v[6:7], 2, v[2:3]
	v_lshl_add_u64 v[8:9], v[8:9], 2, v[2:3]
	v_lshl_add_u64 v[10:11], v[10:11], 2, v[2:3]
	v_lshl_add_u64 v[12:13], v[12:13], 2, v[2:3]
	v_lshl_add_u64 v[14:15], v[14:15], 2, v[2:3]
	v_lshl_add_u64 v[16:17], v[16:17], 2, v[2:3]
	v_lshl_add_u64 v[18:19], v[18:19], 2, v[2:3]
	global_load_dword v80, v[4:5], off nt
	global_load_dword v81, v[6:7], off nt
	global_load_dword v82, v[8:9], off nt
	global_load_dword v83, v[10:11], off nt
	global_load_dword v84, v[12:13], off nt
	global_load_dword v85, v[14:15], off nt
	global_load_dword v86, v[16:17], off nt
	global_load_dword v87, v[18:19], off nt
	v_add_u32_e32 v4, 48, v0
	v_ashrrev_i32_e32 v5, 31, v4
	v_mul_lo_u32 v6, s40, v5
	v_mul_lo_u32 v7, s41, v4
	v_mad_u64_u32 v[4:5], s[42:43], s40, v4, 0
	v_add3_u32 v5, v5, v6, v7
	v_add_u32_e32 v6, 50, v0
	v_ashrrev_i32_e32 v7, 31, v6
	v_mul_lo_u32 v8, s40, v7
	v_mul_lo_u32 v9, s41, v6
	v_mad_u64_u32 v[6:7], s[42:43], s40, v6, 0
	v_add3_u32 v7, v7, v8, v9
	v_add_u32_e32 v8, 52, v0
	v_ashrrev_i32_e32 v9, 31, v8
	v_mul_lo_u32 v10, s40, v9
	v_mul_lo_u32 v11, s41, v8
	v_mad_u64_u32 v[8:9], s[42:43], s40, v8, 0
	v_add3_u32 v9, v9, v10, v11
	v_add_u32_e32 v10, 54, v0
	v_ashrrev_i32_e32 v11, 31, v10
	v_mul_lo_u32 v12, s40, v11
	v_mul_lo_u32 v13, s41, v10
	v_mad_u64_u32 v[10:11], s[42:43], s40, v10, 0
	v_add3_u32 v11, v11, v12, v13
	v_add_u32_e32 v12, 56, v0
	v_ashrrev_i32_e32 v13, 31, v12
	v_mul_lo_u32 v14, s40, v13
	v_mul_lo_u32 v15, s41, v12
	v_mad_u64_u32 v[12:13], s[42:43], s40, v12, 0
	v_add3_u32 v13, v13, v14, v15
	v_add_u32_e32 v14, 58, v0
	v_ashrrev_i32_e32 v15, 31, v14
	v_mul_lo_u32 v16, s40, v15
	v_mul_lo_u32 v17, s41, v14
	v_mad_u64_u32 v[14:15], s[42:43], s40, v14, 0
	v_add3_u32 v15, v15, v16, v17
	v_add_u32_e32 v16, 60, v0
	v_ashrrev_i32_e32 v17, 31, v16
	v_mul_lo_u32 v18, s40, v17
	v_mul_lo_u32 v19, s41, v16
	v_mad_u64_u32 v[16:17], s[42:43], s40, v16, 0
	v_add_u32_e32 v0, 62, v0
	v_add3_u32 v17, v17, v18, v19
	v_ashrrev_i32_e32 v18, 31, v0
	v_mul_lo_u32 v20, s40, v18
	v_mul_lo_u32 v21, s41, v0
	v_mad_u64_u32 v[18:19], s[40:41], s40, v0, 0
	v_lshl_add_u64 v[4:5], v[4:5], 2, v[2:3]
	v_add3_u32 v19, v19, v20, v21
	v_lshl_add_u64 v[6:7], v[6:7], 2, v[2:3]
	v_lshl_add_u64 v[8:9], v[8:9], 2, v[2:3]
	v_lshl_add_u64 v[10:11], v[10:11], 2, v[2:3]
	v_lshl_add_u64 v[12:13], v[12:13], 2, v[2:3]
	v_lshl_add_u64 v[14:15], v[14:15], 2, v[2:3]
	v_lshl_add_u64 v[16:17], v[16:17], 2, v[2:3]
	v_lshl_add_u64 v[2:3], v[18:19], 2, v[2:3]
	global_load_dword v88, v[4:5], off nt
	global_load_dword v89, v[6:7], off nt
	global_load_dword v90, v[8:9], off nt
	global_load_dword v91, v[10:11], off nt
	global_load_dword v92, v[12:13], off nt
	global_load_dword v93, v[14:15], off nt
	global_load_dword v94, v[16:17], off nt
	global_load_dword v95, v[2:3], off nt
	s_xor_b64 s[40:41], s[0:1], -1
	s_cmp_gt_i32 s24, -1
	s_mov_b64 s[0:1], -1
	s_cbranch_scc0 .LBB0_64
	s_branch .LBB0_79

.LBB0_113:
	s_mul_i32 s0, s68, 48
	s_lshl_b32 s1, s56, 2
	s_add_i32 s0, s1, s0
	s_ashr_i32 s1, s0, 31
	s_lshl_b64 s[10:11], s[0:1], 12
	s_add_u32 s10, s4, s10
	v_ashrrev_i32_e32 v97, 31, v96
	s_addc_u32 s11, s5, s11
	s_waitcnt vmcnt(30)
	v_lshlrev_b64 v[32:33], 4, v[96:97]
	v_lshl_add_u64 v[16:17], s[10:11], 0, v[32:33]
	s_or_b32 s10, s0, 2
	s_ashr_i32 s11, s10, 31
	s_lshl_b64 s[12:13], s[10:11], 12
	s_add_u32 s12, s4, s12
	v_add_co_u32_e32 v28, vcc, 0x1000, v16
	s_addc_u32 s13, s5, s13
	global_load_dwordx4 v[0:3], v[16:17], off nt
	global_load_dwordx4 v[4:7], v[16:17], off offset:1024 nt
	global_load_dwordx4 v[8:11], v[16:17], off offset:2048 nt
	global_load_dwordx4 v[12:15], v[16:17], off offset:3072 nt
	v_addc_co_u32_e32 v29, vcc, 0, v17, vcc
	s_movk_i32 s14, 0x1000
	s_waitcnt vmcnt(18)
	v_lshl_add_u64 v[48:49], s[12:13], 0, v[32:33]
	global_load_dwordx4 v[16:19], v[28:29], off nt
	global_load_dwordx4 v[20:23], v[28:29], off offset:1024 nt
	global_load_dwordx4 v[24:27], v[28:29], off offset:2048 nt
	v_add_co_u32_e32 v64, vcc, s14, v48
	global_load_dwordx4 v[28:31], v[28:29], off offset:3072 nt
	s_nop 0
	v_addc_co_u32_e32 v65, vcc, 0, v49, vcc
	global_load_dwordx4 v[32:35], v[48:49], off nt
	global_load_dwordx4 v[36:39], v[48:49], off offset:1024 nt
	global_load_dwordx4 v[40:43], v[48:49], off offset:2048 nt
	global_load_dwordx4 v[44:47], v[48:49], off offset:3072 nt
	s_nop 0
	global_load_dwordx4 v[48:51], v[64:65], off nt
	global_load_dwordx4 v[52:55], v[64:65], off offset:1024 nt
	global_load_dwordx4 v[56:59], v[64:65], off offset:2048 nt
	global_load_dwordx4 v[60:63], v[64:65], off offset:3072 nt
	s_lshl_b64 s[0:1], s[0:1], 11
	s_add_u32 s0, s6, s0
	v_lshlrev_b64 v[64:65], 3, v[96:97]
	s_addc_u32 s1, s7, s1
	s_lshl_b64 s[10:11], s[10:11], 11
	v_lshl_add_u64 v[66:67], s[0:1], 0, v[64:65]
	s_add_u32 s0, s6, s10
	s_addc_u32 s1, s7, s11
	v_lshl_add_u64 v[64:65], s[0:1], 0, v[64:65]
	v_readlane_b32 s88, v246, 36
	s_mov_b64 s[0:1], 0
	v_readlane_b32 s89, v246, 37
	s_waitcnt vmcnt(15)
	v_cvt_pk_f16_f32 v0, v0, v1
	v_cvt_pk_f16_f32 v1, v2, v3
	s_waitcnt vmcnt(14)
	v_cvt_pk_f16_f32 v2, v4, v5
	v_cvt_pk_f16_f32 v3, v6, v7
	s_waitcnt vmcnt(13)
	v_cvt_pk_f16_f32 v4, v8, v9
	v_cvt_pk_f16_f32 v5, v10, v11
	s_waitcnt vmcnt(12)
	v_cvt_pk_f16_f32 v6, v12, v13
	v_cvt_pk_f16_f32 v7, v14, v15
	global_store_dwordx2 v[66:67], v[0:1], off
	global_store_dwordx2 v[66:67], v[2:3], off offset:512
	global_store_dwordx2 v[66:67], v[4:5], off offset:1024
	global_store_dwordx2 v[66:67], v[6:7], off offset:1536
	s_waitcnt vmcnt(15)
	v_cvt_pk_f16_f32 v0, v16, v17
	v_cvt_pk_f16_f32 v1, v18, v19
	s_waitcnt vmcnt(14)
	v_cvt_pk_f16_f32 v2, v20, v21
	v_cvt_pk_f16_f32 v3, v22, v23
	s_waitcnt vmcnt(13)
	v_cvt_pk_f16_f32 v4, v24, v25
	v_cvt_pk_f16_f32 v5, v26, v27
	s_waitcnt vmcnt(12)
	v_cvt_pk_f16_f32 v6, v28, v29
	v_cvt_pk_f16_f32 v7, v30, v31
	global_store_dwordx2 v[66:67], v[0:1], off offset:2048
	global_store_dwordx2 v[66:67], v[2:3], off offset:2560
	global_store_dwordx2 v[66:67], v[4:5], off offset:3072
	global_store_dwordx2 v[66:67], v[6:7], off offset:3584
	s_waitcnt vmcnt(15)
	v_cvt_pk_f16_f32 v0, v32, v33
	v_cvt_pk_f16_f32 v1, v34, v35
	s_waitcnt vmcnt(14)
	v_cvt_pk_f16_f32 v2, v36, v37
	v_cvt_pk_f16_f32 v3, v38, v39
	s_waitcnt vmcnt(13)
	v_cvt_pk_f16_f32 v4, v40, v41
	v_cvt_pk_f16_f32 v5, v42, v43
	global_store_dwordx2 v[64:65], v[0:1], off
	s_waitcnt vmcnt(12)
	v_cvt_pk_f16_f32 v0, v48, v49
	v_cvt_pk_f16_f32 v1, v50, v51
	v_cvt_pk_f16_f32 v6, v44, v45
	global_store_dwordx2 v[64:65], v[2:3], off offset:512
	s_waitcnt vmcnt(12)
	v_cvt_pk_f16_f32 v2, v52, v53
	v_cvt_pk_f16_f32 v3, v54, v55
	global_store_dwordx2 v[64:65], v[4:5], off offset:1024
	s_waitcnt vmcnt(12)
	v_cvt_pk_f16_f32 v4, v56, v57
	v_cvt_pk_f16_f32 v5, v58, v59
	global_store_dwordx2 v[64:65], v[0:1], off offset:2048
	global_store_dwordx2 v[64:65], v[2:3], off offset:2560
	global_store_dwordx2 v[64:65], v[4:5], off offset:3072
	v_cvt_pk_f16_f32 v7, v46, v47
	s_waitcnt vmcnt(14)
	v_cvt_pk_f16_f32 v0, v60, v61
	v_cvt_pk_f16_f32 v1, v62, v63
	global_store_dwordx2 v[64:65], v[6:7], off offset:1536
	global_store_dwordx2 v[64:65], v[0:1], off offset:3584
.LBB0_114:
	s_and_b64 vcc, exec, s[0:1]
	s_cbranch_vccz .LBB0_123
	s_lshl_b32 s0, s94, 2
	s_or_b32 s10, s0, s90
	s_mul_i32 s0, s10, 12
	s_ashr_i32 s1, s0, 31
	s_lshl_b64 s[12:13], s[0:1], 12
	s_add_u32 s12, s4, s12
	v_ashrrev_i32_e32 v97, 31, v96
	s_addc_u32 s13, s5, s13
	v_lshlrev_b64 v[24:25], 4, v[96:97]
	v_lshl_add_u64 v[26:27], s[12:13], 0, v[24:25]
	v_add_co_u32_e32 v28, vcc, 0x1000, v26
	s_mov_b32 s1, 0
	s_nop 0
	v_addc_co_u32_e32 v29, vcc, 0, v27, vcc
	global_load_dwordx4 v[36:39], v[26:27], off nt
	global_load_dwordx4 v[16:19], v[26:27], off offset:1024 nt
	global_load_dwordx4 v[52:55], v[28:29], off nt
	global_load_dwordx4 v[20:23], v[28:29], off offset:1024 nt
	global_load_dwordx4 v[8:11], v[26:27], off offset:2048 nt
	global_load_dwordx4 v[0:3], v[26:27], off offset:3072 nt
	global_load_dwordx4 v[12:15], v[28:29], off offset:2048 nt
	global_load_dwordx4 v[4:7], v[28:29], off offset:3072 nt
	v_lshl_add_u64 v[64:65], s[4:5], 0, v[24:25]
	v_lshl_add_u64 v[66:67], v[96:97], 3, s[6:7]
	s_branch .LBB0_117

.LBB0_117:
	s_add_i32 s6, s0, s1
	s_cmp_gt_u32 s1, 9
	s_cselect_b64 s[4:5], -1, 0
	s_and_b64 vcc, exec, s[4:5]
	s_cbranch_vccnz .LBB0_116
	s_add_i32 s12, s6, 2
	s_ashr_i32 s13, s12, 31
	s_lshl_b64 s[12:13], s[12:13], 12
	v_lshl_add_u64 v[68:69], v[64:65], 0, s[12:13]
	v_add_co_u32_e32 v70, vcc, 0x1000, v68
	s_nop 1
	v_addc_co_u32_e32 v71, vcc, 0, v69, vcc
	global_load_dwordx4 v[24:27], v[68:69], off nt
	global_load_dwordx4 v[28:31], v[68:69], off offset:1024 nt
	global_load_dwordx4 v[48:51], v[70:71], off nt
	global_load_dwordx4 v[44:47], v[70:71], off offset:1024 nt
	global_load_dwordx4 v[32:35], v[68:69], off offset:2048 nt
	global_load_dwordx4 v[40:43], v[68:69], off offset:3072 nt
	global_load_dwordx4 v[60:63], v[70:71], off offset:2048 nt
	global_load_dwordx4 v[56:59], v[70:71], off offset:3072 nt
	s_branch .LBB0_116

.LBB0_121:
	v_ashrrev_i32_e32 v54, 4, v52
	v_ashrrev_i32_e32 v55, 31, v54
	v_lshl_add_u64 v[54:55], v[54:55], 2, s[8:9]
	global_load_dword v80, v[54:55], off nt
	v_mov_b32_e32 v0, v48
	v_mov_b64_e32 v[74:75], v[0:1]
	v_mov_b64_e32 v[54:55], v[32:33]
	v_mov_b64_e32 v[58:59], v[42:43]
	v_mov_b64_e32 v[56:57], v[40:41]
	v_mov_b64_e32 v[62:63], v[46:47]
	v_mov_b64_e32 v[60:61], v[44:45]
	v_mov_b64_e32 v[66:67], v[50:51]
	v_mov_b64_e32 v[64:65], v[48:49]
	v_mov_b64_e32 v[68:69], v[2:3]
	v_mov_b64_e32 v[72:73], v[4:5]
	v_mov_b32_e32 v8, v6
	v_mov_b64_e32 v[70:71], v[6:7]
	v_mov_b64_e32 v[76:77], v[8:9]
	v_add_u32_e32 v52, s18, v52
	v_ashrrev_i32_e32 v11, 31, v10
	v_cmp_lt_i32_e32 vcc, s20, v52
	v_lshl_add_u64 v[78:79], v[10:11], 2, s[6:7]
	v_add_u32_e32 v10, s19, v10
	s_or_b64 s[0:1], vcc, s[0:1]
	s_waitcnt vmcnt(0)
	v_cvt_f32_i32_e32 v0, v80
	v_mul_f32_e32 v0, v53, v0
	v_cvt_f64_f32_e32 v[80:81], v0
	v_mul_f64 v[82:83], v[80:81], s[10:11]
	v_rndne_f64_e32 v[82:83], v[82:83]
	v_fma_f64 v[80:81], v[80:81], s[10:11], -v[82:83]
	v_mul_f64 v[80:81], v[80:81], s[12:13]
	v_mul_f64 v[82:83], v[80:81], -v[80:81]
	v_fma_f64 v[86:87], s[16:17], v[82:83], v[14:15]
	v_fma_f64 v[84:85], s[14:15], v[82:83], v[12:13]
	v_fma_f64 v[86:87], v[82:83], v[86:87], v[18:19]
	v_fma_f64 v[84:85], v[82:83], v[84:85], v[16:17]
	v_fma_f64 v[86:87], v[82:83], v[86:87], v[22:23]
	v_fma_f64 v[84:85], v[82:83], v[84:85], v[20:21]
	v_fma_f64 v[86:87], v[82:83], v[86:87], v[26:27]
	v_fma_f64 v[84:85], v[82:83], v[84:85], v[24:25]
	v_fma_f64 v[86:87], v[82:83], v[86:87], v[30:31]
	v_fma_f64 v[84:85], v[82:83], v[84:85], v[28:29]
	v_fma_f64 v[86:87], v[82:83], v[86:87], v[36:37]
	v_fma_f64 v[84:85], v[82:83], v[84:85], v[34:35]
	v_fmac_f64_e32 v[54:55], v[82:83], v[86:87]
	v_fma_f64 v[84:85], v[82:83], v[84:85], v[38:39]
	v_fmac_f64_e32 v[58:59], v[82:83], v[54:55]
	v_fmac_f64_e32 v[56:57], v[82:83], v[84:85]
	v_fmac_f64_e32 v[62:63], v[82:83], v[58:59]
	v_fmac_f64_e32 v[60:61], v[82:83], v[56:57]
	v_fmac_f64_e32 v[66:67], v[82:83], v[62:63]
	v_fmac_f64_e32 v[64:65], v[82:83], v[60:61]
	v_fmac_f64_e32 v[74:75], v[82:83], v[66:67]
	v_fmac_f64_e32 v[68:69], v[82:83], v[64:65]
	v_fmac_f64_e32 v[72:73], v[82:83], v[74:75]
	v_fmac_f64_e32 v[70:71], v[82:83], v[68:69]
	v_fmac_f64_e32 v[76:77], v[82:83], v[72:73]
	v_fma_f64 v[54:55], v[82:83], v[70:71], 0.5
	v_fma_f64 v[56:57], v[82:83], v[76:77], 1.0
	v_fma_f64 v[54:55], v[82:83], v[54:55], 1.0
	v_mul_f64 v[56:57], v[80:81], v[56:57]
	v_cvt_f32_f64_e32 v54, v[54:55]
	v_cvt_f32_f64_e32 v55, v[56:57]
	global_store_dwordx2 v[78:79], v[54:55], off
	s_andn2_b64 exec, exec, s[0:1]
	s_cbranch_execnz .LBB0_121

.LBB0_125:
	v_lshl_add_u64 v[8:9], s[22:23], 0, v[2:3]
	global_load_dword v5, v[8:9], off nt
	v_add_u32_e32 v0, s4, v0
	v_cmp_lt_i32_e32 vcc, s16, v0
	s_or_b64 s[8:9], vcc, s[8:9]
	v_lshl_add_u64 v[8:9], s[2:3], 0, v[2:3]
	v_lshl_add_u64 v[2:3], v[2:3], 0, s[6:7]
	s_waitcnt vmcnt(0)
	v_mul_f32_e32 v7, 0xbfb8aa3b, v5
	v_fma_f32 v10, v5, s5, -v7
	v_rndne_f32_e32 v11, v7
	v_fmac_f32_e32 v10, 0xb2a5705f, v5
	v_sub_f32_e32 v7, v7, v11
	v_add_f32_e32 v7, v7, v10
	v_cvt_i32_f32_e32 v11, v11
	v_exp_f32_e32 v7, v7
	v_cmp_nlt_f32_e32 vcc, s10, v5
	v_ldexp_f32 v7, v7, v11
	s_nop 0
	v_cndmask_b32_e32 v7, 0, v7, vcc
	v_cmp_ngt_f32_e32 vcc, s11, v5
	s_nop 1
	v_cndmask_b32_e32 v7, v1, v7, vcc
	v_add_f32_e32 v5, 1.0, v7
	v_add_f32_e32 v12, -1.0, v5
	v_frexp_mant_f32_e32 v13, v5
	v_cvt_f64_f32_e32 v[10:11], v5
	v_sub_f32_e32 v14, v12, v5
	v_frexp_exp_i32_f64_e32 v10, v[10:11]
	v_cmp_gt_f32_e32 vcc, s13, v13
	v_sub_f32_e32 v12, v7, v12
	v_add_f32_e32 v11, 1.0, v14
	v_subbrev_co_u32_e32 v10, vcc, 0, v10, vcc
	v_add_f32_e32 v11, v12, v11
	v_sub_u32_e32 v12, 0, v10
	v_ldexp_f32 v5, v5, v12
	v_ldexp_f32 v11, v11, v12
	v_add_f32_e32 v12, -1.0, v5
	v_add_f32_e32 v14, 1.0, v5
	v_add_f32_e32 v13, 1.0, v12
	v_add_f32_e32 v15, -1.0, v14
	v_sub_f32_e32 v13, v5, v13
	v_sub_f32_e32 v5, v5, v15
	v_add_f32_e32 v5, v11, v5
	v_add_f32_e32 v15, v11, v13
	v_add_f32_e32 v11, v14, v5
	v_rcp_f32_e32 v18, v11
	v_add_f32_e32 v13, v12, v15
	v_sub_f32_e32 v14, v14, v11
	v_add_f32_e32 v5, v5, v14
	v_mul_f32_e32 v20, v13, v18
	v_mul_f32_e32 v14, v11, v20
	v_fma_f32 v16, v20, v11, -v14
	v_sub_f32_e32 v12, v12, v13
	v_fmac_f32_e32 v16, v20, v5
	v_add_f32_e32 v19, v15, v12
	v_add_f32_e32 v12, v14, v16
	v_sub_f32_e32 v15, v13, v12
	v_mov_b32_e32 v17, v12
	v_pk_add_f32 v[12:13], v[12:13], v[14:15] neg_lo:[0,1] neg_hi:[0,1]
	v_cvt_f32_i32_e32 v10, v10
	v_pk_add_f32 v[12:13], v[12:13], v[16:17] neg_lo:[0,1] neg_hi:[0,1]
	v_cmp_neq_f32_e32 vcc, s12, v7
	v_add_f32_e32 v13, v19, v13
	v_add_f32_e32 v12, v12, v13
	v_add_f32_e32 v13, v15, v12
	v_mul_f32_e32 v17, v18, v13
	v_mul_f32_e32 v14, v11, v17
	v_fma_f32 v16, v17, v11, -v14
	v_sub_f32_e32 v15, v15, v13
	v_fmac_f32_e32 v16, v17, v5
	v_add_f32_e32 v19, v12, v15
	v_add_f32_e32 v21, v20, v17
	v_add_f32_e32 v12, v14, v16
	v_sub_f32_e32 v11, v21, v20
	v_sub_f32_e32 v15, v13, v12
	v_sub_f32_e32 v5, v17, v11
	v_mov_b32_e32 v17, v12
	v_pk_add_f32 v[12:13], v[12:13], v[14:15] neg_lo:[0,1] neg_hi:[0,1]
	s_nop 0
	v_pk_add_f32 v[12:13], v[12:13], v[16:17] neg_lo:[0,1] neg_hi:[0,1]
	s_nop 0
	v_add_f32_e32 v11, v19, v13
	v_add_f32_e32 v11, v12, v11
	v_add_f32_e32 v11, v15, v11
	v_mul_f32_e32 v11, v18, v11
	v_add_f32_e32 v5, v5, v11
	v_add_f32_e32 v11, v21, v5
	v_mul_f32_e32 v12, v11, v11
	v_sub_f32_e32 v14, v11, v21
	v_fmamk_f32 v15, v12, 0x3e9b6dac, v6
	v_ldexp_f32 v13, v11, 1
	v_sub_f32_e32 v14, v5, v14
	v_mul_f32_e32 v11, v11, v12
	v_fmaak_f32 v5, v12, v15, 0x3f2aaada
	v_ldexp_f32 v17, v14, 1
	v_pk_mul_f32 v[14:15], v[10:11], v[4:5]
	s_nop 0
	v_fma_f32 v12, v10, s14, -v14
	v_fmac_f32_e32 v12, 0xb102e308, v10
	v_pk_add_f32 v[10:11], v[14:15], v[12:13]
	v_mov_b32_e32 v16, v14
	v_sub_f32_e32 v5, v11, v13
	v_sub_f32_e32 v5, v15, v5
	v_add_f32_e32 v17, v17, v5
	v_pk_add_f32 v[18:19], v[10:11], v[14:15] neg_lo:[0,1] neg_hi:[0,1]
	v_pk_add_f32 v[14:15], v[10:11], v[16:17]
	v_mov_b32_e32 v13, v10
	v_mov_b32_e32 v19, v15
	v_pk_add_f32 v[22:23], v[12:13], v[18:19] neg_lo:[0,1] neg_hi:[0,1]
	v_pk_add_f32 v[12:13], v[12:13], v[18:19]
	v_mov_b32_e32 v21, v10
	v_pk_add_f32 v[18:19], v[12:13], v[10:11] op_sel:[1,0] op_sel_hi:[0,1] neg_lo:[0,1] neg_hi:[0,1]
	v_mov_b32_e32 v20, v17
	v_mov_b32_e32 v16, v15
	v_mov_b32_e32 v17, v13
	v_pk_mov_b32 v[10:11], v[10:11], v[18:19] op_sel:[1,0]
	v_pk_add_f32 v[14:15], v[14:15], v[18:19] op_sel_hi:[1,0] neg_lo:[0,1] neg_hi:[0,1]
	v_pk_add_f32 v[10:11], v[16:17], v[10:11] neg_lo:[0,1] neg_hi:[0,1]
	v_mov_b32_e32 v14, v22
	v_pk_add_f32 v[10:11], v[20:21], v[10:11] neg_lo:[0,1] neg_hi:[0,1]
	v_mov_b32_e32 v23, v13
	v_pk_add_f32 v[14:15], v[14:15], v[10:11]
	s_nop 0
	v_pk_add_f32 v[16:17], v[14:15], v[14:15] op_sel:[0,1] op_sel_hi:[1,0]
	s_nop 0
	v_pk_add_f32 v[12:13], v[12:13], v[16:17] op_sel:[1,0] op_sel_hi:[0,1]
	v_mov_b32_e32 v15, v12
	v_mov_b32_e32 v11, v16
	v_pk_add_f32 v[16:17], v[14:15], v[22:23] neg_lo:[0,1] neg_hi:[0,1]
	s_nop 0
	v_sub_f32_e32 v5, v14, v16
	v_pk_add_f32 v[10:11], v[10:11], v[16:17] neg_lo:[0,1] neg_hi:[0,1]
	v_sub_f32_e32 v5, v22, v5
	v_add_f32_e32 v5, v10, v5
	v_add_f32_e32 v5, v5, v11
	v_add_f32_e32 v5, v12, v5
	v_cndmask_b32_e32 v5, v1, v5, vcc
	v_cmp_lt_f32_e64 vcc, |v7|, s15
	s_nop 1
	v_cndmask_b32_e32 v5, v5, v7, vcc
	v_mul_f32_e32 v5, 0xc138aa3b, v5
	global_store_dword v[8:9], v5, off
	s_andn2_b64 exec, exec, s[8:9]
	s_cbranch_execnz .LBB0_125

.LBB0_195:
	s_mul_i32 s3, s6, s2
	s_sub_i32 s3, s4, s3
	s_ashr_i32 s1, s7, 3
	s_xor_b32 s0, s9, s0
	s_add_i32 s4, s6, 1
	s_sub_i32 s7, s3, s2
	s_cmp_ge_u32 s3, s2
	s_cselect_b32 s4, s4, s6
	s_cselect_b32 s3, s7, s3
	s_add_i32 s6, s4, 1
	s_cmp_ge_u32 s3, s2
	s_cselect_b32 s2, s6, s4
	s_xor_b32 s2, s2, s0
	s_sub_i32 s2, s2, s0
	s_add_i32 s0, s5, s1
	s_ashr_i32 s1, s0, 31
	s_lshr_b32 s1, s1, 26
	s_add_i32 s1, s0, s1
	s_and_b32 s1, s1, 0xffc0
	s_sub_i32 s0, s0, s1
	s_bfe_i32 s1, s0, 0x80000
	s_bfe_u32 s1, s1, 0x3000c
	s_add_i32 s0, s0, s1
	s_bfe_i32 s0, s0, 0x80000
	s_sext_i32_i16 s0, s0
	s_ashr_i32 s0, s0, 3
	s_add_i32 s0, s0, 0xfff9
	s_and_b32 s0, s0, 0xffff
	s_cmpk_ge_u32 s0, 0xfffc
	s_cselect_b64 s[0:1], -1, 0
	s_add_i32 s2, s2, -3
	s_cmp_ge_u32 s2, 4
	s_cselect_b64 s[2:3], -1, 0
	s_and_b64 s[0:1], s[2:3], s[0:1]
	v_cndmask_b32_e64 v0, 0, 1, s[0:1]
	s_nop 0
	v_readfirstlane_b32 s33, v0

.LBB0_425:
	s_lshl_b32 s28, s73, 8
	s_add_i32 s28, s28, s44
	s_cmp_eq_u32 s73, s6
	v_readlane_b32 s80, v246, 28
	s_cselect_b32 s29, 0, 0x100
	s_cmp_gt_i32 s72, 4
	s_mov_b64 s[2:3], -1
	v_readlane_b32 s81, v246, 29
	v_readlane_b32 s82, v246, 30
	v_readlane_b32 s83, v246, 31
	v_readlane_b32 s84, v246, 32
	v_readlane_b32 s85, v246, 33
	v_readlane_b32 s86, v246, 34
	v_readlane_b32 s87, v246, 35
	s_cbranch_scc0 .LBB0_464
	s_lshl_b32 s2, s29, 2
	v_mbcnt_lo_u32_b32 v159, -1, 0
	v_mbcnt_hi_u32_b32 v159, -1, v159
	s_add_i32 s2, s61, s2
	v_and_b32_e32 v129, 15, v159
	v_lshl_add_u32 v161, v129, 2, s2
	v_or_b32_e32 v160, s28, v129
	v_ashrrev_i32_e32 v129, 1, v159
	ds_read_b32 v136, v161
	v_and_b32_e32 v130, -8, v129
	v_ashrrev_i32_e32 v131, 31, v130
	s_lshl_b32 s74, s72, 1
	v_lshl_add_u64 v[132:133], v[130:131], 1, s[20:21]
	s_add_i32 s74, s74, -10
	v_mad_i64_i32 v[130:131], s[2:3], s64, v160, 0
	v_lshl_add_u64 v[134:135], v[130:131], 1, v[132:133]
	s_mul_i32 s26, s74, s63
	s_mov_b32 s27, s15
	v_cndmask_b32_e64 v129, 0, 1, s[18:19]
	s_waitcnt lgkmcnt(0)
	v_pk_mul_f32 v[138:139], v[78:79], v[136:137] op_sel_hi:[1,0]
	v_pk_mul_f32 v[142:143], v[76:77], v[136:137] op_sel_hi:[1,0]
	v_pk_mul_f32 v[130:131], v[74:75], v[136:137] op_sel_hi:[1,0]
	v_pk_mul_f32 v[140:141], v[72:73], v[136:137] op_sel_hi:[1,0]
	v_lshl_add_u64 v[144:145], s[26:27], 1, v[134:135]
	v_cmp_ne_u32_e64 s[2:3], 1, v129
	s_andn2_b64 vcc, exec, s[18:19]
	v_cvt_pk_bf16_f32 v162, v142, v143
	v_cvt_pk_bf16_f32 v163, v138, v139
	v_cvt_pk_bf16_f32 v164, v140, v141
	v_cvt_pk_bf16_f32 v165, v130, v131
	global_store_dwordx4 v[144:145], v[162:165], off sc1
	s_cbranch_vccnz .LBB0_428
	v_mul_f32_e32 v129, v143, v143
	v_mul_f32_e32 v137, v139, v139
	v_fmac_f32_e32 v129, v142, v142
	v_fmac_f32_e32 v137, v138, v138
	v_add_f32_e32 v129, v129, v137
	v_mul_f32_e32 v137, v141, v141
	v_mul_f32_e32 v131, v131, v131
	v_fmac_f32_e32 v137, v140, v140
	v_fmac_f32_e32 v131, v130, v130
	v_add_f32_e32 v130, v137, v131
	v_add_f32_e32 v129, v129, v130
	v_mov_b32_e32 v130, v129
	s_nop 1
	v_permlane16_swap_b32_e32 v129, v130
	v_add_f32_e32 v129, v129, v130
	v_mov_b32_e32 v130, v129
	s_nop 1
	v_permlane32_swap_b32_e32 v129, v130
	v_add_f32_e32 v129, v129, v130
	v_max_f32_e32 v130, 0, v129
	v_mov_b32_e32 v131, v128
	s_branch .LBB0_429

.LBB0_429:
	v_mov_b32_e32 v137, v136
	v_mov_b32_e32 v138, v136
	v_mov_b32_e32 v139, v136
	s_add_i32 s14, s26, s63
	v_pk_mul_f32 v[140:141], v[126:127], v[138:139]
	v_pk_mul_f32 v[142:143], v[124:125], v[136:137]
	v_pk_mul_f32 v[138:139], v[122:123], v[138:139]
	v_pk_mul_f32 v[136:137], v[120:121], v[136:137]
	v_lshl_add_u64 v[134:135], s[14:15], 1, v[134:135]
	s_and_b64 vcc, exec, s[2:3]
	v_cvt_pk_bf16_f32 v162, v142, v143
	v_cvt_pk_bf16_f32 v163, v140, v141
	v_cvt_pk_bf16_f32 v164, v136, v137
	v_cvt_pk_bf16_f32 v165, v138, v139
	global_store_dwordx4 v[134:135], v[162:165], off sc1
	s_cbranch_vccnz .LBB0_431
	v_mul_f32_e32 v129, v143, v143
	v_mul_f32_e32 v134, v141, v141
	v_fmac_f32_e32 v129, v142, v142
	v_fmac_f32_e32 v134, v140, v140
	v_add_f32_e32 v129, v129, v134
	v_mul_f32_e32 v134, v137, v137
	v_mul_f32_e32 v135, v139, v139
	v_fmac_f32_e32 v134, v136, v136
	v_fmac_f32_e32 v135, v138, v138
	v_add_f32_e32 v134, v134, v135
	v_add_f32_e32 v129, v129, v134
	v_mov_b32_e32 v134, v129
	s_nop 1
	v_permlane16_swap_b32_e32 v129, v134
	v_add_f32_e32 v129, v129, v134
	v_mov_b32_e32 v134, v129
	s_nop 1
	v_permlane32_swap_b32_e32 v129, v134
	v_add_f32_e32 v129, v129, v134
	v_max_f32_e32 v131, v131, v131
	v_max_f32_e32 v131, v131, v129
.LBB0_431:
	ds_read_b32 v136, v161 offset:64
	v_or_b32_e32 v129, 16, v160
	v_mad_i64_i32 v[134:135], s[76:77], s64, v129, 0
	v_lshl_add_u64 v[134:135], v[134:135], 1, v[132:133]
	s_waitcnt lgkmcnt(0)
	v_pk_mul_f32 v[140:141], v[62:63], v[136:137] op_sel_hi:[1,0]
	v_pk_mul_f32 v[144:145], v[60:61], v[136:137] op_sel_hi:[1,0]
	v_pk_mul_f32 v[138:139], v[58:59], v[136:137] op_sel_hi:[1,0]
	v_pk_mul_f32 v[142:143], v[56:57], v[136:137] op_sel_hi:[1,0]
	v_lshl_add_u64 v[166:167], s[26:27], 1, v[134:135]
	s_and_b64 vcc, exec, s[2:3]
	v_cvt_pk_bf16_f32 v162, v144, v145
	v_cvt_pk_bf16_f32 v163, v140, v141
	v_cvt_pk_bf16_f32 v164, v142, v143
	v_cvt_pk_bf16_f32 v165, v138, v139
	global_store_dwordx4 v[166:167], v[162:165], off sc1
	s_cbranch_vccnz .LBB0_433
	v_mul_f32_e32 v129, v145, v145
	v_mul_f32_e32 v137, v141, v141
	v_fmac_f32_e32 v129, v144, v144
	v_fmac_f32_e32 v137, v140, v140
	v_add_f32_e32 v129, v129, v137
	v_mul_f32_e32 v137, v143, v143
	v_mul_f32_e32 v139, v139, v139
	v_fmac_f32_e32 v137, v142, v142
	v_fmac_f32_e32 v139, v138, v138
	v_add_f32_e32 v137, v137, v139
	v_add_f32_e32 v129, v129, v137
	v_mov_b32_e32 v137, v129
	s_nop 1
	v_permlane16_swap_b32_e32 v129, v137
	v_add_f32_e32 v129, v129, v137
	v_mov_b32_e32 v137, v129
	s_nop 1
	v_permlane32_swap_b32_e32 v129, v137
	v_add_f32_e32 v129, v129, v137
	v_max_f32_e32 v130, v130, v130
	v_max_f32_e32 v130, v130, v129
.LBB0_433:
	v_mov_b32_e32 v137, v136
	v_mov_b32_e32 v138, v136
	v_mov_b32_e32 v139, v136
	v_pk_mul_f32 v[140:141], v[118:119], v[138:139]
	v_pk_mul_f32 v[142:143], v[116:117], v[136:137]
	v_pk_mul_f32 v[138:139], v[114:115], v[138:139]
	v_pk_mul_f32 v[136:137], v[112:113], v[136:137]
	v_lshl_add_u64 v[134:135], s[14:15], 1, v[134:135]
	s_and_b64 vcc, exec, s[2:3]
	v_cvt_pk_bf16_f32 v162, v142, v143
	v_cvt_pk_bf16_f32 v163, v140, v141
	v_cvt_pk_bf16_f32 v164, v136, v137
	v_cvt_pk_bf16_f32 v165, v138, v139
	global_store_dwordx4 v[134:135], v[162:165], off sc1
	s_cbranch_vccnz .LBB0_435
	v_mul_f32_e32 v129, v143, v143
	v_mul_f32_e32 v134, v141, v141
	v_fmac_f32_e32 v129, v142, v142
	v_fmac_f32_e32 v134, v140, v140
	v_add_f32_e32 v129, v129, v134
	v_mul_f32_e32 v134, v137, v137
	v_mul_f32_e32 v135, v139, v139
	v_fmac_f32_e32 v134, v136, v136
	v_fmac_f32_e32 v135, v138, v138
	v_add_f32_e32 v134, v134, v135
	v_add_f32_e32 v129, v129, v134
	v_mov_b32_e32 v134, v129
	s_nop 1
	v_permlane16_swap_b32_e32 v129, v134
	v_add_f32_e32 v129, v129, v134
	v_mov_b32_e32 v134, v129
	s_nop 1
	v_permlane32_swap_b32_e32 v129, v134
	v_add_f32_e32 v129, v129, v134
	v_max_f32_e32 v131, v131, v131
	v_max_f32_e32 v131, v131, v129
.LBB0_435:
	ds_read_b32 v136, v161 offset:128
	v_or_b32_e32 v129, 32, v160
	v_mad_i64_i32 v[134:135], s[76:77], s64, v129, 0
	v_lshl_add_u64 v[134:135], v[134:135], 1, v[132:133]
	s_waitcnt lgkmcnt(0)
	v_pk_mul_f32 v[140:141], v[54:55], v[136:137] op_sel_hi:[1,0]
	v_pk_mul_f32 v[144:145], v[52:53], v[136:137] op_sel_hi:[1,0]
	v_pk_mul_f32 v[138:139], v[46:47], v[136:137] op_sel_hi:[1,0]
	v_pk_mul_f32 v[142:143], v[44:45], v[136:137] op_sel_hi:[1,0]
	v_lshl_add_u64 v[166:167], s[26:27], 1, v[134:135]
	s_and_b64 vcc, exec, s[2:3]
	v_cvt_pk_bf16_f32 v162, v144, v145
	v_cvt_pk_bf16_f32 v163, v140, v141
	v_cvt_pk_bf16_f32 v164, v142, v143
	v_cvt_pk_bf16_f32 v165, v138, v139
	global_store_dwordx4 v[166:167], v[162:165], off sc1
	s_cbranch_vccnz .LBB0_437
	v_mul_f32_e32 v129, v145, v145
	v_mul_f32_e32 v137, v141, v141
	v_fmac_f32_e32 v129, v144, v144
	v_fmac_f32_e32 v137, v140, v140
	v_add_f32_e32 v129, v129, v137
	v_mul_f32_e32 v137, v143, v143
	v_mul_f32_e32 v139, v139, v139
	v_fmac_f32_e32 v137, v142, v142
	v_fmac_f32_e32 v139, v138, v138
	v_add_f32_e32 v137, v137, v139
	v_add_f32_e32 v129, v129, v137
	v_mov_b32_e32 v137, v129
	s_nop 1
	v_permlane16_swap_b32_e32 v129, v137
	v_add_f32_e32 v129, v129, v137
	v_mov_b32_e32 v137, v129
	s_nop 1
	v_permlane32_swap_b32_e32 v129, v137
	v_add_f32_e32 v129, v129, v137
	v_max_f32_e32 v130, v130, v130
	v_max_f32_e32 v130, v130, v129
.LBB0_437:
	v_mov_b32_e32 v137, v136
	v_mov_b32_e32 v138, v136
	v_mov_b32_e32 v139, v136
	v_pk_mul_f32 v[140:141], v[110:111], v[138:139]
	v_pk_mul_f32 v[142:143], v[108:109], v[136:137]
	v_pk_mul_f32 v[138:139], v[106:107], v[138:139]
	v_pk_mul_f32 v[136:137], v[104:105], v[136:137]
	v_lshl_add_u64 v[134:135], s[14:15], 1, v[134:135]
	s_and_b64 vcc, exec, s[2:3]
	v_cvt_pk_bf16_f32 v162, v142, v143
	v_cvt_pk_bf16_f32 v163, v140, v141
	v_cvt_pk_bf16_f32 v164, v136, v137
	v_cvt_pk_bf16_f32 v165, v138, v139
	global_store_dwordx4 v[134:135], v[162:165], off sc1
	s_cbranch_vccnz .LBB0_439
	v_mul_f32_e32 v129, v143, v143
	v_mul_f32_e32 v134, v141, v141
	v_fmac_f32_e32 v129, v142, v142
	v_fmac_f32_e32 v134, v140, v140
	v_add_f32_e32 v129, v129, v134
	v_mul_f32_e32 v134, v137, v137
	v_mul_f32_e32 v135, v139, v139
	v_fmac_f32_e32 v134, v136, v136
	v_fmac_f32_e32 v135, v138, v138
	v_add_f32_e32 v134, v134, v135
	v_add_f32_e32 v129, v129, v134
	v_mov_b32_e32 v134, v129
	s_nop 1
	v_permlane16_swap_b32_e32 v129, v134
	v_add_f32_e32 v129, v129, v134
	v_mov_b32_e32 v134, v129
	s_nop 1
	v_permlane32_swap_b32_e32 v129, v134
	v_add_f32_e32 v129, v129, v134
	v_max_f32_e32 v131, v131, v131
	v_max_f32_e32 v131, v131, v129
.LBB0_439:
	ds_read_b32 v136, v161 offset:192
	v_or_b32_e32 v129, 48, v160
	v_mad_i64_i32 v[134:135], s[76:77], s64, v129, 0
	v_lshl_add_u64 v[134:135], v[134:135], 1, v[132:133]
	s_waitcnt lgkmcnt(0)
	v_pk_mul_f32 v[140:141], v[38:39], v[136:137] op_sel_hi:[1,0]
	v_pk_mul_f32 v[144:145], v[36:37], v[136:137] op_sel_hi:[1,0]
	v_pk_mul_f32 v[138:139], v[34:35], v[136:137] op_sel_hi:[1,0]
	v_pk_mul_f32 v[142:143], v[32:33], v[136:137] op_sel_hi:[1,0]
	v_lshl_add_u64 v[166:167], s[26:27], 1, v[134:135]
	s_and_b64 vcc, exec, s[2:3]
	v_cvt_pk_bf16_f32 v162, v144, v145
	v_cvt_pk_bf16_f32 v163, v140, v141
	v_cvt_pk_bf16_f32 v164, v142, v143
	v_cvt_pk_bf16_f32 v165, v138, v139
	global_store_dwordx4 v[166:167], v[162:165], off sc1
	s_cbranch_vccnz .LBB0_441
	v_mul_f32_e32 v129, v145, v145
	v_mul_f32_e32 v137, v141, v141
	v_fmac_f32_e32 v129, v144, v144
	v_fmac_f32_e32 v137, v140, v140
	v_add_f32_e32 v129, v129, v137
	v_mul_f32_e32 v137, v143, v143
	v_mul_f32_e32 v139, v139, v139
	v_fmac_f32_e32 v137, v142, v142
	v_fmac_f32_e32 v139, v138, v138
	v_add_f32_e32 v137, v137, v139
	v_add_f32_e32 v129, v129, v137
	v_mov_b32_e32 v137, v129
	s_nop 1
	v_permlane16_swap_b32_e32 v129, v137
	v_add_f32_e32 v129, v129, v137
	v_mov_b32_e32 v137, v129
	s_nop 1
	v_permlane32_swap_b32_e32 v129, v137
	v_add_f32_e32 v129, v129, v137
	v_max_f32_e32 v130, v130, v130
	v_max_f32_e32 v130, v130, v129
.LBB0_441:
	v_mov_b32_e32 v137, v136
	v_mov_b32_e32 v138, v136
	v_mov_b32_e32 v139, v136
	v_pk_mul_f32 v[140:141], v[102:103], v[138:139]
	v_pk_mul_f32 v[142:143], v[100:101], v[136:137]
	v_pk_mul_f32 v[138:139], v[98:99], v[138:139]
	v_pk_mul_f32 v[136:137], v[96:97], v[136:137]
	v_lshl_add_u64 v[134:135], s[14:15], 1, v[134:135]
	s_and_b64 vcc, exec, s[2:3]
	v_cvt_pk_bf16_f32 v162, v142, v143
	v_cvt_pk_bf16_f32 v163, v140, v141
	v_cvt_pk_bf16_f32 v164, v136, v137
	v_cvt_pk_bf16_f32 v165, v138, v139
	global_store_dwordx4 v[134:135], v[162:165], off sc1
	s_cbranch_vccnz .LBB0_443
	v_mul_f32_e32 v129, v143, v143
	v_mul_f32_e32 v134, v141, v141
	v_fmac_f32_e32 v129, v142, v142
	v_fmac_f32_e32 v134, v140, v140
	v_add_f32_e32 v129, v129, v134
	v_mul_f32_e32 v134, v137, v137
	v_mul_f32_e32 v135, v139, v139
	v_fmac_f32_e32 v134, v136, v136
	v_fmac_f32_e32 v135, v138, v138
	v_add_f32_e32 v134, v134, v135
	v_add_f32_e32 v129, v129, v134
	v_mov_b32_e32 v134, v129
	s_nop 1
	v_permlane16_swap_b32_e32 v129, v134
	v_add_f32_e32 v129, v129, v134
	v_mov_b32_e32 v134, v129
	s_nop 1
	v_permlane32_swap_b32_e32 v129, v134
	v_add_f32_e32 v129, v129, v134
	v_max_f32_e32 v131, v131, v131
	v_max_f32_e32 v131, v131, v129
.LBB0_443:
	ds_read_b32 v136, v161 offset:512
	v_add_u32_e32 v129, 0x80, v160
	v_mad_i64_i32 v[134:135], s[76:77], s64, v129, 0
	v_lshl_add_u64 v[134:135], v[134:135], 1, v[132:133]
	s_waitcnt lgkmcnt(0)
	v_pk_mul_f32 v[140:141], v[30:31], v[136:137] op_sel_hi:[1,0]
	v_pk_mul_f32 v[144:145], v[28:29], v[136:137] op_sel_hi:[1,0]
	v_pk_mul_f32 v[138:139], v[26:27], v[136:137] op_sel_hi:[1,0]
	v_pk_mul_f32 v[142:143], v[24:25], v[136:137] op_sel_hi:[1,0]
	v_lshl_add_u64 v[166:167], s[26:27], 1, v[134:135]
	s_and_b64 vcc, exec, s[2:3]
	v_cvt_pk_bf16_f32 v162, v144, v145
	v_cvt_pk_bf16_f32 v163, v140, v141
	v_cvt_pk_bf16_f32 v164, v142, v143
	v_cvt_pk_bf16_f32 v165, v138, v139
	global_store_dwordx4 v[166:167], v[162:165], off sc1
	s_cbranch_vccnz .LBB0_445
	v_mul_f32_e32 v129, v145, v145
	v_mul_f32_e32 v137, v141, v141
	v_fmac_f32_e32 v129, v144, v144
	v_fmac_f32_e32 v137, v140, v140
	v_add_f32_e32 v129, v129, v137
	v_mul_f32_e32 v137, v143, v143
	v_mul_f32_e32 v139, v139, v139
	v_fmac_f32_e32 v137, v142, v142
	v_fmac_f32_e32 v139, v138, v138
	v_add_f32_e32 v137, v137, v139
	v_add_f32_e32 v129, v129, v137
	v_mov_b32_e32 v137, v129
	s_nop 1
	v_permlane16_swap_b32_e32 v129, v137
	v_add_f32_e32 v129, v129, v137
	v_mov_b32_e32 v137, v129
	s_nop 1
	v_permlane32_swap_b32_e32 v129, v137
	v_add_f32_e32 v129, v129, v137
	v_max_f32_e32 v130, v130, v130
	v_max_f32_e32 v130, v130, v129
.LBB0_445:
	v_mov_b32_e32 v137, v136
	v_mov_b32_e32 v138, v136
	v_mov_b32_e32 v139, v136
	v_pk_mul_f32 v[140:141], v[94:95], v[138:139]
	v_pk_mul_f32 v[142:143], v[92:93], v[136:137]
	v_pk_mul_f32 v[138:139], v[90:91], v[138:139]
	v_pk_mul_f32 v[136:137], v[88:89], v[136:137]
	v_lshl_add_u64 v[134:135], s[14:15], 1, v[134:135]
	s_and_b64 vcc, exec, s[2:3]
	v_cvt_pk_bf16_f32 v162, v142, v143
	v_cvt_pk_bf16_f32 v163, v140, v141
	v_cvt_pk_bf16_f32 v164, v136, v137
	v_cvt_pk_bf16_f32 v165, v138, v139
	global_store_dwordx4 v[134:135], v[162:165], off sc1
	s_cbranch_vccnz .LBB0_447
	v_mul_f32_e32 v129, v143, v143
	v_mul_f32_e32 v134, v141, v141
	v_fmac_f32_e32 v129, v142, v142
	v_fmac_f32_e32 v134, v140, v140
	v_add_f32_e32 v129, v129, v134
	v_mul_f32_e32 v134, v137, v137
	v_mul_f32_e32 v135, v139, v139
	v_fmac_f32_e32 v134, v136, v136
	v_fmac_f32_e32 v135, v138, v138
	v_add_f32_e32 v134, v134, v135
	v_add_f32_e32 v129, v129, v134
	v_mov_b32_e32 v134, v129
	s_nop 1
	v_permlane16_swap_b32_e32 v129, v134
	v_add_f32_e32 v129, v129, v134
	v_mov_b32_e32 v134, v129
	s_nop 1
	v_permlane32_swap_b32_e32 v129, v134
	v_add_f32_e32 v129, v129, v134
	v_max_f32_e32 v131, v131, v131
	v_max_f32_e32 v131, v131, v129
.LBB0_447:
	ds_read_b32 v136, v161 offset:576
	v_add_u32_e32 v129, 0x90, v160
	v_mad_i64_i32 v[134:135], s[76:77], s64, v129, 0
	v_lshl_add_u64 v[134:135], v[134:135], 1, v[132:133]
	s_waitcnt lgkmcnt(0)
	v_pk_mul_f32 v[140:141], v[22:23], v[136:137] op_sel_hi:[1,0]
	v_pk_mul_f32 v[144:145], v[20:21], v[136:137] op_sel_hi:[1,0]
	v_pk_mul_f32 v[138:139], v[18:19], v[136:137] op_sel_hi:[1,0]
	v_pk_mul_f32 v[142:143], v[16:17], v[136:137] op_sel_hi:[1,0]
	v_lshl_add_u64 v[166:167], s[26:27], 1, v[134:135]
	s_and_b64 vcc, exec, s[2:3]
	v_cvt_pk_bf16_f32 v162, v144, v145
	v_cvt_pk_bf16_f32 v163, v140, v141
	v_cvt_pk_bf16_f32 v164, v142, v143
	v_cvt_pk_bf16_f32 v165, v138, v139
	global_store_dwordx4 v[166:167], v[162:165], off sc1
	s_cbranch_vccnz .LBB0_449
	v_mul_f32_e32 v129, v145, v145
	v_mul_f32_e32 v137, v141, v141
	v_fmac_f32_e32 v129, v144, v144
	v_fmac_f32_e32 v137, v140, v140
	v_add_f32_e32 v129, v129, v137
	v_mul_f32_e32 v137, v143, v143
	v_mul_f32_e32 v139, v139, v139
	v_fmac_f32_e32 v137, v142, v142
	v_fmac_f32_e32 v139, v138, v138
	v_add_f32_e32 v137, v137, v139
	v_add_f32_e32 v129, v129, v137
	v_mov_b32_e32 v137, v129
	s_nop 1
	v_permlane16_swap_b32_e32 v129, v137
	v_add_f32_e32 v129, v129, v137
	v_mov_b32_e32 v137, v129
	s_nop 1
	v_permlane32_swap_b32_e32 v129, v137
	v_add_f32_e32 v129, v129, v137
	v_max_f32_e32 v130, v130, v130
	v_max_f32_e32 v130, v130, v129
.LBB0_449:
	v_mov_b32_e32 v137, v136
	v_mov_b32_e32 v138, v136
	v_mov_b32_e32 v139, v136
	v_pk_mul_f32 v[140:141], v[86:87], v[138:139]
	v_pk_mul_f32 v[142:143], v[84:85], v[136:137]
	v_pk_mul_f32 v[138:139], v[82:83], v[138:139]
	v_pk_mul_f32 v[136:137], v[80:81], v[136:137]
	v_lshl_add_u64 v[134:135], s[14:15], 1, v[134:135]
	s_and_b64 vcc, exec, s[2:3]
	v_cvt_pk_bf16_f32 v162, v142, v143
	v_cvt_pk_bf16_f32 v163, v140, v141
	v_cvt_pk_bf16_f32 v164, v136, v137
	v_cvt_pk_bf16_f32 v165, v138, v139
	global_store_dwordx4 v[134:135], v[162:165], off sc1
	s_cbranch_vccnz .LBB0_451
	v_mul_f32_e32 v129, v143, v143
	v_mul_f32_e32 v134, v141, v141
	v_fmac_f32_e32 v129, v142, v142
	v_fmac_f32_e32 v134, v140, v140
	v_add_f32_e32 v129, v129, v134
	v_mul_f32_e32 v134, v137, v137
	v_mul_f32_e32 v135, v139, v139
	v_fmac_f32_e32 v134, v136, v136
	v_fmac_f32_e32 v135, v138, v138
	v_add_f32_e32 v134, v134, v135
	v_add_f32_e32 v129, v129, v134
	v_mov_b32_e32 v134, v129
	s_nop 1
	v_permlane16_swap_b32_e32 v129, v134
	v_add_f32_e32 v129, v129, v134
	v_mov_b32_e32 v134, v129
	s_nop 1
	v_permlane32_swap_b32_e32 v129, v134
	v_add_f32_e32 v129, v129, v134
	v_max_f32_e32 v131, v131, v131
	v_max_f32_e32 v131, v131, v129
.LBB0_451:
	ds_read_b32 v136, v161 offset:640
	v_add_u32_e32 v129, 0xa0, v160
	v_mad_i64_i32 v[134:135], s[76:77], s64, v129, 0
	v_lshl_add_u64 v[134:135], v[134:135], 1, v[132:133]
	s_waitcnt lgkmcnt(0)
	v_pk_mul_f32 v[140:141], v[14:15], v[136:137] op_sel_hi:[1,0]
	v_pk_mul_f32 v[144:145], v[12:13], v[136:137] op_sel_hi:[1,0]
	v_pk_mul_f32 v[138:139], v[10:11], v[136:137] op_sel_hi:[1,0]
	v_pk_mul_f32 v[142:143], v[8:9], v[136:137] op_sel_hi:[1,0]
	v_lshl_add_u64 v[166:167], s[26:27], 1, v[134:135]
	s_and_b64 vcc, exec, s[2:3]
	v_cvt_pk_bf16_f32 v162, v144, v145
	v_cvt_pk_bf16_f32 v163, v140, v141
	v_cvt_pk_bf16_f32 v164, v142, v143
	v_cvt_pk_bf16_f32 v165, v138, v139
	global_store_dwordx4 v[166:167], v[162:165], off sc1
	s_cbranch_vccnz .LBB0_453
	v_mul_f32_e32 v129, v145, v145
	v_mul_f32_e32 v137, v141, v141
	v_fmac_f32_e32 v129, v144, v144
	v_fmac_f32_e32 v137, v140, v140
	v_add_f32_e32 v129, v129, v137
	v_mul_f32_e32 v137, v143, v143
	v_mul_f32_e32 v139, v139, v139
	v_fmac_f32_e32 v137, v142, v142
	v_fmac_f32_e32 v139, v138, v138
	v_add_f32_e32 v137, v137, v139
	v_add_f32_e32 v129, v129, v137
	v_mov_b32_e32 v137, v129
	s_nop 1
	v_permlane16_swap_b32_e32 v129, v137
	v_add_f32_e32 v129, v129, v137
	v_mov_b32_e32 v137, v129
	s_nop 1
	v_permlane32_swap_b32_e32 v129, v137
	v_add_f32_e32 v129, v129, v137
	v_max_f32_e32 v130, v130, v130
	v_max_f32_e32 v130, v130, v129
.LBB0_453:
	v_mov_b32_e32 v137, v136
	v_mov_b32_e32 v138, v136
	v_mov_b32_e32 v139, v136
	v_pk_mul_f32 v[140:141], v[70:71], v[138:139]
	v_pk_mul_f32 v[142:143], v[68:69], v[136:137]
	v_pk_mul_f32 v[138:139], v[66:67], v[138:139]
	v_pk_mul_f32 v[136:137], v[64:65], v[136:137]
	v_lshl_add_u64 v[134:135], s[14:15], 1, v[134:135]
	s_and_b64 vcc, exec, s[2:3]
	v_cvt_pk_bf16_f32 v162, v142, v143
	v_cvt_pk_bf16_f32 v163, v140, v141
	v_cvt_pk_bf16_f32 v164, v136, v137
	v_cvt_pk_bf16_f32 v165, v138, v139
	global_store_dwordx4 v[134:135], v[162:165], off sc1
	s_cbranch_vccnz .LBB0_455
	v_mul_f32_e32 v129, v143, v143
	v_mul_f32_e32 v134, v141, v141
	v_fmac_f32_e32 v129, v142, v142
	v_fmac_f32_e32 v134, v140, v140
	v_add_f32_e32 v129, v129, v134
	v_mul_f32_e32 v134, v137, v137
	v_mul_f32_e32 v135, v139, v139
	v_fmac_f32_e32 v134, v136, v136
	v_fmac_f32_e32 v135, v138, v138
	v_add_f32_e32 v134, v134, v135
	v_add_f32_e32 v129, v129, v134
	v_mov_b32_e32 v134, v129
	s_nop 1
	v_permlane16_swap_b32_e32 v129, v134
	v_add_f32_e32 v129, v129, v134
	v_mov_b32_e32 v134, v129
	s_nop 1
	v_permlane32_swap_b32_e32 v129, v134
	v_add_f32_e32 v129, v129, v134
	v_max_f32_e32 v131, v131, v131
	v_max_f32_e32 v131, v131, v129
.LBB0_455:
	ds_read_b32 v134, v161 offset:704
	v_add_u32_e32 v129, 0xb0, v160
	v_mad_i64_i32 v[136:137], s[76:77], s64, v129, 0
	v_lshl_add_u64 v[132:133], v[136:137], 1, v[132:133]
	s_waitcnt lgkmcnt(0)
	v_pk_mul_f32 v[138:139], v[6:7], v[134:135] op_sel_hi:[1,0]
	v_pk_mul_f32 v[142:143], v[4:5], v[134:135] op_sel_hi:[1,0]
	v_pk_mul_f32 v[136:137], v[2:3], v[134:135] op_sel_hi:[1,0]
	v_pk_mul_f32 v[140:141], v[0:1], v[134:135] op_sel_hi:[1,0]
	v_lshl_add_u64 v[144:145], s[26:27], 1, v[132:133]
	s_and_b64 vcc, exec, s[2:3]
	v_cvt_pk_bf16_f32 v160, v142, v143
	v_cvt_pk_bf16_f32 v161, v138, v139
	v_cvt_pk_bf16_f32 v162, v140, v141
	v_cvt_pk_bf16_f32 v163, v136, v137
	global_store_dwordx4 v[144:145], v[160:163], off sc1
	s_cbranch_vccnz .LBB0_457
	v_mul_f32_e32 v129, v143, v143
	v_mul_f32_e32 v135, v139, v139
	v_fmac_f32_e32 v129, v142, v142
	v_fmac_f32_e32 v135, v138, v138
	v_add_f32_e32 v129, v129, v135
	v_mul_f32_e32 v135, v141, v141
	v_mul_f32_e32 v137, v137, v137
	v_fmac_f32_e32 v135, v140, v140
	v_fmac_f32_e32 v137, v136, v136
	v_add_f32_e32 v135, v135, v137
	v_add_f32_e32 v129, v129, v135
	v_mov_b32_e32 v135, v129
	s_nop 1
	v_permlane16_swap_b32_e32 v129, v135
	v_add_f32_e32 v129, v129, v135
	v_mov_b32_e32 v135, v129
	s_nop 1
	v_permlane32_swap_b32_e32 v129, v135
	v_add_f32_e32 v129, v129, v135
	v_max_f32_e32 v130, v130, v130
	v_max_f32_e32 v130, v130, v129
.LBB0_457:
	v_mov_b32_e32 v135, v134
	v_mov_b32_e32 v136, v134
	v_mov_b32_e32 v137, v134
	v_pk_mul_f32 v[138:139], v[50:51], v[136:137]
	v_pk_mul_f32 v[140:141], v[48:49], v[134:135]
	v_pk_mul_f32 v[136:137], v[42:43], v[136:137]
	v_pk_mul_f32 v[134:135], v[40:41], v[134:135]
	v_lshl_add_u64 v[132:133], s[14:15], 1, v[132:133]
	s_and_b64 vcc, exec, s[2:3]
	v_cvt_pk_bf16_f32 v142, v140, v141
	v_cvt_pk_bf16_f32 v143, v138, v139
	v_cvt_pk_bf16_f32 v144, v134, v135
	v_cvt_pk_bf16_f32 v145, v136, v137
	global_store_dwordx4 v[132:133], v[142:145], off sc1
	s_cbranch_vccnz .LBB0_463
	v_mul_f32_e32 v129, v141, v141
	v_mul_f32_e32 v132, v139, v139
	v_fmac_f32_e32 v129, v140, v140
	v_fmac_f32_e32 v132, v138, v138
	v_add_f32_e32 v129, v129, v132
	v_mul_f32_e32 v132, v135, v135
	v_fmac_f32_e32 v132, v134, v134
	ds_bpermute_b32 v134, v146, v130
	v_mul_f32_e32 v133, v137, v137
	v_fmac_f32_e32 v133, v136, v136
	v_add_f32_e32 v132, v132, v133
	v_max_f32_e32 v130, v130, v130
	s_waitcnt lgkmcnt(0)
	v_max_f32_e32 v133, v134, v134
	v_max_f32_e32 v133, v130, v133
	ds_bpermute_b32 v134, v147, v133
	v_add_f32_e32 v129, v129, v132
	v_mov_b32_e32 v132, v129
	s_nop 1
	v_permlane16_swap_b32_e32 v129, v132
	v_add_f32_e32 v129, v129, v132
	s_waitcnt lgkmcnt(0)
	v_max_f32_e32 v132, v134, v134
	v_max_f32_e32 v132, v133, v132
	ds_bpermute_b32 v133, v148, v132
	s_lshr_b32 s2, s73, 5
	s_mul_i32 s14, s2, 12
	s_lshl_b32 s2, s73, 1
	v_mov_b32_e32 v130, v129
	s_waitcnt lgkmcnt(0)
	v_max_f32_e32 v133, v133, v133
	v_max_f32_e32 v132, v132, v133
	ds_bpermute_b32 v133, v149, v132
	s_and_b32 s2, s2, 62
	v_permlane32_swap_b32_e32 v129, v130
	v_cmp_eq_u32_e32 vcc, 0, v159
	s_add_i32 s14, s14, s74
	s_add_i32 s26, s59, s2
	s_and_saveexec_b64 s[2:3], vcc
	s_cbranch_execz .LBB0_460
	s_lshl_b32 s27, s14, 7
	s_add_i32 s74, s27, s26
	s_ashr_i32 s75, s74, 31
	s_lshl_b64 s[74:75], s[74:75], 2
	s_add_u32 s74, s47, s74
	s_waitcnt lgkmcnt(0)
	v_max_f32_e32 v133, v133, v133
	v_max_f32_e32 v132, v132, v132
	s_addc_u32 s75, s48, s75
	v_max_f32_e32 v132, v132, v133
	global_store_dword v128, v132, s[74:75]

.LBB0_464:
	s_and_b64 vcc, exec, s[2:3]
	s_cbranch_vccz .LBB0_469
	s_lshl_b32 s2, s29, 2
	s_waitcnt lgkmcnt(0)
	v_mbcnt_lo_u32_b32 v130, -1, 0
	v_mbcnt_hi_u32_b32 v130, -1, v130
	s_add_i32 s2, s62, s2
	v_and_b32_e32 v129, 15, v130
	v_or_b32_e32 v141, s28, v129
	v_lshl_add_u32 v129, v129, 2, s2
	ds_read_b32 v132, v129
	s_lshl_b32 s2, s72, 9
	s_or_b32 s2, s2, s65
	v_ashrrev_i32_e32 v130, 1, v130
	s_add_u32 s2, s45, s2
	v_and_b32_e32 v130, -8, v130
	s_addc_u32 s3, s46, 0
	v_ashrrev_i32_e32 v131, 31, v130
	s_waitcnt lgkmcnt(0)
	v_mov_b32_e32 v133, v132
	v_lshl_add_u64 v[130:131], v[130:131], 1, s[2:3]
	s_cmp_lg_u32 s72, 4
	s_mov_b64 s[2:3], -1
	v_pk_mul_f32 v[76:77], v[76:77], v[132:133]
	v_pk_mul_f32 v[72:73], v[72:73], v[132:133]
	v_or_b32_e32 v140, 16, v141
	v_or_b32_e32 v139, 32, v141
	v_or_b32_e32 v138, 48, v141
	v_add_u32_e32 v137, 0x80, v141
	v_add_u32_e32 v136, 0x90, v141
	v_add_u32_e32 v135, 0xa0, v141
	v_add_u32_e32 v134, 0xb0, v141
	s_cbranch_scc0 .LBB0_467
	v_mov_b32_e32 v162, v132
	v_mov_b32_e32 v163, v132
	v_mad_i64_i32 v[160:161], s[2:3], v141, s66, v[130:131]
	v_pk_mul_f32 v[144:145], v[78:79], v[162:163]
	v_cvt_pk_bf16_f32 v142, v76, v77
	v_pk_mul_f32 v[164:165], v[74:75], v[162:163]
	v_cvt_pk_bf16_f32 v143, v144, v145
	v_cvt_pk_bf16_f32 v144, v72, v73
	v_pk_mul_f32 v[124:125], v[124:125], v[132:133]
	v_cvt_pk_bf16_f32 v145, v164, v165
	global_store_dwordx4 v[160:161], v[142:145], off sc1
	v_pk_mul_f32 v[126:127], v[126:127], v[162:163]
	s_nop 0
	v_pk_mul_f32 v[142:143], v[122:123], v[162:163]
	v_pk_mul_f32 v[122:123], v[120:121], v[132:133]
	v_cvt_pk_bf16_f32 v120, v124, v125
	v_cvt_pk_bf16_f32 v121, v126, v127
	v_mad_i64_i32 v[126:127], s[2:3], v140, s66, v[130:131]
	v_cvt_pk_bf16_f32 v122, v122, v123
	v_cvt_pk_bf16_f32 v123, v142, v143
	ds_read_b32 v124, v129 offset:64
	global_store_dwordx4 v[160:161], v[120:123], off offset:256 sc1
	s_waitcnt lgkmcnt(0)
	v_pk_mul_f32 v[142:143], v[58:59], v[124:125] op_sel_hi:[1,0]
	v_pk_mul_f32 v[120:121], v[60:61], v[124:125] op_sel_hi:[1,0]
	v_pk_mul_f32 v[122:123], v[62:63], v[124:125] op_sel_hi:[1,0]
	v_cvt_pk_bf16_f32 v120, v120, v121
	v_pk_mul_f32 v[144:145], v[56:57], v[124:125] op_sel_hi:[1,0]
	v_cvt_pk_bf16_f32 v121, v122, v123
	v_pk_mul_f32 v[116:117], v[116:117], v[124:125] op_sel_hi:[1,0]
	v_cvt_pk_bf16_f32 v122, v144, v145
	v_cvt_pk_bf16_f32 v123, v142, v143
	global_store_dwordx4 v[126:127], v[120:123], off sc1
	v_pk_mul_f32 v[118:119], v[118:119], v[124:125] op_sel_hi:[1,0]
	s_nop 0
	v_pk_mul_f32 v[120:121], v[114:115], v[124:125] op_sel_hi:[1,0]
	v_pk_mul_f32 v[114:115], v[112:113], v[124:125] op_sel_hi:[1,0]
	v_cvt_pk_bf16_f32 v112, v116, v117
	v_cvt_pk_bf16_f32 v113, v118, v119
	v_mad_i64_i32 v[118:119], s[2:3], v139, s66, v[130:131]
	v_cvt_pk_bf16_f32 v114, v114, v115
	v_cvt_pk_bf16_f32 v115, v120, v121
	ds_read_b32 v116, v129 offset:128
	global_store_dwordx4 v[126:127], v[112:115], off offset:256 sc1
	s_waitcnt lgkmcnt(0)
	v_pk_mul_f32 v[120:121], v[46:47], v[116:117] op_sel_hi:[1,0]
	v_pk_mul_f32 v[112:113], v[52:53], v[116:117] op_sel_hi:[1,0]
	v_pk_mul_f32 v[114:115], v[54:55], v[116:117] op_sel_hi:[1,0]
	v_cvt_pk_bf16_f32 v112, v112, v113
	v_pk_mul_f32 v[122:123], v[44:45], v[116:117] op_sel_hi:[1,0]
	v_cvt_pk_bf16_f32 v113, v114, v115
	v_pk_mul_f32 v[108:109], v[108:109], v[116:117] op_sel_hi:[1,0]
	v_cvt_pk_bf16_f32 v114, v122, v123
	v_cvt_pk_bf16_f32 v115, v120, v121
	global_store_dwordx4 v[118:119], v[112:115], off sc1
	v_pk_mul_f32 v[110:111], v[110:111], v[116:117] op_sel_hi:[1,0]
	s_nop 0
	v_pk_mul_f32 v[112:113], v[106:107], v[116:117] op_sel_hi:[1,0]
	v_pk_mul_f32 v[106:107], v[104:105], v[116:117] op_sel_hi:[1,0]
	v_cvt_pk_bf16_f32 v104, v108, v109
	v_cvt_pk_bf16_f32 v105, v110, v111
	v_mad_i64_i32 v[110:111], s[2:3], v138, s66, v[130:131]
	v_cvt_pk_bf16_f32 v106, v106, v107
	v_cvt_pk_bf16_f32 v107, v112, v113
	ds_read_b32 v108, v129 offset:192
	global_store_dwordx4 v[118:119], v[104:107], off offset:256 sc1
	s_waitcnt lgkmcnt(0)
	v_pk_mul_f32 v[112:113], v[34:35], v[108:109] op_sel_hi:[1,0]
	v_pk_mul_f32 v[104:105], v[36:37], v[108:109] op_sel_hi:[1,0]
	v_pk_mul_f32 v[106:107], v[38:39], v[108:109] op_sel_hi:[1,0]
	v_cvt_pk_bf16_f32 v104, v104, v105
	v_pk_mul_f32 v[114:115], v[32:33], v[108:109] op_sel_hi:[1,0]
	v_cvt_pk_bf16_f32 v105, v106, v107
	v_pk_mul_f32 v[100:101], v[100:101], v[108:109] op_sel_hi:[1,0]
	v_cvt_pk_bf16_f32 v106, v114, v115
	v_cvt_pk_bf16_f32 v107, v112, v113
	global_store_dwordx4 v[110:111], v[104:107], off sc1
	v_pk_mul_f32 v[102:103], v[102:103], v[108:109] op_sel_hi:[1,0]
	s_nop 0
	v_pk_mul_f32 v[104:105], v[98:99], v[108:109] op_sel_hi:[1,0]
	v_pk_mul_f32 v[98:99], v[96:97], v[108:109] op_sel_hi:[1,0]
	v_cvt_pk_bf16_f32 v96, v100, v101
	v_cvt_pk_bf16_f32 v97, v102, v103
	v_mad_i64_i32 v[102:103], s[2:3], v137, s66, v[130:131]
	v_cvt_pk_bf16_f32 v98, v98, v99
	v_cvt_pk_bf16_f32 v99, v104, v105
	ds_read_b32 v100, v129 offset:512
	global_store_dwordx4 v[110:111], v[96:99], off offset:256 sc1
	s_waitcnt lgkmcnt(0)
	v_pk_mul_f32 v[104:105], v[26:27], v[100:101] op_sel_hi:[1,0]
	v_pk_mul_f32 v[96:97], v[28:29], v[100:101] op_sel_hi:[1,0]
	v_pk_mul_f32 v[98:99], v[30:31], v[100:101] op_sel_hi:[1,0]
	v_cvt_pk_bf16_f32 v96, v96, v97
	v_pk_mul_f32 v[106:107], v[24:25], v[100:101] op_sel_hi:[1,0]
	v_cvt_pk_bf16_f32 v97, v98, v99
	v_pk_mul_f32 v[92:93], v[92:93], v[100:101] op_sel_hi:[1,0]
	v_cvt_pk_bf16_f32 v98, v106, v107
	v_cvt_pk_bf16_f32 v99, v104, v105
	global_store_dwordx4 v[102:103], v[96:99], off sc1
	v_pk_mul_f32 v[94:95], v[94:95], v[100:101] op_sel_hi:[1,0]
	s_nop 0
	v_pk_mul_f32 v[96:97], v[90:91], v[100:101] op_sel_hi:[1,0]
	v_pk_mul_f32 v[90:91], v[88:89], v[100:101] op_sel_hi:[1,0]
	v_cvt_pk_bf16_f32 v88, v92, v93
	v_cvt_pk_bf16_f32 v89, v94, v95
	v_mad_i64_i32 v[94:95], s[2:3], v136, s66, v[130:131]
	v_cvt_pk_bf16_f32 v90, v90, v91
	v_cvt_pk_bf16_f32 v91, v96, v97
	ds_read_b32 v92, v129 offset:576
	global_store_dwordx4 v[102:103], v[88:91], off offset:256 sc1
	s_waitcnt lgkmcnt(0)
	v_pk_mul_f32 v[96:97], v[18:19], v[92:93] op_sel_hi:[1,0]
	v_pk_mul_f32 v[88:89], v[20:21], v[92:93] op_sel_hi:[1,0]
	v_pk_mul_f32 v[90:91], v[22:23], v[92:93] op_sel_hi:[1,0]
	v_cvt_pk_bf16_f32 v88, v88, v89
	v_pk_mul_f32 v[98:99], v[16:17], v[92:93] op_sel_hi:[1,0]
	v_cvt_pk_bf16_f32 v89, v90, v91
	v_pk_mul_f32 v[84:85], v[84:85], v[92:93] op_sel_hi:[1,0]
	v_cvt_pk_bf16_f32 v90, v98, v99
	v_cvt_pk_bf16_f32 v91, v96, v97
	global_store_dwordx4 v[94:95], v[88:91], off sc1
	v_pk_mul_f32 v[86:87], v[86:87], v[92:93] op_sel_hi:[1,0]
	s_nop 0
	v_pk_mul_f32 v[88:89], v[82:83], v[92:93] op_sel_hi:[1,0]
	v_pk_mul_f32 v[82:83], v[80:81], v[92:93] op_sel_hi:[1,0]
	v_cvt_pk_bf16_f32 v80, v84, v85
	v_cvt_pk_bf16_f32 v81, v86, v87
	v_mad_i64_i32 v[86:87], s[2:3], v135, s66, v[130:131]
	v_cvt_pk_bf16_f32 v82, v82, v83
	v_cvt_pk_bf16_f32 v83, v88, v89
	ds_read_b32 v84, v129 offset:640
	global_store_dwordx4 v[94:95], v[80:83], off offset:256 sc1
	s_waitcnt lgkmcnt(0)
	v_pk_mul_f32 v[88:89], v[10:11], v[84:85] op_sel_hi:[1,0]
	v_pk_mul_f32 v[80:81], v[12:13], v[84:85] op_sel_hi:[1,0]
	v_pk_mul_f32 v[82:83], v[14:15], v[84:85] op_sel_hi:[1,0]
	v_cvt_pk_bf16_f32 v80, v80, v81
	v_pk_mul_f32 v[90:91], v[8:9], v[84:85] op_sel_hi:[1,0]
	v_cvt_pk_bf16_f32 v81, v82, v83
	v_pk_mul_f32 v[68:69], v[68:69], v[84:85] op_sel_hi:[1,0]
	v_cvt_pk_bf16_f32 v82, v90, v91
	v_cvt_pk_bf16_f32 v83, v88, v89
	global_store_dwordx4 v[86:87], v[80:83], off sc1
	v_pk_mul_f32 v[70:71], v[70:71], v[84:85] op_sel_hi:[1,0]
	s_nop 0
	v_pk_mul_f32 v[80:81], v[66:67], v[84:85] op_sel_hi:[1,0]
	v_pk_mul_f32 v[66:67], v[64:65], v[84:85] op_sel_hi:[1,0]
	v_cvt_pk_bf16_f32 v64, v68, v69
	v_cvt_pk_bf16_f32 v65, v70, v71
	v_mad_i64_i32 v[70:71], s[2:3], v134, s66, v[130:131]
	v_cvt_pk_bf16_f32 v66, v66, v67
	v_cvt_pk_bf16_f32 v67, v80, v81
	ds_read_b32 v68, v129 offset:704
	global_store_dwordx4 v[86:87], v[64:67], off offset:256 sc1
	s_mov_b64 s[2:3], 0
	s_waitcnt lgkmcnt(0)
	v_pk_mul_f32 v[80:81], v[2:3], v[68:69] op_sel_hi:[1,0]
	v_pk_mul_f32 v[64:65], v[4:5], v[68:69] op_sel_hi:[1,0]
	v_pk_mul_f32 v[66:67], v[6:7], v[68:69] op_sel_hi:[1,0]
	v_cvt_pk_bf16_f32 v64, v64, v65
	v_pk_mul_f32 v[82:83], v[0:1], v[68:69] op_sel_hi:[1,0]
	v_cvt_pk_bf16_f32 v65, v66, v67
	v_pk_mul_f32 v[50:51], v[50:51], v[68:69] op_sel_hi:[1,0]
	v_cvt_pk_bf16_f32 v66, v82, v83
	v_cvt_pk_bf16_f32 v67, v80, v81
	global_store_dwordx4 v[70:71], v[64:67], off sc1
	v_pk_mul_f32 v[48:49], v[48:49], v[68:69] op_sel_hi:[1,0]
	s_nop 0
	v_pk_mul_f32 v[64:65], v[42:43], v[68:69] op_sel_hi:[1,0]
	v_pk_mul_f32 v[42:43], v[40:41], v[68:69] op_sel_hi:[1,0]
	v_cvt_pk_bf16_f32 v40, v48, v49
	v_cvt_pk_bf16_f32 v41, v50, v51
	s_nop 0
	v_cvt_pk_bf16_f32 v42, v42, v43
	v_cvt_pk_bf16_f32 v43, v64, v65
	global_store_dwordx4 v[70:71], v[40:43], off offset:256 sc1
.LBB0_467:
	s_andn2_b64 vcc, exec, s[2:3]
	s_cbranch_vccnz .LBB0_469
	v_mov_b32_e32 v133, v132
	v_pk_mul_f32 v[42:43], v[78:79], v[132:133]
	v_pk_mul_f32 v[48:49], v[74:75], v[132:133]
	v_cvt_pk_bf16_f32 v40, v76, v77
	v_cvt_pk_bf16_f32 v41, v42, v43
	v_cvt_pk_bf16_f32 v42, v72, v73
	v_mad_i64_i32 v[50:51], s[2:3], v141, s66, v[130:131]
	v_cvt_pk_bf16_f32 v43, v48, v49
	ds_read_b32 v48, v129 offset:64
	global_store_dwordx4 v[50:51], v[40:43], off sc1
	s_waitcnt lgkmcnt(0)
	v_pk_mul_f32 v[50:51], v[58:59], v[48:49] op_sel_hi:[1,0]
	v_pk_mul_f32 v[42:43], v[62:63], v[48:49] op_sel_hi:[1,0]
	v_pk_mul_f32 v[40:41], v[60:61], v[48:49] op_sel_hi:[1,0]
	v_pk_mul_f32 v[48:49], v[56:57], v[48:49] op_sel_hi:[1,0]
	v_cvt_pk_bf16_f32 v40, v40, v41
	v_cvt_pk_bf16_f32 v41, v42, v43
	s_nop 0
	v_cvt_pk_bf16_f32 v42, v48, v49
	v_cvt_pk_bf16_f32 v43, v50, v51
	ds_read_b32 v48, v129 offset:128
	v_mad_i64_i32 v[50:51], s[2:3], v140, s66, v[130:131]
	global_store_dwordx4 v[50:51], v[40:43], off sc1
	s_waitcnt lgkmcnt(0)
	v_pk_mul_f32 v[44:45], v[44:45], v[48:49] op_sel_hi:[1,0]
	v_pk_mul_f32 v[42:43], v[54:55], v[48:49] op_sel_hi:[1,0]
	v_pk_mul_f32 v[40:41], v[52:53], v[48:49] op_sel_hi:[1,0]
	v_pk_mul_f32 v[46:47], v[46:47], v[48:49] op_sel_hi:[1,0]
	v_cvt_pk_bf16_f32 v40, v40, v41
	v_cvt_pk_bf16_f32 v41, v42, v43
	v_cvt_pk_bf16_f32 v42, v44, v45
	s_nop 0
	v_cvt_pk_bf16_f32 v43, v46, v47
	ds_read_b32 v44, v129 offset:192
	v_mad_i64_i32 v[46:47], s[2:3], v139, s66, v[130:131]
	global_store_dwordx4 v[46:47], v[40:43], off sc1
	s_waitcnt lgkmcnt(0)
	v_pk_mul_f32 v[36:37], v[36:37], v[44:45] op_sel_hi:[1,0]
	v_pk_mul_f32 v[40:41], v[34:35], v[44:45] op_sel_hi:[1,0]
	v_pk_mul_f32 v[34:35], v[32:33], v[44:45] op_sel_hi:[1,0]
	v_pk_mul_f32 v[38:39], v[38:39], v[44:45] op_sel_hi:[1,0]
	v_cvt_pk_bf16_f32 v32, v36, v37
	s_nop 0
	v_cvt_pk_bf16_f32 v33, v38, v39
	v_cvt_pk_bf16_f32 v34, v34, v35
	v_cvt_pk_bf16_f32 v35, v40, v41
	ds_read_b32 v36, v129 offset:512
	v_mad_i64_i32 v[38:39], s[2:3], v138, s66, v[130:131]
	global_store_dwordx4 v[38:39], v[32:35], off sc1
	s_waitcnt lgkmcnt(0)
	v_pk_mul_f32 v[28:29], v[28:29], v[36:37] op_sel_hi:[1,0]
	v_pk_mul_f32 v[32:33], v[26:27], v[36:37] op_sel_hi:[1,0]
	v_pk_mul_f32 v[26:27], v[24:25], v[36:37] op_sel_hi:[1,0]
	v_pk_mul_f32 v[30:31], v[30:31], v[36:37] op_sel_hi:[1,0]
	v_cvt_pk_bf16_f32 v24, v28, v29
	s_nop 0
	v_cvt_pk_bf16_f32 v25, v30, v31
	v_cvt_pk_bf16_f32 v26, v26, v27
	v_cvt_pk_bf16_f32 v27, v32, v33
	ds_read_b32 v28, v129 offset:576
	v_mad_i64_i32 v[30:31], s[2:3], v137, s66, v[130:131]
	global_store_dwordx4 v[30:31], v[24:27], off sc1
	s_waitcnt lgkmcnt(0)
	v_pk_mul_f32 v[20:21], v[20:21], v[28:29] op_sel_hi:[1,0]
	v_pk_mul_f32 v[24:25], v[18:19], v[28:29] op_sel_hi:[1,0]
	v_pk_mul_f32 v[18:19], v[16:17], v[28:29] op_sel_hi:[1,0]
	v_pk_mul_f32 v[22:23], v[22:23], v[28:29] op_sel_hi:[1,0]
	v_cvt_pk_bf16_f32 v16, v20, v21
	s_nop 0
	v_cvt_pk_bf16_f32 v17, v22, v23
	v_cvt_pk_bf16_f32 v18, v18, v19
	v_cvt_pk_bf16_f32 v19, v24, v25
	ds_read_b32 v20, v129 offset:640
	v_mad_i64_i32 v[22:23], s[2:3], v136, s66, v[130:131]
	global_store_dwordx4 v[22:23], v[16:19], off sc1
	s_waitcnt lgkmcnt(0)
	v_pk_mul_f32 v[12:13], v[12:13], v[20:21] op_sel_hi:[1,0]
	v_pk_mul_f32 v[16:17], v[10:11], v[20:21] op_sel_hi:[1,0]
	v_pk_mul_f32 v[10:11], v[8:9], v[20:21] op_sel_hi:[1,0]
	v_pk_mul_f32 v[14:15], v[14:15], v[20:21] op_sel_hi:[1,0]
	v_cvt_pk_bf16_f32 v8, v12, v13
	s_nop 0
	v_cvt_pk_bf16_f32 v9, v14, v15
	v_cvt_pk_bf16_f32 v10, v10, v11
	v_cvt_pk_bf16_f32 v11, v16, v17
	ds_read_b32 v12, v129 offset:704
	v_mad_i64_i32 v[14:15], s[2:3], v135, s66, v[130:131]
	global_store_dwordx4 v[14:15], v[8:11], off sc1
	s_waitcnt lgkmcnt(0)
	v_pk_mul_f32 v[4:5], v[4:5], v[12:13] op_sel_hi:[1,0]
	v_pk_mul_f32 v[8:9], v[2:3], v[12:13] op_sel_hi:[1,0]
	v_pk_mul_f32 v[2:3], v[0:1], v[12:13] op_sel_hi:[1,0]
	v_cvt_pk_bf16_f32 v0, v4, v5
	v_mad_i64_i32 v[4:5], s[2:3], v134, s66, v[130:131]
	v_pk_mul_f32 v[6:7], v[6:7], v[12:13] op_sel_hi:[1,0]
	s_nop 0
	v_cvt_pk_bf16_f32 v1, v6, v7
	v_cvt_pk_bf16_f32 v2, v2, v3
	v_cvt_pk_bf16_f32 v3, v8, v9
	global_store_dwordx4 v[4:5], v[0:3], off sc1

.LBB0_484:
	s_mov_b64 s[12:13], -1
	s_cmp_gt_i32 s6, -1
	v_lshl_add_u64 v[84:85], s[10:11], 0, v[70:71]
	v_lshl_add_u64 v[82:83], s[10:11], 0, v[72:73]
	v_lshl_add_u64 v[80:81], s[10:11], 0, v[74:75]
	v_lshl_add_u64 v[78:79], s[10:11], 0, v[76:77]
	v_lshlrev_b32_e32 v68, 1, v66
	s_cbranch_scc0 .LBB0_486
	s_waitcnt vmcnt(30)
	ds_write2_b32 v87, v0, v1 offset1:66
	s_waitcnt vmcnt(28)
	ds_write2_b32 v87, v2, v3 offset0:132 offset1:198
	v_add_u32_e32 v0, 0x400, v87
	s_waitcnt vmcnt(26)
	ds_write2_b32 v0, v4, v5 offset0:8 offset1:74
	s_waitcnt vmcnt(24)
	ds_write2_b32 v0, v6, v7 offset0:140 offset1:206
	v_add_u32_e32 v0, 0x800, v87
	s_waitcnt vmcnt(22)
	ds_write2_b32 v0, v8, v9 offset0:16 offset1:82
	s_waitcnt vmcnt(20)
	ds_write2_b32 v0, v10, v11 offset0:148 offset1:214
	v_add_u32_e32 v0, 0xc00, v87
	s_waitcnt vmcnt(18)
	ds_write2_b32 v0, v12, v13 offset0:24 offset1:90
	s_waitcnt vmcnt(16)
	ds_write2_b32 v0, v14, v15 offset0:156 offset1:222
	v_add_u32_e32 v0, 0x1000, v87
	s_waitcnt vmcnt(14)
	ds_write2_b32 v0, v16, v17 offset0:32 offset1:98
	s_waitcnt vmcnt(12)
	ds_write2_b32 v0, v18, v19 offset0:164 offset1:230
	v_add_u32_e32 v0, 0x1400, v87
	s_waitcnt vmcnt(10)
	ds_write2_b32 v0, v20, v21 offset0:40 offset1:106
	s_waitcnt vmcnt(8)
	ds_write2_b32 v0, v22, v23 offset0:172 offset1:238
	v_add_u32_e32 v0, 0x1800, v87
	s_waitcnt vmcnt(6)
	ds_write2_b32 v0, v24, v25 offset0:48 offset1:114
	s_waitcnt vmcnt(4)
	ds_write2_b32 v0, v26, v27 offset0:180 offset1:246
	v_add_u32_e32 v0, 0x1c00, v87
	s_waitcnt vmcnt(2)
	ds_write2_b32 v0, v28, v29 offset0:56 offset1:122
	s_waitcnt vmcnt(0)
	ds_write2_b32 v0, v30, v31 offset0:188 offset1:254
	s_waitcnt lgkmcnt(0)
	ds_read2_b32 v[4:5], v86 offset0:33 offset1:41
	ds_read2_b32 v[6:7], v86 offset1:8
	ds_read2_b32 v[8:9], v86 offset0:66 offset1:74
	ds_read2_b32 v[10:11], v86 offset0:99 offset1:107
	ds_read2_b32 v[12:13], v86 offset0:132 offset1:140
	ds_read2_b32 v[14:15], v86 offset0:165 offset1:173
	ds_read2_b32 v[16:17], v86 offset0:198 offset1:206
	ds_read2_b32 v[18:19], v86 offset0:231 offset1:239
	s_ashr_i32 s3, s2, 31
	s_lshl_b64 s[10:11], s[2:3], 1
	v_lshl_add_u64 v[20:21], v[84:85], 0, s[10:11]
	s_waitcnt lgkmcnt(6)
	v_cvt_pk_f16_f32 v0, v6, v4
	s_waitcnt lgkmcnt(4)
	v_cvt_pk_f16_f32 v1, v8, v10
	s_waitcnt lgkmcnt(2)
	v_cvt_pk_f16_f32 v2, v12, v14
	s_waitcnt lgkmcnt(0)
	v_cvt_pk_f16_f32 v3, v16, v18
	v_lshl_add_u64 v[20:21], v[20:21], 0, v[68:69]
	global_store_dwordx4 v[20:21], v[0:3], off sc1
	s_mov_b64 s[12:13], 0
	s_nop 0
	v_cvt_pk_f16_f32 v0, v7, v5
	v_cvt_pk_f16_f32 v1, v9, v11
	v_cvt_pk_f16_f32 v2, v13, v15
	v_cvt_pk_f16_f32 v3, v17, v19
	ds_read2_b32 v[6:7], v86 offset0:49 offset1:57
	ds_read2_b32 v[8:9], v86 offset0:16 offset1:24
	ds_read2_b32 v[10:11], v86 offset0:82 offset1:90
	ds_read2_b32 v[12:13], v86 offset0:115 offset1:123
	ds_read2_b32 v[14:15], v86 offset0:148 offset1:156
	ds_read2_b32 v[16:17], v86 offset0:181 offset1:189
	ds_read2_b32 v[18:19], v86 offset0:214 offset1:222
	ds_read2_b32 v[20:21], v86 offset0:247 offset1:255
	v_lshl_add_u64 v[4:5], v[82:83], 0, s[10:11]
	v_lshl_add_u64 v[4:5], v[4:5], 0, v[68:69]
	global_store_dwordx4 v[4:5], v[0:3], off sc1
	v_lshl_add_u64 v[4:5], v[80:81], 0, s[10:11]
	v_lshl_add_u64 v[4:5], v[4:5], 0, v[68:69]
	s_waitcnt lgkmcnt(6)
	v_cvt_pk_f16_f32 v0, v8, v6
	s_waitcnt lgkmcnt(4)
	v_cvt_pk_f16_f32 v1, v10, v12
	s_waitcnt lgkmcnt(2)
	v_cvt_pk_f16_f32 v2, v14, v16
	s_waitcnt lgkmcnt(0)
	v_cvt_pk_f16_f32 v3, v18, v20
	global_store_dwordx4 v[4:5], v[0:3], off sc1
	v_lshl_add_u64 v[4:5], v[78:79], 0, s[10:11]
	v_lshl_add_u64 v[4:5], v[4:5], 0, v[68:69]
	v_cvt_pk_f16_f32 v0, v9, v7
	v_cvt_pk_f16_f32 v1, v11, v13
	v_cvt_pk_f16_f32 v2, v15, v17
	v_cvt_pk_f16_f32 v3, v19, v21
	global_store_dwordx4 v[4:5], v[0:3], off sc1
	s_waitcnt lgkmcnt(0)
.LBB0_486:
	s_andn2_b64 vcc, exec, s[12:13]
	s_cbranch_vccnz .LBB0_479
	s_ashr_i32 s3, s2, 31
	s_lshl_b64 s[10:11], s[2:3], 1
	s_mov_b32 s2, s0
	s_mov_b32 s3, s0
	s_waitcnt vmcnt(30)
	v_lshl_add_u64 v[0:1], v[84:85], 0, s[10:11]
	s_mov_b32 s1, s0
	s_waitcnt vmcnt(26)
	v_mov_b64_e32 v[4:5], s[2:3]
	v_lshl_add_u64 v[0:1], v[0:1], 0, v[68:69]
	v_mov_b64_e32 v[2:3], s[0:1]
	global_store_dwordx4 v[0:1], v[2:5], off sc1
	v_lshl_add_u64 v[0:1], v[82:83], 0, s[10:11]
	v_lshl_add_u64 v[0:1], v[0:1], 0, v[68:69]
	global_store_dwordx4 v[0:1], v[2:5], off sc1
	v_lshl_add_u64 v[0:1], v[80:81], 0, s[10:11]
	v_lshl_add_u64 v[0:1], v[0:1], 0, v[68:69]
	global_store_dwordx4 v[0:1], v[2:5], off sc1
	v_lshl_add_u64 v[0:1], v[78:79], 0, s[10:11]
	v_lshl_add_u64 v[0:1], v[0:1], 0, v[68:69]
	global_store_dwordx4 v[0:1], v[2:5], off sc1
	s_branch .LBB0_479

.LBB0_1198:
	ds_read_b128 v[64:67], v132 offset:5376
	ds_read_b128 v[68:71], v132 offset:5392
	v_add_u32_e32 v129, s2, v145
	ds_read_b128 v[96:99], v132 offset:4352
	ds_read_b128 v[100:103], v132 offset:4368
	ds_read_b128 v[88:91], v132 offset:4608
	ds_read_b128 v[92:95], v132 offset:4624
	ds_read_b128 v[80:83], v132 offset:4864
	ds_read_b128 v[84:87], v132 offset:4880
	ds_read_b128 v[72:75], v132 offset:5120
	ds_read_b128 v[76:79], v132 offset:5136
	ds_read_b128 v[104:107], v132 offset:5504
	ds_read_b128 v[108:111], v132 offset:5520
	ds_read_b128 v[112:115], v132 offset:4480
	ds_read_b128 v[150:153], v132 offset:4496
	ds_read_b128 v[154:157], v132 offset:4736
	ds_read_b128 v[158:161], v132 offset:4752
	ds_read_b128 v[162:165], v132 offset:4992
	ds_read_b128 v[166:169], v132 offset:5008
	ds_read_b128 v[170:173], v132 offset:5248
	ds_read_b128 v[174:177], v132 offset:5264
	ds_read_b128 v[178:181], v129
	ds_read_b128 v[184:187], v129 offset:64
	ds_read_b128 v[188:191], v129 offset:144
	ds_read_b128 v[192:195], v129 offset:208
	ds_read_b128 v[196:199], v129 offset:288
	ds_read_b128 v[200:203], v129 offset:352
	ds_read_b128 v[204:207], v129 offset:432
	ds_read_b128 v[208:211], v129 offset:496
	s_waitcnt lgkmcnt(7)
	v_and_b32_e32 v131, 0xffff0000, v178
	v_lshlrev_b32_e32 v130, 16, v178
	s_waitcnt lgkmcnt(5)
	v_and_b32_e32 v213, 0xffff0000, v188
	v_lshlrev_b32_e32 v212, 16, v188
	s_waitcnt lgkmcnt(3)
	v_and_b32_e32 v215, 0xffff0000, v196
	v_lshlrev_b32_e32 v214, 16, v196
	s_waitcnt lgkmcnt(1)
	v_and_b32_e32 v217, 0xffff0000, v204
	v_lshlrev_b32_e32 v216, 16, v204
	v_and_b32_e32 v219, 0xffff0000, v180
	v_lshlrev_b32_e32 v218, 16, v180
	v_and_b32_e32 v227, 0xffff0000, v179
	v_lshlrev_b32_e32 v226, 16, v179
	v_and_b32_e32 v179, 0xffff0000, v189
	v_lshlrev_b32_e32 v178, 16, v189
	v_and_b32_e32 v189, 0xffff0000, v197
	v_lshlrev_b32_e32 v188, 16, v197
	v_and_b32_e32 v197, 0xffff0000, v205
	v_lshlrev_b32_e32 v196, 16, v205
	v_and_b32_e32 v205, 0xffff0000, v181
	v_lshlrev_b32_e32 v204, 16, v181
	v_and_b32_e32 v221, 0xffff0000, v190
	v_lshlrev_b32_e32 v220, 16, v190
	v_and_b32_e32 v181, 0xffff0000, v191
	v_lshlrev_b32_e32 v180, 16, v191
	v_pk_fma_f32 v[64:65], v[96:97], v[130:131], v[64:65]
	v_pk_fma_f32 v[68:69], v[100:101], v[218:219], v[68:69]
	v_pk_fma_f32 v[66:67], v[98:99], v[226:227], v[66:67]
	v_pk_fma_f32 v[70:71], v[102:103], v[204:205], v[70:71]
	v_and_b32_e32 v223, 0xffff0000, v198
	v_lshlrev_b32_e32 v222, 16, v198
	v_and_b32_e32 v191, 0xffff0000, v199
	v_lshlrev_b32_e32 v190, 16, v199
	v_pk_fma_f32 v[64:65], v[88:89], v[212:213], v[64:65]
	v_pk_fma_f32 v[68:69], v[92:93], v[220:221], v[68:69]
	v_pk_fma_f32 v[66:67], v[90:91], v[178:179], v[66:67]
	v_pk_fma_f32 v[70:71], v[94:95], v[180:181], v[70:71]
	v_and_b32_e32 v225, 0xffff0000, v206
	v_lshlrev_b32_e32 v224, 16, v206
	v_and_b32_e32 v199, 0xffff0000, v207
	v_lshlrev_b32_e32 v198, 16, v207
	v_pk_fma_f32 v[64:65], v[80:81], v[214:215], v[64:65]
	v_pk_fma_f32 v[80:81], v[84:85], v[222:223], v[68:69]
	v_pk_fma_f32 v[66:67], v[82:83], v[188:189], v[66:67]
	v_pk_fma_f32 v[82:83], v[86:87], v[190:191], v[70:71]
	v_and_b32_e32 v207, 0xffff0000, v184
	v_lshlrev_b32_e32 v206, 16, v184
	v_and_b32_e32 v229, 0xffff0000, v192
	v_lshlrev_b32_e32 v228, 16, v192
	v_and_b32_e32 v231, 0xffff0000, v200
	v_lshlrev_b32_e32 v230, 16, v200
	s_waitcnt lgkmcnt(0)
	v_and_b32_e32 v233, 0xffff0000, v208
	v_lshlrev_b32_e32 v232, 16, v208
	v_and_b32_e32 v235, 0xffff0000, v186
	v_lshlrev_b32_e32 v234, 16, v186
	v_and_b32_e32 v243, 0xffff0000, v185
	v_lshlrev_b32_e32 v242, 16, v185
	v_and_b32_e32 v185, 0xffff0000, v193
	v_lshlrev_b32_e32 v184, 16, v193
	v_and_b32_e32 v193, 0xffff0000, v201
	v_lshlrev_b32_e32 v192, 16, v201
	v_and_b32_e32 v201, 0xffff0000, v209
	v_lshlrev_b32_e32 v200, 16, v209
	v_and_b32_e32 v209, 0xffff0000, v187
	v_lshlrev_b32_e32 v208, 16, v187
	v_pk_fma_f32 v[68:69], v[72:73], v[216:217], v[64:65]
	v_pk_fma_f32 v[64:65], v[76:77], v[224:225], v[80:81]
	v_pk_fma_f32 v[70:71], v[74:75], v[196:197], v[66:67]
	v_pk_fma_f32 v[66:67], v[78:79], v[198:199], v[82:83]
	v_and_b32_e32 v237, 0xffff0000, v194
	v_lshlrev_b32_e32 v236, 16, v194
	v_and_b32_e32 v187, 0xffff0000, v195
	v_lshlrev_b32_e32 v186, 16, v195
	v_cvt_pk_bf16_f32 v76, v68, v69
	v_cvt_pk_bf16_f32 v77, v70, v71
	v_cvt_pk_bf16_f32 v78, v64, v65
	v_cvt_pk_bf16_f32 v79, v66, v67
	v_pk_fma_f32 v[84:85], v[112:113], v[206:207], v[104:105]
	v_pk_fma_f32 v[86:87], v[150:151], v[234:235], v[108:109]
	v_pk_fma_f32 v[90:91], v[114:115], v[242:243], v[106:107]
	v_pk_fma_f32 v[92:93], v[152:153], v[208:209], v[110:111]
	v_and_b32_e32 v239, 0xffff0000, v202
	v_lshlrev_b32_e32 v238, 16, v202
	v_and_b32_e32 v195, 0xffff0000, v203
	v_lshlrev_b32_e32 v194, 16, v203
	v_pk_fma_f32 v[94:95], v[154:155], v[228:229], v[84:85]
	v_pk_fma_f32 v[96:97], v[158:159], v[236:237], v[86:87]
	v_pk_fma_f32 v[90:91], v[156:157], v[184:185], v[90:91]
	v_pk_fma_f32 v[98:99], v[160:161], v[186:187], v[92:93]
	v_and_b32_e32 v241, 0xffff0000, v210
	v_lshlrev_b32_e32 v240, 16, v210
	v_and_b32_e32 v89, 0xffff0000, v211
	v_lshlrev_b32_e32 v88, 16, v211
	v_pk_fma_f32 v[100:101], v[162:163], v[230:231], v[94:95]
	v_pk_fma_f32 v[102:103], v[166:167], v[238:239], v[96:97]
	v_pk_fma_f32 v[90:91], v[164:165], v[192:193], v[90:91]
	v_pk_fma_f32 v[104:105], v[168:169], v[194:195], v[98:99]
	v_pk_fma_f32 v[108:109], v[170:171], v[232:233], v[100:101]
	v_pk_fma_f32 v[112:113], v[174:175], v[240:241], v[102:103]
	v_pk_fma_f32 v[110:111], v[172:173], v[200:201], v[90:91]
	v_pk_fma_f32 v[114:115], v[176:177], v[88:89], v[104:105]
	v_cvt_pk_bf16_f32 v88, v108, v109
	v_cvt_pk_bf16_f32 v89, v110, v111
	v_cvt_pk_bf16_f32 v90, v112, v113
	v_cvt_pk_bf16_f32 v91, v114, v115
	s_waitcnt vmcnt(13)
	v_mfma_f32_16x16x32_bf16 v[72:75], v[76:79], v[8:11], 0
	v_ashrrev_i32_e32 v127, 31, v126
	v_lshl_add_u64 v[130:131], s[54:55], 0, v[126:127]
	s_addk_i32 s2, 0x900
	s_waitcnt vmcnt(1)
	v_mfma_f32_16x16x32_bf16 v[80:83], v[76:79], v[56:59], 0
	v_add_u32_e32 v126, 16, v126
	s_cmpk_lg_i32 s2, 0x3a00
	v_mfma_f32_16x16x32_bf16 v[150:153], v[88:91], v[12:15], v[72:75]
	s_nop 2
	v_lshlrev_b64 v[72:73], 11, v[130:131]
	v_lshl_add_u64 v[74:75], v[122:123], 0, v[72:73]
	v_mfma_f32_16x16x32_bf16 v[154:157], v[88:91], v[16:19], v[80:83]
	v_lshl_add_u64 v[130:131], v[124:125], 0, v[72:73]
	s_nop 1
	global_load_dwordx4 v[80:83], v[74:75], off
	s_nop 0
	global_load_dwordx4 v[72:75], v[74:75], off offset:64
	ds_write_b128 v147, v[68:71]
	ds_write_b128 v147, v[64:67] offset:16
	ds_write_b128 v147, v[108:111] offset:128
	v_mfma_f32_16x16x32_bf16 v[178:181], v[76:79], v[0:3], 0
	v_add_f32_e32 v127, v135, v154
	v_add_f32_e32 v129, v135, v155
	v_add_f32_e32 v149, v135, v156
	v_mfma_f32_16x16x32_bf16 v[92:95], v[76:79], v[24:27], 0
	v_mul_f32_e32 v127, 0xbfb8aa3b, v127
	v_mul_f32_e32 v129, 0xbfb8aa3b, v129
	v_mul_f32_e32 v149, 0xbfb8aa3b, v149
	v_mfma_f32_16x16x32_bf16 v[96:99], v[76:79], v[32:35], 0
	v_exp_f32_e32 v127, v127
	v_exp_f32_e32 v129, v129
	v_exp_f32_e32 v149, v149
	v_mfma_f32_16x16x32_bf16 v[100:103], v[76:79], v[44:47], 0
	ds_write_b128 v147, v[112:115] offset:144
	ds_read2_b32 v[66:67], v148 offset1:16
	ds_read2_b32 v[108:109], v148 offset0:68 offset1:84
	ds_read2_b32 v[110:111], v148 offset0:136 offset1:152
	ds_read2_b32 v[112:113], v148 offset0:204 offset1:220
	ds_read2_b32 v[64:65], v148 offset0:32 offset1:48
	v_mfma_f32_16x16x32_bf16 v[84:87], v[76:79], v[20:23], 0
	v_add_f32_e32 v127, 1.0, v127
	v_add_f32_e32 v129, 1.0, v129
	v_add_f32_e32 v149, 1.0, v149
	v_mfma_f32_16x16x32_bf16 v[104:107], v[76:79], v[52:55], 0
	v_rcp_f32_e32 v149, v149
	v_mfma_f32_16x16x32_bf16 v[76:79], v[88:91], v[4:7], v[178:181]
	v_mfma_f32_16x16x32_bf16 v[68:71], v[88:91], v[28:31], v[92:95]
	v_mfma_f32_16x16x32_bf16 v[92:95], v[88:91], v[36:39], v[96:99]
	s_nop 5
	v_add_f32_e32 v76, v133, v76
	v_mul_f32_e32 v76, 0xbfb8aa3b, v76
	v_add_f32_e32 v68, v137, v68
	v_mfma_f32_16x16x32_bf16 v[96:99], v[88:91], v[48:51], v[100:103]
	v_add_f32_e32 v70, v137, v70
	v_add_f32_e32 v71, v137, v71
	v_add_f32_e32 v92, v138, v92
	v_mfma_f32_16x16x32_bf16 v[84:87], v[88:91], v[40:43], v[84:87]
	v_add_f32_e32 v95, v138, v95
	s_nop 2
	v_add_f32_e32 v98, v139, v98
	v_add_f32_e32 v96, v139, v96
	s_waitcnt vmcnt(2)
	v_mfma_f32_16x16x32_bf16 v[88:91], v[88:91], v[60:63], v[104:107]
	v_mul_f32_e32 v98, 0xbfb8aa3b, v98
	v_exp_f32_e32 v76, v76
	v_add_f32_e32 v77, v133, v77
	v_add_f32_e32 v104, v134, v150
	v_add_f32_e32 v105, v134, v151
	v_add_f32_e32 v106, v134, v152
	v_add_f32_e32 v107, v134, v153
	v_add_f32_e32 v69, v137, v69
	v_add_f32_e32 v93, v138, v93
	v_add_f32_e32 v97, v139, v97
	v_add_f32_e32 v99, v139, v99
	v_add_f32_e32 v84, v136, v84
	v_mul_f32_e32 v68, 0xbfb8aa3b, v68
	v_mul_f32_e32 v70, 0xbfb8aa3b, v70
	v_mul_f32_e32 v71, 0xbfb8aa3b, v71
	v_mul_f32_e32 v104, 0xbfb8aa3b, v104
	v_mul_f32_e32 v92, 0xbfb8aa3b, v92
	v_mul_f32_e32 v105, 0xbfb8aa3b, v105
	v_mul_f32_e32 v106, 0xbfb8aa3b, v106
	v_mul_f32_e32 v107, 0xbfb8aa3b, v107
	v_mul_f32_e32 v95, 0xbfb8aa3b, v95
	v_mul_f32_e32 v96, 0xbfb8aa3b, v96
	v_exp_f32_e32 v98, v98
	v_add_f32_e32 v78, v133, v78
	v_add_f32_e32 v94, v138, v94
	v_add_f32_e32 v150, v135, v157
	v_add_f32_e32 v85, v136, v85
	v_add_f32_e32 v89, v140, v89
	v_add_f32_e32 v90, v140, v90
	v_mul_f32_e32 v77, 0xbfb8aa3b, v77
	v_mul_f32_e32 v69, 0xbfb8aa3b, v69
	v_mul_f32_e32 v93, 0xbfb8aa3b, v93
	v_mul_f32_e32 v97, 0xbfb8aa3b, v97
	v_mul_f32_e32 v99, 0xbfb8aa3b, v99
	v_mul_f32_e32 v84, 0xbfb8aa3b, v84
	v_exp_f32_e32 v68, v68
	v_exp_f32_e32 v70, v70
	v_exp_f32_e32 v71, v71
	v_exp_f32_e32 v104, v104
	v_exp_f32_e32 v92, v92
	v_exp_f32_e32 v105, v105
	v_exp_f32_e32 v106, v106
	v_exp_f32_e32 v107, v107
	v_exp_f32_e32 v95, v95
	v_exp_f32_e32 v96, v96
	v_add_f32_e32 v88, v140, v88
	v_add_f32_e32 v86, v136, v86
	v_mul_f32_e32 v78, 0xbfb8aa3b, v78
	v_mul_f32_e32 v94, 0xbfb8aa3b, v94
	v_mul_f32_e32 v150, 0xbfb8aa3b, v150
	v_mul_f32_e32 v85, 0xbfb8aa3b, v85
	v_mul_f32_e32 v89, 0xbfb8aa3b, v89
	v_mul_f32_e32 v90, 0xbfb8aa3b, v90
	v_exp_f32_e32 v77, v77
	v_exp_f32_e32 v69, v69
	v_exp_f32_e32 v93, v93
	v_exp_f32_e32 v97, v97
	v_exp_f32_e32 v99, v99
	v_exp_f32_e32 v84, v84
	v_add_f32_e32 v79, v133, v79
	v_add_f32_e32 v87, v136, v87
	v_mul_f32_e32 v88, 0xbfb8aa3b, v88
	v_mul_f32_e32 v86, 0xbfb8aa3b, v86
	v_exp_f32_e32 v78, v78
	v_exp_f32_e32 v94, v94
	v_exp_f32_e32 v150, v150
	v_exp_f32_e32 v85, v85
	v_exp_f32_e32 v89, v89
	v_exp_f32_e32 v90, v90
	v_add_f32_e32 v76, 1.0, v76
	v_mul_f32_e32 v79, 0xbfb8aa3b, v79
	v_mul_f32_e32 v87, 0xbfb8aa3b, v87
	v_exp_f32_e32 v88, v88
	v_exp_f32_e32 v86, v86
	v_add_f32_e32 v98, 1.0, v98
	v_rcp_f32_e32 v76, v76
	ds_read2_b32 v[100:101], v148 offset0:100 offset1:116
	ds_read2_b32 v[102:103], v148 offset0:168 offset1:184
	ds_read2_b32 v[114:115], v148 offset0:236 offset1:252
	v_exp_f32_e32 v79, v79
	v_exp_f32_e32 v87, v87
	v_add_f32_e32 v68, 1.0, v68
	v_add_f32_e32 v70, 1.0, v70
	v_add_f32_e32 v71, 1.0, v71
	v_add_f32_e32 v104, 1.0, v104
	v_add_f32_e32 v92, 1.0, v92
	v_add_f32_e32 v105, 1.0, v105
	v_add_f32_e32 v106, 1.0, v106
	v_add_f32_e32 v107, 1.0, v107
	v_add_f32_e32 v95, 1.0, v95
	v_add_f32_e32 v96, 1.0, v96
	v_rcp_f32_e32 v98, v98
	v_add_f32_e32 v77, 1.0, v77
	v_add_f32_e32 v69, 1.0, v69
	v_add_f32_e32 v93, 1.0, v93
	v_add_f32_e32 v97, 1.0, v97
	v_add_f32_e32 v99, 1.0, v99
	v_add_f32_e32 v84, 1.0, v84
	v_rcp_f32_e32 v68, v68
	v_rcp_f32_e32 v70, v70
	v_rcp_f32_e32 v71, v71
	v_rcp_f32_e32 v104, v104
	v_rcp_f32_e32 v171, v92
	v_rcp_f32_e32 v92, v105
	v_rcp_f32_e32 v105, v106
	v_rcp_f32_e32 v106, v107
	v_rcp_f32_e32 v95, v95
	v_rcp_f32_e32 v107, v127
	v_rcp_f32_e32 v127, v96
	v_rcp_f32_e32 v96, v129
	v_add_f32_e32 v91, v140, v91
	v_add_f32_e32 v78, 1.0, v78
	v_add_f32_e32 v94, 1.0, v94
	v_add_f32_e32 v150, 1.0, v150
	v_add_f32_e32 v85, 1.0, v85
	v_add_f32_e32 v89, 1.0, v89
	v_add_f32_e32 v90, 1.0, v90
	v_rcp_f32_e32 v77, v77
	v_rcp_f32_e32 v69, v69
	v_rcp_f32_e32 v93, v93
	v_rcp_f32_e32 v97, v97
	v_rcp_f32_e32 v99, v99
	v_rcp_f32_e32 v151, v84
	v_mul_f32_e32 v91, 0xbfb8aa3b, v91
	v_add_f32_e32 v88, 1.0, v88
	v_add_f32_e32 v86, 1.0, v86
	v_rcp_f32_e32 v78, v78
	v_rcp_f32_e32 v94, v94
	v_rcp_f32_e32 v150, v150
	v_rcp_f32_e32 v85, v85
	v_rcp_f32_e32 v89, v89
	v_rcp_f32_e32 v153, v90
	v_mul_f32_e32 v154, v141, v76
	v_exp_f32_e32 v91, v91
	v_add_f32_e32 v79, 1.0, v79
	v_add_f32_e32 v87, 1.0, v87
	v_rcp_f32_e32 v175, v88
	v_rcp_f32_e32 v152, v86
	s_waitcnt lgkmcnt(1)
	v_mul_f32_e32 v88, v98, v102
	v_exp_f32_e32 v98, v154
	v_rcp_f32_e32 v79, v79
	v_rcp_f32_e32 v87, v87
	v_mul_f32_e32 v129, v68, v66
	v_mul_f32_e32 v68, v70, v110
	v_mul_f32_e32 v70, v71, v112
	v_mul_f32_e32 v71, v142, v104
	v_mul_f32_e32 v104, v142, v92
	v_mul_f32_e32 v84, v95, v113
	v_mul_f32_e32 v95, v143, v107
	v_mul_f32_e32 v107, v143, v96
	v_mul_f32_e32 v77, v141, v77
	v_mul_f32_e32 v66, v69, v108
	v_mul_f32_e32 v76, v93, v109
	v_mul_f32_e32 v93, v142, v105
	v_mul_f32_e32 v108, v142, v106
	v_mul_f32_e32 v86, v97, v100
	v_mul_f32_e32 v97, v143, v149
	s_waitcnt lgkmcnt(0)
	v_mul_f32_e32 v90, v99, v114
	v_mul_f32_e32 v99, v144, v151
	v_exp_f32_e32 v106, v71
	v_exp_f32_e32 v109, v104
	v_exp_f32_e32 v114, v95
	v_exp_f32_e32 v151, v107
	v_mul_f32_e32 v69, v141, v78
	v_mul_f32_e32 v78, v94, v111
	v_mul_f32_e32 v100, v143, v150
	v_mul_f32_e32 v85, v144, v85
	v_mul_f32_e32 v92, v89, v101
	v_mul_f32_e32 v94, v153, v103
	v_exp_f32_e32 v101, v77
	v_exp_f32_e32 v111, v93
	v_exp_f32_e32 v153, v97
	v_add_f32_e32 v91, 1.0, v91
	v_mul_f32_e32 v89, v144, v152
	v_exp_f32_e32 v103, v69
	v_exp_f32_e32 v113, v108
	v_exp_f32_e32 v155, v100
	v_exp_f32_e32 v156, v99
	v_exp_f32_e32 v159, v85
	v_fma_f32 v69, -v98, v98, 1.0
	v_rcp_f32_e32 v91, v91
	v_mul_f32_e32 v79, v141, v79
	v_mul_f32_e32 v87, v144, v87
	v_exp_f32_e32 v161, v89
	v_sqrt_f32_e32 v99, v69
	v_exp_f32_e32 v105, v79
	v_exp_f32_e32 v163, v87
	v_fma_f32 v85, -v106, v106, 1.0
	v_mul_f32_e32 v177, v106, v109
	v_mul_f32_e32 v178, v114, v151
	v_fma_f32 v71, -v101, v101, 1.0
	v_sqrt_f32_e32 v107, v85
	v_mul_f32_e32 v181, v111, v177
	v_mul_f32_e32 v183, v153, v178
	v_mul_f32_e32 v149, v98, v101
	v_fma_f32 v77, -v103, v103, 1.0
	v_fma_f32 v93, -v114, v114, 1.0
	v_mul_f32_e32 v179, v156, v159
	v_sqrt_f32_e32 v100, v71
	v_mul_f32_e32 v186, v113, v181
	v_mul_f32_e32 v187, v155, v183
	v_mul_f32_e32 v96, v91, v115
	v_fma_f32 v87, -v109, v109, 1.0
	v_sqrt_f32_e32 v102, v77
	v_mul_f32_e32 v180, v103, v149
	v_sqrt_f32_e32 v115, v93
	v_mul_f32_e32 v184, v161, v179
	v_mov_b32_e32 v71, v186
	v_mov_b32_e32 v189, v186
	v_mov_b32_e32 v77, v187
	v_mov_b32_e32 v190, v187
	v_mul_f32_e32 v164, v99, v129
	v_fma_f32 v79, -v105, v105, 1.0
	v_fma_f32 v97, -v153, v153, 1.0
	v_fma_f32 v157, -v156, v156, 1.0
	v_sqrt_f32_e32 v108, v87
	v_mul_f32_e32 v185, v105, v180
	v_mul_f32_e32 v188, v163, v184
	v_permlane16_swap_b32_e32 v71, v189
	v_permlane16_swap_b32_e32 v77, v190
	v_pk_fma_f32 v[164:165], v[98:99], v[128:129], v[164:165] op_sel_hi:[1,1,0]
	v_mul_f32_e32 v129, v171, v67
	v_fma_f32 v89, -v111, v111, 1.0
	v_fma_f32 v95, -v151, v151, 1.0
	v_sqrt_f32_e32 v104, v79
	v_sqrt_f32_e32 v152, v97
	v_sqrt_f32_e32 v157, v157
	v_mov_b32_e32 v69, v185
	v_mov_b32_e32 v97, v185
	v_mov_b32_e32 v79, v188
	v_mov_b32_e32 v191, v188
	v_mul_f32_e32 v167, v71, v189
	v_mul_f32_e32 v168, v77, v190
	v_mov_b32_e32 v67, v164
	v_mul_f32_e32 v174, v101, v164
	v_mul_f32_e32 v176, v107, v129
	v_sqrt_f32_e32 v110, v89
	v_sqrt_f32_e32 v150, v95
	v_permlane16_swap_b32_e32 v69, v97
	v_permlane16_swap_b32_e32 v79, v191
	v_mov_b32_e32 v171, v167
	v_mov_b32_e32 v172, v168
	v_pk_fma_f32 v[66:67], v[100:101], v[66:67], v[174:175] op_sel_hi:[1,1,0]
	v_pk_fma_f32 v[100:101], v[106:107], v[128:129], v[176:177] op_sel_hi:[1,1,0]
	v_mul_f32_e32 v129, v127, v64
	v_fma_f32 v91, -v113, v113, 1.0
	v_fma_f32 v158, -v159, v159, 1.0
	v_mul_f32_e32 v166, v69, v97
	v_cndmask_b32_e64 v192, v69, 1.0, vcc
	v_cndmask_b32_e64 v194, v77, 1.0, vcc
	v_mul_f32_e32 v169, v79, v191
	v_permlane32_swap_b32_e32 v167, v171
	v_permlane32_swap_b32_e32 v168, v172
	v_mov_b32_e32 v69, v66
	v_mul_f32_e32 v64, v103, v66
	v_mov_b32_e32 v77, v100
	v_mul_f32_e32 v174, v109, v100
	v_mul_f32_e32 v176, v115, v129
	v_sqrt_f32_e32 v112, v91
	v_sqrt_f32_e32 v158, v158
	v_cndmask_b32_e64 v193, v71, 1.0, vcc
	v_cndmask_b32_e64 v195, v79, 1.0, vcc
	v_mov_b32_e32 v173, v169
	v_cndmask_b32_e64 v71, v167, 1.0, s[0:1]
	v_cndmask_b32_e64 v79, v168, 1.0, s[0:1]
	v_pk_fma_f32 v[68:69], v[102:103], v[68:69], v[64:65] op_sel_hi:[1,1,0]
	v_pk_fma_f32 v[76:77], v[108:109], v[76:77], v[174:175] op_sel_hi:[1,1,0]
	v_pk_fma_f32 v[102:103], v[114:115], v[128:129], v[176:177] op_sel_hi:[1,1,0]
	v_mul_f32_e32 v129, v175, v65
	v_fma_f32 v160, -v161, v161, 1.0
	v_permlane32_swap_b32_e32 v169, v173
	v_mul_f32_e32 v99, v193, v71
	v_mul_f32_e32 v101, v194, v79
	v_mov_b32_e32 v71, v68
	v_mov_b32_e32 v79, v76
	v_mul_f32_e32 v64, v111, v76
	v_mov_b32_e32 v87, v102
	v_mul_f32_e32 v108, v151, v102
	v_mul_f32_e32 v174, v157, v129
	v_fma_f32 v154, -v155, v155, 1.0
	v_sqrt_f32_e32 v160, v160
	v_cndmask_b32_e64 v85, v169, 1.0, s[0:1]
	v_pk_mul_f32 v[70:71], v[104:105], v[70:71]
	v_pk_fma_f32 v[64:65], v[110:111], v[78:79], v[64:65] op_sel_hi:[1,1,0]
	v_pk_fma_f32 v[78:79], v[150:151], v[86:87], v[108:109] op_sel_hi:[1,1,0]
	v_pk_fma_f32 v[86:87], v[156:157], v[128:129], v[174:175] op_sel_hi:[1,1,0]
	v_fma_f32 v162, -v163, v163, 1.0
	v_sqrt_f32_e32 v154, v154
	v_mul_f32_e32 v107, v195, v85
	v_add_f32_e32 v65, v70, v71
	v_mov_b32_e32 v85, v64
	v_mov_b32_e32 v89, v78
	v_mul_f32_e32 v70, v153, v78
	v_mov_b32_e32 v93, v86
	v_mul_f32_e32 v104, v159, v86
	v_sqrt_f32_e32 v162, v162
	v_mov_b32_e32 v69, v65
	v_mov_b32_e32 v108, v65
	v_pk_mul_f32 v[84:85], v[112:113], v[84:85]
	v_pk_fma_f32 v[70:71], v[152:153], v[88:89], v[70:71] op_sel_hi:[1,1,0]
	v_pk_fma_f32 v[88:89], v[158:159], v[92:93], v[104:105] op_sel_hi:[1,1,0]
	v_permlane16_swap_b32_e32 v69, v108
	v_add_f32_e32 v71, v84, v85
	v_mov_b32_e32 v95, v88
	v_mul_f32_e32 v84, v161, v88
	v_mov_b32_e32 v91, v70
	v_fmac_f32_e32 v108, v97, v69
	v_pk_fma_f32 v[84:85], v[160:161], v[94:95], v[84:85] op_sel_hi:[1,1,0]
	v_pk_mul_f32 v[90:91], v[154:155], v[90:91]
	v_mov_b32_e32 v92, v108
	v_mov_b32_e32 v97, v84
	v_add_f32_e32 v79, v90, v91
	v_permlane32_swap_b32_e32 v108, v92
	v_pk_mul_f32 v[94:95], v[162:163], v[96:97]
	v_mov_b32_e32 v170, v166
	v_cndmask_b32_e64 v69, v69, 0, vcc
	v_mov_b32_e32 v77, v71
	v_mov_b32_e32 v109, v71
	v_mov_b32_e32 v85, v79
	v_mov_b32_e32 v90, v79
	v_cndmask_b32_e64 v87, v108, 0, s[0:1]
	v_add_f32_e32 v89, v94, v95
	v_permlane32_swap_b32_e32 v166, v170
	v_permlane16_swap_b32_e32 v77, v109
	v_permlane16_swap_b32_e32 v85, v90
	v_fmac_f32_e32 v69, v192, v87
	v_mov_b32_e32 v87, v89
	v_mov_b32_e32 v91, v89
	v_cndmask_b32_e64 v67, v166, 1.0, s[0:1]
	v_fmac_f32_e32 v109, v189, v77
	v_fmac_f32_e32 v90, v190, v85
	v_permlane16_swap_b32_e32 v87, v91
	v_mul_f32_e32 v67, v192, v67
	v_mov_b32_e32 v93, v109
	v_mov_b32_e32 v94, v90
	v_fmac_f32_e32 v91, v191, v87
	v_permlane32_swap_b32_e32 v109, v93
	v_fmac_f32_e32 v69, v120, v67
	v_permlane32_swap_b32_e32 v90, v94
	v_mov_b32_e32 v95, v91
	v_cndmask_b32_e64 v77, v77, 0, vcc
	v_cndmask_b32_e64 v85, v85, 0, vcc
	v_cndmask_b32_e64 v67, v109, 0, s[0:1]
	v_fmac_f32_e32 v164, v98, v69
	v_fmac_f32_e32 v66, v149, v69
	v_fmac_f32_e32 v68, v180, v69
	v_fmac_f32_e32 v65, v185, v69
	v_cndmask_b32_e64 v69, v90, 0, s[0:1]
	v_permlane32_swap_b32_e32 v91, v95
	v_fmac_f32_e32 v77, v193, v67
	v_cndmask_b32_e64 v67, v87, 0, vcc
	v_fmac_f32_e32 v85, v194, v69
	v_cndmask_b32_e64 v69, v91, 0, s[0:1]
	v_fmac_f32_e32 v67, v195, v69
	v_fmac_f32_e32 v77, v121, v99
	v_fmac_f32_e32 v85, v118, v101
	v_fmac_f32_e32 v67, v119, v107
	v_fmac_f32_e32 v100, v106, v77
	v_fmac_f32_e32 v64, v181, v77
	v_fmac_f32_e32 v102, v114, v85
	v_fmac_f32_e32 v86, v156, v67
	v_pk_mul_f32 v[168:169], v[172:173], v[168:169]
	v_fmac_f32_e32 v76, v177, v77
	v_fmac_f32_e32 v71, v186, v77
	ds_write2_b32 v148, v164, v100 offset1:16
	ds_write2_b32 v148, v66, v76 offset0:68 offset1:84
	ds_write2_b32 v148, v68, v64 offset0:136 offset1:152
	ds_write2_b32 v148, v65, v71 offset0:204 offset1:220
	v_pk_fma_f32 v[64:65], v[172:173], v[90:91], v[94:95]
	v_fmac_f32_e32 v78, v178, v85
	v_fmac_f32_e32 v70, v183, v85
	v_fmac_f32_e32 v79, v187, v85
	v_fmac_f32_e32 v88, v179, v67
	v_fmac_f32_e32 v84, v184, v67
	v_fmac_f32_e32 v89, v188, v67
	ds_write2_b32 v148, v102, v86 offset0:32 offset1:48
	ds_write2_b32 v148, v78, v88 offset0:100 offset1:116
	ds_write2_b32 v148, v70, v84 offset0:168 offset1:184
	ds_write2_b32 v148, v79, v89 offset0:236 offset1:252
	v_pk_fma_f32 v[118:119], v[118:119], v[168:169], v[64:65]
	ds_read_b128 v[64:67], v147
	ds_read_b128 v[68:71], v147 offset:16
	ds_read_b128 v[76:79], v147 offset:128
	ds_read_b128 v[84:87], v147 offset:144
	v_pk_mul_f32 v[166:167], v[170:171], v[166:167]
	v_pk_fma_f32 v[92:93], v[170:171], v[108:109], v[92:93]
	s_waitcnt vmcnt(1)
	v_lshlrev_b32_e32 v88, 16, v80
	v_and_b32_e32 v89, 0xffff0000, v80
	v_lshlrev_b32_e32 v80, 16, v81
	v_and_b32_e32 v81, 0xffff0000, v81
	v_lshlrev_b32_e32 v90, 16, v82
	v_and_b32_e32 v91, 0xffff0000, v82
	v_lshlrev_b32_e32 v82, 16, v83
	v_and_b32_e32 v83, 0xffff0000, v83
	v_pk_fma_f32 v[120:121], v[120:121], v[166:167], v[92:93]
	s_waitcnt vmcnt(0)
	v_lshlrev_b32_e32 v92, 16, v72
	v_and_b32_e32 v93, 0xffff0000, v72
	v_lshlrev_b32_e32 v72, 16, v73
	v_and_b32_e32 v73, 0xffff0000, v73
	v_lshlrev_b32_e32 v94, 16, v74
	v_and_b32_e32 v95, 0xffff0000, v74
	v_lshlrev_b32_e32 v74, 16, v75
	v_and_b32_e32 v75, 0xffff0000, v75
	s_waitcnt lgkmcnt(3)
	v_pk_mul_f32 v[64:65], v[64:65], v[88:89]
	v_pk_mul_f32 v[66:67], v[66:67], v[80:81]
	s_waitcnt lgkmcnt(2)
	v_pk_mul_f32 v[68:69], v[68:69], v[90:91]
	v_pk_mul_f32 v[70:71], v[70:71], v[82:83]
	s_waitcnt lgkmcnt(1)
	v_pk_mul_f32 v[76:77], v[76:77], v[92:93]
	v_pk_mul_f32 v[72:73], v[78:79], v[72:73]
	s_waitcnt lgkmcnt(0)
	v_pk_mul_f32 v[78:79], v[84:85], v[94:95]
	v_pk_mul_f32 v[74:75], v[86:87], v[74:75]
	v_cvt_pk_bf16_f32 v64, v64, v65
	v_cvt_pk_bf16_f32 v65, v66, v67
	v_cvt_pk_bf16_f32 v66, v68, v69
	v_cvt_pk_bf16_f32 v67, v70, v71
	v_cvt_pk_bf16_f32 v68, v76, v77
	v_cvt_pk_bf16_f32 v69, v72, v73
	v_cvt_pk_bf16_f32 v70, v78, v79
	v_cvt_pk_bf16_f32 v71, v74, v75
	global_store_dwordx4 v[130:131], v[64:67], off sc1
	global_store_dwordx4 v[130:131], v[68:71], off offset:64 sc1
	s_cbranch_scc1 .LBB0_1198
	s_lshl_b32 s0, s94, 2
	s_add_i32 s16, s0, s66
	s_cmpk_gt_i32 s16, 0x1ff
	s_cbranch_scc1 .LBB0_1222
	v_readlane_b32 s0, v246, 19
	v_readlane_b32 s2, v246, 21
	v_readlane_b32 s1, v246, 20
	v_readlane_b32 s3, v246, 22
	s_add_u32 s0, s2, 0x400000
	s_addc_u32 s1, s3, 0
	s_ashr_i32 s2, s16, 31
	s_lshr_b32 s2, s2, 27
	s_add_i32 s2, s16, s2
	s_and_b32 s3, s2, 0xffffffe0
	v_readlane_b32 s4, v246, 23
	s_sub_i32 s3, s16, s3
	s_lshl_b32 s2, s2, 1
	s_lshl_b32 s4, s3, 5
	s_andn2_b32 s2, s2, 63
	s_cmp_gt_i32 s3, -1
	v_ashrrev_i32_e32 v67, 5, v182
	v_and_b32_e32 v32, 31, v182
	v_readlane_b32 s5, v246, 24
	v_readlane_b32 s6, v246, 25
	v_readlane_b32 s7, v246, 26
	s_cbranch_scc0 .LBB0_1210
	s_mov_b32 s5, 0
	s_lshl_b64 s[6:7], s[4:5], 2
	v_add_u32_e32 v24, s2, v67
	v_and_b32_e32 v34, 31, v182
	v_mov_b32_e32 v35, 0
	s_add_u32 s6, s0, s6
	s_addc_u32 s7, s1, s7
	v_lshlrev_b32_e32 v0, 2, v34
	v_mov_b32_e32 v1, v35
	v_ashrrev_i32_e32 v25, 31, v24
	v_lshl_add_u64 v[26:27], s[6:7], 0, v[0:1]
	v_lshlrev_b64 v[0:1], 12, v[24:25]
	v_lshl_add_u64 v[8:9], v[26:27], 0, v[0:1]
	v_add_u32_e32 v0, 2, v24
	v_ashrrev_i32_e32 v1, 31, v0
	v_lshlrev_b64 v[0:1], 12, v[0:1]
	v_lshl_add_u64 v[10:11], v[26:27], 0, v[0:1]
	v_add_u32_e32 v0, 4, v24
	v_ashrrev_i32_e32 v1, 31, v0
	v_lshlrev_b64 v[0:1], 12, v[0:1]
	v_lshl_add_u64 v[12:13], v[26:27], 0, v[0:1]
	v_add_u32_e32 v0, 6, v24
	v_ashrrev_i32_e32 v1, 31, v0
	v_lshlrev_b64 v[0:1], 12, v[0:1]
	v_lshl_add_u64 v[14:15], v[26:27], 0, v[0:1]
	v_add_u32_e32 v0, 8, v24
	v_ashrrev_i32_e32 v1, 31, v0
	v_lshlrev_b64 v[0:1], 12, v[0:1]
	v_lshl_add_u64 v[16:17], v[26:27], 0, v[0:1]
	v_add_u32_e32 v0, 10, v24
	v_ashrrev_i32_e32 v1, 31, v0
	v_lshlrev_b64 v[0:1], 12, v[0:1]
	v_lshl_add_u64 v[18:19], v[26:27], 0, v[0:1]
	v_add_u32_e32 v0, 12, v24
	v_ashrrev_i32_e32 v1, 31, v0
	v_lshlrev_b64 v[0:1], 12, v[0:1]
	v_lshl_add_u64 v[20:21], v[26:27], 0, v[0:1]
	v_add_u32_e32 v0, 14, v24
	v_ashrrev_i32_e32 v1, 31, v0
	v_lshlrev_b64 v[0:1], 12, v[0:1]
	v_lshl_add_u64 v[22:23], v[26:27], 0, v[0:1]
	global_load_dword v0, v[8:9], off
	global_load_dword v1, v[10:11], off
	global_load_dword v2, v[12:13], off
	global_load_dword v3, v[14:15], off
	global_load_dword v4, v[16:17], off
	global_load_dword v5, v[18:19], off
	global_load_dword v6, v[20:21], off
	global_load_dword v7, v[22:23], off
	v_add_u32_e32 v8, 16, v24
	v_ashrrev_i32_e32 v9, 31, v8
	v_lshlrev_b64 v[8:9], 12, v[8:9]
	v_lshl_add_u64 v[16:17], v[26:27], 0, v[8:9]
	v_add_u32_e32 v8, 18, v24
	v_ashrrev_i32_e32 v9, 31, v8
	v_lshlrev_b64 v[8:9], 12, v[8:9]
	v_lshl_add_u64 v[18:19], v[26:27], 0, v[8:9]
	v_add_u32_e32 v8, 20, v24
	v_ashrrev_i32_e32 v9, 31, v8
	v_lshlrev_b64 v[8:9], 12, v[8:9]
	v_lshl_add_u64 v[20:21], v[26:27], 0, v[8:9]
	v_add_u32_e32 v8, 22, v24
	v_ashrrev_i32_e32 v9, 31, v8
	v_lshlrev_b64 v[8:9], 12, v[8:9]
	v_lshl_add_u64 v[22:23], v[26:27], 0, v[8:9]
	v_add_u32_e32 v8, 24, v24
	v_ashrrev_i32_e32 v9, 31, v8
	v_lshlrev_b64 v[8:9], 12, v[8:9]
	v_lshl_add_u64 v[28:29], v[26:27], 0, v[8:9]
	v_add_u32_e32 v8, 26, v24
	v_ashrrev_i32_e32 v9, 31, v8
	v_lshlrev_b64 v[8:9], 12, v[8:9]
	v_lshl_add_u64 v[30:31], v[26:27], 0, v[8:9]
	v_add_u32_e32 v8, 28, v24
	v_ashrrev_i32_e32 v9, 31, v8
	v_lshlrev_b64 v[8:9], 12, v[8:9]
	v_lshl_add_u64 v[36:37], v[26:27], 0, v[8:9]
	v_add_u32_e32 v8, 30, v24
	v_ashrrev_i32_e32 v9, 31, v8
	v_lshlrev_b64 v[8:9], 12, v[8:9]
	v_lshl_add_u64 v[38:39], v[26:27], 0, v[8:9]
	global_load_dword v8, v[16:17], off
	global_load_dword v9, v[18:19], off
	global_load_dword v10, v[20:21], off
	global_load_dword v11, v[22:23], off
	global_load_dword v12, v[28:29], off
	global_load_dword v13, v[30:31], off
	global_load_dword v14, v[36:37], off
	global_load_dword v15, v[38:39], off
	v_add_u32_e32 v16, 32, v24
	v_ashrrev_i32_e32 v17, 31, v16
	v_lshlrev_b64 v[16:17], 12, v[16:17]
	v_lshl_add_u64 v[28:29], v[26:27], 0, v[16:17]
	v_add_u32_e32 v16, 34, v24
	v_ashrrev_i32_e32 v17, 31, v16
	v_lshlrev_b64 v[16:17], 12, v[16:17]
	v_lshl_add_u64 v[30:31], v[26:27], 0, v[16:17]
	v_add_u32_e32 v16, 36, v24
	v_ashrrev_i32_e32 v17, 31, v16
	v_lshlrev_b64 v[16:17], 12, v[16:17]
	v_lshl_add_u64 v[36:37], v[26:27], 0, v[16:17]
	v_add_u32_e32 v16, 38, v24
	v_ashrrev_i32_e32 v17, 31, v16
	v_lshlrev_b64 v[16:17], 12, v[16:17]
	v_lshl_add_u64 v[38:39], v[26:27], 0, v[16:17]
	v_add_u32_e32 v16, 40, v24
	v_ashrrev_i32_e32 v17, 31, v16
	v_lshlrev_b64 v[16:17], 12, v[16:17]
	v_lshl_add_u64 v[40:41], v[26:27], 0, v[16:17]
	v_add_u32_e32 v16, 42, v24
	v_ashrrev_i32_e32 v17, 31, v16
	v_lshlrev_b64 v[16:17], 12, v[16:17]
	v_lshl_add_u64 v[42:43], v[26:27], 0, v[16:17]
	v_add_u32_e32 v16, 44, v24
	v_ashrrev_i32_e32 v17, 31, v16
	v_lshlrev_b64 v[16:17], 12, v[16:17]
	v_lshl_add_u64 v[44:45], v[26:27], 0, v[16:17]
	v_add_u32_e32 v16, 46, v24
	v_ashrrev_i32_e32 v17, 31, v16
	v_lshlrev_b64 v[16:17], 12, v[16:17]
	v_lshl_add_u64 v[46:47], v[26:27], 0, v[16:17]
	global_load_dword v16, v[28:29], off
	global_load_dword v17, v[30:31], off
	global_load_dword v18, v[36:37], off
	global_load_dword v19, v[38:39], off
	global_load_dword v20, v[40:41], off
	global_load_dword v21, v[42:43], off
	global_load_dword v22, v[44:45], off
	global_load_dword v23, v[46:47], off
	v_add_u32_e32 v28, 48, v24
	v_ashrrev_i32_e32 v29, 31, v28
	v_lshlrev_b64 v[28:29], 12, v[28:29]
	v_lshl_add_u64 v[36:37], v[26:27], 0, v[28:29]
	v_add_u32_e32 v28, 50, v24
	v_ashrrev_i32_e32 v29, 31, v28
	v_lshlrev_b64 v[28:29], 12, v[28:29]
	v_lshl_add_u64 v[38:39], v[26:27], 0, v[28:29]
	v_add_u32_e32 v28, 52, v24
	v_ashrrev_i32_e32 v29, 31, v28
	v_lshlrev_b64 v[28:29], 12, v[28:29]
	v_lshl_add_u64 v[40:41], v[26:27], 0, v[28:29]
	v_add_u32_e32 v28, 54, v24
	v_ashrrev_i32_e32 v29, 31, v28
	v_lshlrev_b64 v[28:29], 12, v[28:29]
	v_lshl_add_u64 v[42:43], v[26:27], 0, v[28:29]
	v_add_u32_e32 v28, 56, v24
	v_ashrrev_i32_e32 v29, 31, v28
	v_lshlrev_b64 v[28:29], 12, v[28:29]
	v_lshl_add_u64 v[44:45], v[26:27], 0, v[28:29]
	v_add_u32_e32 v28, 58, v24
	v_ashrrev_i32_e32 v29, 31, v28
	v_lshlrev_b64 v[28:29], 12, v[28:29]
	v_lshl_add_u64 v[46:47], v[26:27], 0, v[28:29]
	v_add_u32_e32 v28, 60, v24
	v_add_u32_e32 v24, 62, v24
	v_ashrrev_i32_e32 v29, 31, v28
	v_ashrrev_i32_e32 v25, 31, v24
	v_lshlrev_b64 v[28:29], 12, v[28:29]
	v_lshlrev_b64 v[24:25], 12, v[24:25]
	v_lshl_add_u64 v[48:49], v[26:27], 0, v[28:29]
	v_lshl_add_u64 v[50:51], v[26:27], 0, v[24:25]
	global_load_dword v24, v[36:37], off
	global_load_dword v25, v[38:39], off
	global_load_dword v26, v[40:41], off
	global_load_dword v27, v[42:43], off
	global_load_dword v28, v[44:45], off
	global_load_dword v29, v[46:47], off
	global_load_dword v30, v[48:49], off
	global_load_dword v31, v[50:51], off
	v_mov_b64_e32 v[36:37], v[34:35]
	s_cbranch_execz .LBB0_1211
	s_branch .LBB0_1212

.LBB0_1218:
	s_mov_b64 s[14:15], -1
	s_cmp_gt_i32 s4, -1
	v_lshl_add_u64 v[84:85], s[12:13], 0, v[70:71]
	v_lshl_add_u64 v[82:83], s[12:13], 0, v[72:73]
	v_lshl_add_u64 v[80:81], s[12:13], 0, v[74:75]
	v_lshl_add_u64 v[78:79], s[12:13], 0, v[76:77]
	v_lshlrev_b32_e32 v68, 1, v66
	s_cbranch_scc0 .LBB0_1220
	s_waitcnt vmcnt(30)
	ds_write2_b32 v87, v0, v1 offset1:66
	s_waitcnt vmcnt(28)
	ds_write2_b32 v87, v2, v3 offset0:132 offset1:198
	v_add_u32_e32 v0, 0x400, v87
	s_waitcnt vmcnt(26)
	ds_write2_b32 v0, v4, v5 offset0:8 offset1:74
	s_waitcnt vmcnt(24)
	ds_write2_b32 v0, v6, v7 offset0:140 offset1:206
	v_add_u32_e32 v0, 0x800, v87
	s_waitcnt vmcnt(22)
	ds_write2_b32 v0, v8, v9 offset0:16 offset1:82
	s_waitcnt vmcnt(20)
	ds_write2_b32 v0, v10, v11 offset0:148 offset1:214
	v_add_u32_e32 v0, 0xc00, v87
	s_waitcnt vmcnt(18)
	ds_write2_b32 v0, v12, v13 offset0:24 offset1:90
	s_waitcnt vmcnt(16)
	ds_write2_b32 v0, v14, v15 offset0:156 offset1:222
	v_add_u32_e32 v0, 0x1000, v87
	s_waitcnt vmcnt(14)
	ds_write2_b32 v0, v16, v17 offset0:32 offset1:98
	s_waitcnt vmcnt(12)
	ds_write2_b32 v0, v18, v19 offset0:164 offset1:230
	v_add_u32_e32 v0, 0x1400, v87
	s_waitcnt vmcnt(10)
	ds_write2_b32 v0, v20, v21 offset0:40 offset1:106
	s_waitcnt vmcnt(8)
	ds_write2_b32 v0, v22, v23 offset0:172 offset1:238
	v_add_u32_e32 v0, 0x1800, v87
	s_waitcnt vmcnt(6)
	ds_write2_b32 v0, v24, v25 offset0:48 offset1:114
	s_waitcnt vmcnt(4)
	ds_write2_b32 v0, v26, v27 offset0:180 offset1:246
	v_add_u32_e32 v0, 0x1c00, v87
	s_waitcnt vmcnt(2)
	ds_write2_b32 v0, v28, v29 offset0:56 offset1:122
	s_waitcnt vmcnt(0)
	ds_write2_b32 v0, v30, v31 offset0:188 offset1:254
	s_waitcnt lgkmcnt(0)
	ds_read2_b32 v[4:5], v86 offset1:8
	ds_read2_b32 v[6:7], v86 offset0:33 offset1:41
	ds_read2_b32 v[8:9], v86 offset0:66 offset1:74
	ds_read2_b32 v[10:11], v86 offset0:99 offset1:107
	ds_read2_b32 v[12:13], v86 offset0:132 offset1:140
	s_waitcnt lgkmcnt(4)
	v_bfe_u32 v0, v4, 16, 1
	v_add3_u32 v0, v4, v0, s22
	s_waitcnt lgkmcnt(3)
	v_bfe_u32 v1, v6, 16, 1
	v_lshrrev_b32_e32 v0, 16, v0
	v_add3_u32 v1, v6, v1, s22
	ds_read2_b32 v[14:15], v86 offset0:165 offset1:173
	v_and_or_b32 v0, v1, s23, v0
	s_waitcnt lgkmcnt(3)
	v_bfe_u32 v1, v8, 16, 1
	v_add3_u32 v1, v8, v1, s22
	s_waitcnt lgkmcnt(2)
	v_bfe_u32 v2, v10, 16, 1
	ds_read2_b32 v[16:17], v86 offset0:198 offset1:206
	v_lshrrev_b32_e32 v1, 16, v1
	v_add3_u32 v2, v10, v2, s22
	ds_read2_b32 v[18:19], v86 offset0:231 offset1:239
	v_and_or_b32 v1, v2, s23, v1
	s_waitcnt lgkmcnt(3)
	v_bfe_u32 v2, v12, 16, 1
	v_add3_u32 v2, v12, v2, s22
	s_waitcnt lgkmcnt(2)
	v_bfe_u32 v3, v14, 16, 1
	v_lshrrev_b32_e32 v2, 16, v2
	v_add3_u32 v3, v14, v3, s22
	v_and_or_b32 v2, v3, s23, v2
	s_waitcnt lgkmcnt(1)
	v_bfe_u32 v3, v16, 16, 1
	s_ashr_i32 s3, s2, 31
	v_add3_u32 v3, v16, v3, s22
	s_waitcnt lgkmcnt(0)
	v_bfe_u32 v4, v18, 16, 1
	s_lshl_b64 s[4:5], s[2:3], 1
	v_lshrrev_b32_e32 v3, 16, v3
	v_add3_u32 v4, v18, v4, s22
	v_lshl_add_u64 v[20:21], v[84:85], 0, s[4:5]
	v_and_or_b32 v3, v4, s23, v3
	v_lshl_add_u64 v[20:21], v[20:21], 0, v[68:69]
	global_store_dwordx4 v[20:21], v[0:3], off sc1
	v_bfe_u32 v4, v19, 16, 1
	v_add3_u32 v4, v19, v4, s22
	v_bfe_u32 v0, v5, 16, 1
	v_add3_u32 v0, v5, v0, s22
	v_bfe_u32 v1, v7, 16, 1
	v_lshrrev_b32_e32 v0, 16, v0
	v_add3_u32 v1, v7, v1, s22
	v_and_or_b32 v0, v1, s23, v0
	v_bfe_u32 v1, v9, 16, 1
	v_add3_u32 v1, v9, v1, s22
	v_bfe_u32 v2, v11, 16, 1
	v_lshrrev_b32_e32 v1, 16, v1
	v_add3_u32 v2, v11, v2, s22
	v_and_or_b32 v1, v2, s23, v1
	v_bfe_u32 v2, v13, 16, 1
	v_add3_u32 v2, v13, v2, s22
	v_bfe_u32 v3, v15, 16, 1
	v_lshrrev_b32_e32 v2, 16, v2
	v_add3_u32 v3, v15, v3, s22
	v_and_or_b32 v2, v3, s23, v2
	v_bfe_u32 v3, v17, 16, 1
	v_add3_u32 v3, v17, v3, s22
	v_lshrrev_b32_e32 v3, 16, v3
	v_lshl_add_u64 v[6:7], v[82:83], 0, s[4:5]
	v_and_or_b32 v3, v4, s23, v3
	ds_read2_b32 v[4:5], v86 offset0:16 offset1:24
	v_lshl_add_u64 v[6:7], v[6:7], 0, v[68:69]
	global_store_dwordx4 v[6:7], v[0:3], off sc1
	ds_read2_b32 v[6:7], v86 offset0:49 offset1:57
	ds_read2_b32 v[8:9], v86 offset0:82 offset1:90
	ds_read2_b32 v[10:11], v86 offset0:115 offset1:123
	s_waitcnt lgkmcnt(3)
	v_bfe_u32 v0, v4, 16, 1
	v_add3_u32 v0, v4, v0, s22
	s_waitcnt lgkmcnt(2)
	v_bfe_u32 v1, v6, 16, 1
	ds_read2_b32 v[12:13], v86 offset0:148 offset1:156
	v_lshrrev_b32_e32 v0, 16, v0
	v_add3_u32 v1, v6, v1, s22
	ds_read2_b32 v[14:15], v86 offset0:181 offset1:189
	v_and_or_b32 v0, v1, s23, v0
	s_waitcnt lgkmcnt(3)
	v_bfe_u32 v1, v8, 16, 1
	v_add3_u32 v1, v8, v1, s22
	s_waitcnt lgkmcnt(2)
	v_bfe_u32 v2, v10, 16, 1
	ds_read2_b32 v[16:17], v86 offset0:214 offset1:222
	v_lshrrev_b32_e32 v1, 16, v1
	v_add3_u32 v2, v10, v2, s22
	ds_read2_b32 v[18:19], v86 offset0:247 offset1:255
	v_and_or_b32 v1, v2, s23, v1
	s_waitcnt lgkmcnt(3)
	v_bfe_u32 v2, v12, 16, 1
	v_add3_u32 v2, v12, v2, s22
	s_waitcnt lgkmcnt(2)
	v_bfe_u32 v3, v14, 16, 1
	v_lshrrev_b32_e32 v2, 16, v2
	v_add3_u32 v3, v14, v3, s22
	v_and_or_b32 v2, v3, s23, v2
	s_waitcnt lgkmcnt(1)
	v_bfe_u32 v3, v16, 16, 1
	v_add3_u32 v3, v16, v3, s22
	s_waitcnt lgkmcnt(0)
	v_bfe_u32 v4, v18, 16, 1
	v_lshrrev_b32_e32 v3, 16, v3
	v_add3_u32 v4, v18, v4, s22
	v_lshl_add_u64 v[20:21], v[80:81], 0, s[4:5]
	v_and_or_b32 v3, v4, s23, v3
	v_lshl_add_u64 v[20:21], v[20:21], 0, v[68:69]
	global_store_dwordx4 v[20:21], v[0:3], off sc1
	v_bfe_u32 v4, v19, 16, 1
	v_add3_u32 v4, v19, v4, s22
	v_bfe_u32 v0, v5, 16, 1
	v_add3_u32 v0, v5, v0, s22
	v_bfe_u32 v1, v7, 16, 1
	v_lshrrev_b32_e32 v0, 16, v0
	v_add3_u32 v1, v7, v1, s22
	v_and_or_b32 v0, v1, s23, v0
	v_bfe_u32 v1, v9, 16, 1
	v_add3_u32 v1, v9, v1, s22
	v_bfe_u32 v2, v11, 16, 1
	v_lshrrev_b32_e32 v1, 16, v1
	v_add3_u32 v2, v11, v2, s22
	v_and_or_b32 v1, v2, s23, v1
	v_bfe_u32 v2, v13, 16, 1
	v_add3_u32 v2, v13, v2, s22
	v_bfe_u32 v3, v15, 16, 1
	v_lshrrev_b32_e32 v2, 16, v2
	v_add3_u32 v3, v15, v3, s22
	v_and_or_b32 v2, v3, s23, v2
	v_bfe_u32 v3, v17, 16, 1
	v_add3_u32 v3, v17, v3, s22
	v_lshrrev_b32_e32 v3, 16, v3
	v_and_or_b32 v3, v4, s23, v3
	v_lshl_add_u64 v[4:5], v[78:79], 0, s[4:5]
	v_lshl_add_u64 v[4:5], v[4:5], 0, v[68:69]
	global_store_dwordx4 v[4:5], v[0:3], off sc1
	s_waitcnt lgkmcnt(0)
	s_mov_b64 s[14:15], 0
.LBB0_1220:
	s_andn2_b64 vcc, exec, s[14:15]
	s_cbranch_vccnz .LBB0_1213
	s_ashr_i32 s3, s2, 31
	s_lshl_b64 s[4:5], s[2:3], 1
	s_mov_b32 s2, s0
	s_mov_b32 s3, s0
	s_waitcnt vmcnt(30)
	v_lshl_add_u64 v[0:1], v[84:85], 0, s[4:5]
	s_mov_b32 s1, s0
	s_waitcnt vmcnt(26)
	v_mov_b64_e32 v[4:5], s[2:3]
	v_lshl_add_u64 v[0:1], v[0:1], 0, v[68:69]
	v_mov_b64_e32 v[2:3], s[0:1]
	global_store_dwordx4 v[0:1], v[2:5], off sc1
	v_lshl_add_u64 v[0:1], v[82:83], 0, s[4:5]
	v_lshl_add_u64 v[0:1], v[0:1], 0, v[68:69]
	global_store_dwordx4 v[0:1], v[2:5], off sc1
	v_lshl_add_u64 v[0:1], v[80:81], 0, s[4:5]
	v_lshl_add_u64 v[0:1], v[0:1], 0, v[68:69]
	global_store_dwordx4 v[0:1], v[2:5], off sc1
	v_lshl_add_u64 v[0:1], v[78:79], 0, s[4:5]
	v_lshl_add_u64 v[0:1], v[0:1], 0, v[68:69]
	global_store_dwordx4 v[0:1], v[2:5], off sc1
	s_branch .LBB0_1213

.LBB0_1266:
	v_lshl_add_u64 v[92:93], v[88:89], 0, s[24:25]
	v_add_co_u32_e32 v64, vcc, 0xb000000, v92
	s_add_u32 s24, s24, 0x8000
	s_nop 0
	v_addc_co_u32_e32 v65, vcc, 0, v93, vcc
	global_load_dwordx4 v[68:71], v[64:65], off
	s_nop 0
	global_load_dwordx4 v[64:67], v[64:65], off offset:64
	ds_read_b128 v[72:75], v188 offset:5376
	ds_read_b128 v[76:79], v188 offset:5392
	ds_read_b128 v[80:83], v137
	ds_read_b128 v[84:87], v188 offset:4352
	ds_read_b128 v[94:97], v188 offset:4368
	ds_read_b128 v[170:173], v137 offset:144
	ds_read_b128 v[180:183], v188 offset:4608
	ds_read_b128 v[184:187], v188 offset:4624
	ds_read_b128 v[206:209], v137 offset:288
	ds_read_b128 v[210:213], v188 offset:4864
	ds_read_b128 v[214:217], v188 offset:4880
	ds_read_b128 v[218:221], v137 offset:432
	ds_read_b128 v[222:225], v188 offset:5120
	ds_read_b128 v[226:229], v188 offset:5136
	s_waitcnt lgkmcnt(11)
	v_and_b32_e32 v99, 0xffff0000, v80
	v_lshlrev_b32_e32 v98, 16, v80
	s_waitcnt lgkmcnt(10)
	v_pk_fma_f32 v[72:73], v[84:85], v[98:99], v[72:73]
	s_waitcnt lgkmcnt(8)
	v_and_b32_e32 v85, 0xffff0000, v170
	v_lshlrev_b32_e32 v84, 16, v170
	s_waitcnt lgkmcnt(7)
	v_pk_fma_f32 v[72:73], v[180:181], v[84:85], v[72:73]
	s_waitcnt lgkmcnt(5)
	v_and_b32_e32 v85, 0xffff0000, v206
	v_lshlrev_b32_e32 v84, 16, v206
	s_waitcnt lgkmcnt(4)
	v_pk_fma_f32 v[72:73], v[210:211], v[84:85], v[72:73]
	s_waitcnt lgkmcnt(2)
	v_and_b32_e32 v85, 0xffff0000, v218
	v_lshlrev_b32_e32 v84, 16, v218
	s_waitcnt lgkmcnt(1)
	v_pk_fma_f32 v[72:73], v[222:223], v[84:85], v[72:73]
	v_and_b32_e32 v85, 0xffff0000, v82
	v_lshlrev_b32_e32 v84, 16, v82
	v_pk_fma_f32 v[76:77], v[94:95], v[84:85], v[76:77]
	v_and_b32_e32 v85, 0xffff0000, v172
	v_lshlrev_b32_e32 v84, 16, v172
	v_pk_fma_f32 v[76:77], v[184:185], v[84:85], v[76:77]
	v_and_b32_e32 v85, 0xffff0000, v208
	v_lshlrev_b32_e32 v84, 16, v208
	v_pk_fma_f32 v[76:77], v[214:215], v[84:85], v[76:77]
	v_and_b32_e32 v85, 0xffff0000, v220
	v_lshlrev_b32_e32 v84, 16, v220
	s_waitcnt lgkmcnt(0)
	v_pk_fma_f32 v[76:77], v[226:227], v[84:85], v[76:77]
	v_and_b32_e32 v85, 0xffff0000, v81
	v_lshlrev_b32_e32 v84, 16, v81
	v_pk_fma_f32 v[74:75], v[86:87], v[84:85], v[74:75]
	v_and_b32_e32 v81, 0xffff0000, v171
	v_lshlrev_b32_e32 v80, 16, v171
	v_pk_fma_f32 v[74:75], v[182:183], v[80:81], v[74:75]
	v_and_b32_e32 v81, 0xffff0000, v207
	v_lshlrev_b32_e32 v80, 16, v207
	v_pk_fma_f32 v[74:75], v[212:213], v[80:81], v[74:75]
	v_and_b32_e32 v81, 0xffff0000, v219
	v_lshlrev_b32_e32 v80, 16, v219
	v_pk_fma_f32 v[74:75], v[224:225], v[80:81], v[74:75]
	v_and_b32_e32 v81, 0xffff0000, v83
	v_lshlrev_b32_e32 v80, 16, v83
	v_pk_fma_f32 v[78:79], v[96:97], v[80:81], v[78:79]
	v_and_b32_e32 v81, 0xffff0000, v173
	v_lshlrev_b32_e32 v80, 16, v173
	v_pk_fma_f32 v[78:79], v[186:187], v[80:81], v[78:79]
	v_and_b32_e32 v81, 0xffff0000, v209
	v_lshlrev_b32_e32 v80, 16, v209
	v_pk_fma_f32 v[78:79], v[216:217], v[80:81], v[78:79]
	v_and_b32_e32 v81, 0xffff0000, v221
	v_lshlrev_b32_e32 v80, 16, v221
	v_pk_fma_f32 v[78:79], v[228:229], v[80:81], v[78:79]
	ds_read_b128 v[80:83], v188 offset:5504
	ds_read_b128 v[84:87], v188 offset:5520
	ds_read_b128 v[94:97], v137 offset:64
	ds_read_b128 v[170:173], v188 offset:4480
	ds_read_b128 v[180:183], v188 offset:4496
	ds_read_b128 v[184:187], v137 offset:208
	ds_read_b128 v[206:209], v188 offset:4736
	ds_read_b128 v[210:213], v188 offset:4752
	ds_read_b128 v[214:217], v137 offset:352
	ds_read_b128 v[218:221], v188 offset:4992
	ds_read_b128 v[222:225], v188 offset:5008
	ds_read_b128 v[226:229], v137 offset:496
	ds_read_b128 v[230:233], v188 offset:5248
	ds_read_b128 v[234:237], v188 offset:5264
	s_waitcnt lgkmcnt(11)
	v_and_b32_e32 v99, 0xffff0000, v94
	v_lshlrev_b32_e32 v98, 16, v94
	s_waitcnt lgkmcnt(10)
	v_pk_fma_f32 v[80:81], v[170:171], v[98:99], v[80:81]
	s_waitcnt lgkmcnt(8)
	v_and_b32_e32 v99, 0xffff0000, v184
	v_lshlrev_b32_e32 v98, 16, v184
	s_waitcnt lgkmcnt(7)
	v_pk_fma_f32 v[80:81], v[206:207], v[98:99], v[80:81]
	s_waitcnt lgkmcnt(5)
	v_and_b32_e32 v99, 0xffff0000, v214
	v_lshlrev_b32_e32 v98, 16, v214
	s_waitcnt lgkmcnt(4)
	v_pk_fma_f32 v[80:81], v[218:219], v[98:99], v[80:81]
	s_waitcnt lgkmcnt(2)
	v_and_b32_e32 v99, 0xffff0000, v226
	v_lshlrev_b32_e32 v98, 16, v226
	s_waitcnt lgkmcnt(1)
	v_pk_fma_f32 v[80:81], v[230:231], v[98:99], v[80:81]
	v_and_b32_e32 v99, 0xffff0000, v96
	v_lshlrev_b32_e32 v98, 16, v96
	v_pk_fma_f32 v[84:85], v[180:181], v[98:99], v[84:85]
	v_and_b32_e32 v99, 0xffff0000, v186
	v_lshlrev_b32_e32 v98, 16, v186
	v_pk_fma_f32 v[84:85], v[210:211], v[98:99], v[84:85]
	v_and_b32_e32 v99, 0xffff0000, v216
	v_lshlrev_b32_e32 v98, 16, v216
	v_pk_fma_f32 v[84:85], v[222:223], v[98:99], v[84:85]
	v_and_b32_e32 v99, 0xffff0000, v228
	v_lshlrev_b32_e32 v98, 16, v228
	s_waitcnt lgkmcnt(0)
	v_pk_fma_f32 v[84:85], v[234:235], v[98:99], v[84:85]
	v_and_b32_e32 v99, 0xffff0000, v95
	v_lshlrev_b32_e32 v98, 16, v95
	v_pk_fma_f32 v[82:83], v[172:173], v[98:99], v[82:83]
	v_and_b32_e32 v95, 0xffff0000, v185
	v_lshlrev_b32_e32 v94, 16, v185
	v_pk_fma_f32 v[82:83], v[208:209], v[94:95], v[82:83]
	v_and_b32_e32 v95, 0xffff0000, v215
	v_lshlrev_b32_e32 v94, 16, v215
	v_pk_fma_f32 v[82:83], v[220:221], v[94:95], v[82:83]
	v_and_b32_e32 v95, 0xffff0000, v227
	v_lshlrev_b32_e32 v94, 16, v227
	v_pk_fma_f32 v[82:83], v[232:233], v[94:95], v[82:83]
	v_and_b32_e32 v95, 0xffff0000, v97
	v_lshlrev_b32_e32 v94, 16, v97
	v_pk_fma_f32 v[86:87], v[182:183], v[94:95], v[86:87]
	v_and_b32_e32 v95, 0xffff0000, v187
	v_lshlrev_b32_e32 v94, 16, v187
	v_pk_fma_f32 v[86:87], v[212:213], v[94:95], v[86:87]
	v_and_b32_e32 v95, 0xffff0000, v217
	v_lshlrev_b32_e32 v94, 16, v217
	v_pk_fma_f32 v[86:87], v[224:225], v[94:95], v[86:87]
	v_and_b32_e32 v95, 0xffff0000, v229
	v_lshlrev_b32_e32 v94, 16, v229
	v_pk_fma_f32 v[86:87], v[236:237], v[94:95], v[86:87]
	v_cvt_pk_bf16_f32 v94, v72, v73
	v_cvt_pk_bf16_f32 v95, v74, v75
	v_cvt_pk_bf16_f32 v96, v76, v77
	v_cvt_pk_bf16_f32 v97, v78, v79
	ds_write_b128 v190, v[72:75]
	ds_write_b128 v190, v[76:79] offset:16
	v_cvt_pk_bf16_f32 v76, v80, v81
	v_cvt_pk_bf16_f32 v77, v82, v83
	v_cvt_pk_bf16_f32 v78, v84, v85
	v_cvt_pk_bf16_f32 v79, v86, v87
	s_waitcnt vmcnt(17)
	v_mfma_f32_16x16x32_bf16 v[72:75], v[94:97], v[0:3], 0
	ds_write_b128 v190, v[80:83] offset:128
	ds_write_b128 v190, v[84:87] offset:144
	ds_read2_b32 v[174:175], v191 offset0:68 offset1:84
	ds_read2_b32 v[216:217], v191 offset0:204 offset1:220
	s_waitcnt vmcnt(16)
	v_mfma_f32_16x16x32_bf16 v[170:173], v[76:79], v[4:7], v[72:75]
	s_addc_u32 s25, s25, 0
	v_add_u32_e32 v137, 0x900, v137
	s_cmp_lg_u32 s24, 0x20000
	s_waitcnt vmcnt(15)
	v_mfma_f32_16x16x32_bf16 v[72:75], v[94:97], v[8:11], 0
	s_waitcnt vmcnt(11)
	v_mfma_f32_16x16x32_bf16 v[84:87], v[94:97], v[24:27], 0
	s_nop 0
	v_add_f32_e32 v91, v193, v170
	v_mul_f32_e32 v91, 0xbfb8aa3b, v91
	v_exp_f32_e32 v91, v91
	v_mfma_f32_16x16x32_bf16 v[206:209], v[76:79], v[12:15], v[72:75]
	v_add_f32_e32 v91, 1.0, v91
	s_waitcnt vmcnt(3)
	v_mfma_f32_16x16x32_bf16 v[72:75], v[94:97], v[56:59], 0
	v_rcp_f32_e32 v91, v91
	s_nop 0
	v_mul_f32_e32 v91, v201, v91
	v_mfma_f32_16x16x32_bf16 v[180:183], v[76:79], v[28:31], v[84:87]
	v_exp_f32_e32 v214, v91
	s_nop 0
	v_fma_f32 v91, -v214, v214, 1.0
	v_mfma_f32_16x16x32_bf16 v[84:87], v[94:97], v[32:35], 0
	v_sqrt_f32_e32 v215, v91
	v_mfma_f32_16x16x32_bf16 v[80:83], v[76:79], v[16:19], v[72:75]
	v_mfma_f32_16x16x32_bf16 v[72:75], v[94:97], v[20:23], 0
	v_mfma_f32_16x16x32_bf16 v[210:213], v[76:79], v[36:39], v[84:87]
	s_nop 5
	v_add_f32_e32 v80, v195, v80
	v_mul_f32_e32 v80, 0xbfb8aa3b, v80
	v_exp_f32_e32 v80, v80
	v_mfma_f32_16x16x32_bf16 v[84:87], v[94:97], v[44:47], 0
	v_add_f32_e32 v82, v195, v82
	v_mul_f32_e32 v82, 0xbfb8aa3b, v82
	v_add_f32_e32 v80, 1.0, v80
	v_mfma_f32_16x16x32_bf16 v[94:97], v[94:97], v[52:55], 0
	v_rcp_f32_e32 v80, v80
	v_exp_f32_e32 v82, v82
	v_mul_f32_e32 v80, v203, v80
	v_mfma_f32_16x16x32_bf16 v[72:75], v[76:79], v[40:43], v[72:75]
	v_add_f32_e32 v82, 1.0, v82
	v_rcp_f32_e32 v82, v82
	v_mfma_f32_16x16x32_bf16 v[84:87], v[76:79], v[48:51], v[84:87]
	v_mul_f32_e32 v82, v203, v82
	s_nop 3
	v_add_f32_e32 v72, v196, v72
	s_waitcnt vmcnt(2)
	v_mfma_f32_16x16x32_bf16 v[76:79], v[76:79], v[60:63], v[94:97]
	v_mul_f32_e32 v72, 0xbfb8aa3b, v72
	v_exp_f32_e32 v72, v72
	v_add_f32_e32 v84, v199, v84
	v_add_f32_e32 v94, v197, v180
	v_mul_f32_e32 v94, 0xbfb8aa3b, v94
	v_exp_f32_e32 v94, v94
	ds_read2_b32 v[96:97], v191 offset1:16
	v_add_f32_e32 v72, 1.0, v72
	v_rcp_f32_e32 v72, v72
	v_add_f32_e32 v94, 1.0, v94
	v_rcp_f32_e32 v94, v94
	v_mul_f32_e32 v84, 0xbfb8aa3b, v84
	v_exp_f32_e32 v84, v84
	v_add_f32_e32 v76, v200, v76
	s_waitcnt lgkmcnt(0)
	v_mul_f32_e32 v91, v94, v96
	v_mul_f32_e32 v94, v215, v91
	v_pk_fma_f32 v[94:95], v[214:215], v[90:91], v[94:95] op_sel_hi:[1,1,0]
	v_add_f32_e32 v91, v193, v171
	v_mul_f32_e32 v91, 0xbfb8aa3b, v91
	v_exp_f32_e32 v91, v91
	v_add_f32_e32 v95, v197, v181
	v_mul_f32_e32 v95, 0xbfb8aa3b, v95
	v_exp_f32_e32 v95, v95
	v_add_f32_e32 v91, 1.0, v91
	v_rcp_f32_e32 v91, v91
	v_mov_b32_e32 v99, v94
	v_add_f32_e32 v95, 1.0, v95
	v_rcp_f32_e32 v95, v95
	v_mul_f32_e32 v91, v201, v91
	v_exp_f32_e32 v171, v91
	v_mul_f32_e32 v76, 0xbfb8aa3b, v76
	v_mul_f32_e32 v98, v95, v174
	v_exp_f32_e32 v76, v76
	v_fma_f32 v91, -v171, v171, 1.0
	v_sqrt_f32_e32 v170, v91
	v_add_f32_e32 v91, v193, v172
	v_mul_f32_e32 v91, 0xbfb8aa3b, v91
	v_exp_f32_e32 v91, v91
	v_mul_f32_e32 v96, v171, v94
	v_pk_fma_f32 v[98:99], v[170:171], v[98:99], v[96:97] op_sel_hi:[1,1,0]
	v_add_f32_e32 v96, v197, v182
	v_add_f32_e32 v91, 1.0, v91
	v_rcp_f32_e32 v91, v91
	v_mul_f32_e32 v96, 0xbfb8aa3b, v96
	v_exp_f32_e32 v96, v96
	v_mul_f32_e32 v95, v214, v171
	v_mul_f32_e32 v91, v201, v91
	v_exp_f32_e32 v185, v91
	ds_read2_b32 v[170:171], v191 offset0:136 offset1:152
	v_add_f32_e32 v96, 1.0, v96
	v_rcp_f32_e32 v96, v96
	v_fma_f32 v91, -v185, v185, 1.0
	v_sqrt_f32_e32 v184, v91
	v_add_f32_e32 v91, v193, v173
	v_mul_f32_e32 v91, 0xbfb8aa3b, v91
	v_exp_f32_e32 v91, v91
	s_waitcnt lgkmcnt(0)
	v_mul_f32_e32 v180, v96, v170
	v_mov_b32_e32 v181, v98
	v_mul_f32_e32 v96, v185, v98
	v_add_f32_e32 v91, 1.0, v91
	v_rcp_f32_e32 v91, v91
	v_pk_fma_f32 v[180:181], v[184:185], v[180:181], v[96:97] op_sel_hi:[1,1,0]
	v_add_f32_e32 v96, v197, v183
	v_mul_f32_e32 v96, 0xbfb8aa3b, v96
	v_exp_f32_e32 v96, v96
	v_mul_f32_e32 v91, v201, v91
	v_exp_f32_e32 v173, v91
	v_mul_f32_e32 v99, v185, v95
	v_add_f32_e32 v96, 1.0, v96
	v_rcp_f32_e32 v96, v96
	v_fma_f32 v91, -v173, v173, 1.0
	v_sqrt_f32_e32 v172, v91
	v_mul_f32_e32 v215, v173, v99
	v_mov_b32_e32 v91, v215
	v_mov_b32_e32 v170, v215
	v_mul_f32_e32 v182, v96, v216
	v_mov_b32_e32 v183, v180
	v_permlane16_swap_b32_e32 v91, v170
	v_pk_mul_f32 v[182:183], v[172:173], v[182:183]
	v_mul_f32_e32 v172, v91, v170
	v_cndmask_b32_e64 v216, v91, 1.0, s[6:7]
	v_add_f32_e32 v91, v194, v206
	v_mul_f32_e32 v91, 0xbfb8aa3b, v91
	v_exp_f32_e32 v91, v91
	v_add_f32_e32 v181, v182, v183
	v_mov_b32_e32 v173, v181
	v_mov_b32_e32 v96, v181
	v_add_f32_e32 v91, 1.0, v91
	v_rcp_f32_e32 v91, v91
	v_permlane16_swap_b32_e32 v173, v96
	v_fmac_f32_e32 v96, v170, v173
	v_cndmask_b32_e64 v220, v173, 0, s[6:7]
	v_add_f32_e32 v173, v198, v210
	v_mul_f32_e32 v173, 0xbfb8aa3b, v173
	v_exp_f32_e32 v173, v173
	v_mul_f32_e32 v91, v202, v91
	v_exp_f32_e32 v218, v91
	v_mov_b32_e32 v170, v172
	v_add_f32_e32 v173, 1.0, v173
	v_rcp_f32_e32 v173, v173
	v_fma_f32 v91, -v218, v218, 1.0
	v_sqrt_f32_e32 v219, v91
	v_mov_b32_e32 v174, v96
	v_mul_f32_e32 v91, v173, v97
	v_add_f32_e32 v97, v198, v211
	v_mul_f32_e32 v182, v219, v91
	v_mul_f32_e32 v97, 0xbfb8aa3b, v97
	v_pk_fma_f32 v[182:183], v[218:219], v[90:91], v[182:183] op_sel_hi:[1,1,0]
	v_add_f32_e32 v91, v194, v207
	v_exp_f32_e32 v97, v97
	v_mul_f32_e32 v91, 0xbfb8aa3b, v91
	v_exp_f32_e32 v91, v91
	v_mov_b32_e32 v185, v182
	v_add_f32_e32 v97, 1.0, v97
	v_rcp_f32_e32 v97, v97
	v_add_f32_e32 v91, 1.0, v91
	v_rcp_f32_e32 v91, v91
	v_add_f32_e32 v173, v198, v212
	v_mul_f32_e32 v184, v97, v175
	v_add_f32_e32 v97, v194, v208
	v_mul_f32_e32 v97, 0xbfb8aa3b, v97
	v_mul_f32_e32 v91, v202, v91
	v_exp_f32_e32 v97, v97
	v_exp_f32_e32 v187, v91
	v_mul_f32_e32 v173, 0xbfb8aa3b, v173
	v_exp_f32_e32 v173, v173
	v_add_f32_e32 v97, 1.0, v97
	v_fma_f32 v91, -v187, v187, 1.0
	v_rcp_f32_e32 v97, v97
	v_sqrt_f32_e32 v186, v91
	v_mul_f32_e32 v206, v187, v182
	v_add_f32_e32 v173, 1.0, v173
	v_mul_f32_e32 v97, v202, v97
	v_pk_fma_f32 v[184:185], v[186:187], v[184:185], v[206:207] op_sel_hi:[1,1,0]
	v_exp_f32_e32 v207, v97
	v_rcp_f32_e32 v173, v173
	v_mul_f32_e32 v91, v218, v187
	v_mov_b32_e32 v187, v184
	v_fma_f32 v97, -v207, v207, 1.0
	v_sqrt_f32_e32 v206, v97
	v_add_f32_e32 v97, v194, v209
	v_mul_f32_e32 v97, 0xbfb8aa3b, v97
	v_exp_f32_e32 v97, v97
	v_mul_f32_e32 v186, v173, v171
	v_add_f32_e32 v171, v198, v213
	v_mul_f32_e32 v171, 0xbfb8aa3b, v171
	v_add_f32_e32 v97, 1.0, v97
	v_rcp_f32_e32 v97, v97
	v_mul_f32_e32 v208, v207, v184
	v_exp_f32_e32 v171, v171
	v_pk_fma_f32 v[186:187], v[206:207], v[186:187], v[208:209] op_sel_hi:[1,1,0]
	v_mul_f32_e32 v97, v202, v97
	v_mul_f32_e32 v183, v207, v91
	v_exp_f32_e32 v207, v97
	v_add_f32_e32 v171, 1.0, v171
	v_rcp_f32_e32 v171, v171
	v_mov_b32_e32 v209, v186
	v_fma_f32 v97, -v207, v207, 1.0
	v_sqrt_f32_e32 v206, v97
	v_mul_f32_e32 v208, v171, v217
	v_mul_f32_e32 v187, v207, v183
	v_mov_b32_e32 v171, v187
	v_pk_mul_f32 v[208:209], v[206:207], v[208:209]
	v_mov_b32_e32 v206, v187
	v_add_f32_e32 v185, v208, v209
	v_mov_b32_e32 v207, v185
	v_mov_b32_e32 v97, v185
	v_permlane32_swap_b32_e32 v172, v170
	v_permlane32_swap_b32_e32 v96, v174
	v_permlane16_swap_b32_e32 v206, v171
	v_permlane16_swap_b32_e32 v207, v97
	v_mul_f32_e32 v173, v206, v171
	v_fmac_f32_e32 v97, v171, v207
	v_cndmask_b32_e64 v208, v172, 1.0, s[8:9]
	v_cndmask_b32_e64 v209, v96, 0, s[8:9]
	v_mov_b32_e32 v171, v173
	v_mov_b32_e32 v175, v97
	v_mul_f32_e32 v208, v216, v208
	v_fmac_f32_e32 v220, v216, v209
	v_permlane32_swap_b32_e32 v173, v171
	v_permlane32_swap_b32_e32 v97, v175
	v_fmac_f32_e32 v220, v178, v208
	v_cndmask_b32_e64 v206, v206, 1.0, s[6:7]
	v_cndmask_b32_e64 v207, v207, 0, s[6:7]
	v_fmac_f32_e32 v98, v95, v220
	v_fmac_f32_e32 v180, v99, v220
	v_cndmask_b32_e64 v95, v173, 1.0, s[8:9]
	v_cndmask_b32_e64 v99, v97, 0, s[8:9]
	v_mul_f32_e32 v95, v206, v95
	v_fmac_f32_e32 v207, v206, v99
	v_exp_f32_e32 v208, v80
	v_fmac_f32_e32 v207, v179, v95
	v_mul_f32_e32 v72, v204, v72
	v_fmac_f32_e32 v182, v218, v207
	v_exp_f32_e32 v218, v72
	v_fmac_f32_e32 v184, v91, v207
	v_fmac_f32_e32 v186, v183, v207
	v_fmac_f32_e32 v185, v187, v207
	ds_read2_b32 v[206:207], v191 offset0:32 offset1:48
	v_add_f32_e32 v84, 1.0, v84
	v_rcp_f32_e32 v84, v84
	v_fma_f32 v80, -v208, v208, 1.0
	v_sqrt_f32_e32 v209, v80
	v_add_f32_e32 v76, 1.0, v76
	v_rcp_f32_e32 v76, v76
	v_fma_f32 v72, -v218, v218, 1.0
	v_sqrt_f32_e32 v219, v72
	s_waitcnt lgkmcnt(0)
	v_mul_f32_e32 v91, v84, v206
	v_mul_f32_e32 v80, v209, v91
	v_pk_fma_f32 v[210:211], v[208:209], v[90:91], v[80:81] op_sel_hi:[1,1,0]
	v_mul_f32_e32 v91, v76, v207
	v_mul_f32_e32 v72, v219, v91
	v_fmac_f32_e32 v94, v214, v220
	v_fmac_f32_e32 v181, v215, v220
	v_pk_fma_f32 v[220:221], v[218:219], v[90:91], v[72:73] op_sel_hi:[1,1,0]
	v_add_f32_e32 v72, v196, v73
	v_mul_f32_e32 v72, 0xbfb8aa3b, v72
	v_exp_f32_e32 v72, v72
	v_add_f32_e32 v73, v200, v77
	v_mul_f32_e32 v73, 0xbfb8aa3b, v73
	v_exp_f32_e32 v73, v73
	v_add_f32_e32 v72, 1.0, v72
	v_rcp_f32_e32 v72, v72
	v_add_f32_e32 v80, v195, v81
	v_add_f32_e32 v81, v199, v85
	v_mul_f32_e32 v81, 0xbfb8aa3b, v81
	v_exp_f32_e32 v81, v81
	v_add_f32_e32 v73, 1.0, v73
	v_mul_f32_e32 v72, v204, v72
	v_mul_f32_e32 v80, 0xbfb8aa3b, v80
	v_rcp_f32_e32 v76, v73
	v_exp_f32_e32 v73, v72
	v_exp_f32_e32 v80, v80
	ds_read2_b32 v[212:213], v191 offset0:100 offset1:116
	v_add_f32_e32 v81, 1.0, v81
	v_rcp_f32_e32 v84, v81
	v_fma_f32 v72, -v73, v73, 1.0
	v_add_f32_e32 v80, 1.0, v80
	v_sqrt_f32_e32 v72, v72
	v_rcp_f32_e32 v80, v80
	s_waitcnt lgkmcnt(0)
	v_mul_f32_e32 v84, v84, v212
	v_mul_f32_e32 v76, v76, v213
	v_mov_b32_e32 v77, v220
	v_mul_f32_e32 v212, v73, v220
	v_pk_fma_f32 v[76:77], v[72:73], v[76:77], v[212:213] op_sel_hi:[1,1,0]
	v_add_f32_e32 v72, v196, v74
	v_mul_f32_e32 v80, v203, v80
	v_mul_f32_e32 v72, 0xbfb8aa3b, v72
	v_exp_f32_e32 v81, v80
	v_exp_f32_e32 v72, v72
	v_mul_f32_e32 v77, v218, v73
	v_add_f32_e32 v73, v200, v78
	v_fma_f32 v80, -v81, v81, 1.0
	v_add_f32_e32 v86, v199, v86
	v_add_f32_e32 v72, 1.0, v72
	v_mul_f32_e32 v73, 0xbfb8aa3b, v73
	v_sqrt_f32_e32 v80, v80
	v_mul_f32_e32 v86, 0xbfb8aa3b, v86
	v_rcp_f32_e32 v72, v72
	v_exp_f32_e32 v73, v73
	v_exp_f32_e32 v86, v86
	v_exp_f32_e32 v215, v82
	v_mov_b32_e32 v85, v210
	v_mul_f32_e32 v206, v81, v210
	v_pk_fma_f32 v[84:85], v[80:81], v[84:85], v[206:207] op_sel_hi:[1,1,0]
	v_add_f32_e32 v73, 1.0, v73
	v_mul_f32_e32 v72, v204, v72
	v_mul_f32_e32 v85, v208, v81
	ds_read2_b32 v[80:81], v191 offset0:168 offset1:184
	v_add_f32_e32 v86, 1.0, v86
	v_rcp_f32_e32 v74, v73
	v_exp_f32_e32 v73, v72
	v_rcp_f32_e32 v86, v86
	v_fma_f32 v82, -v215, v215, 1.0
	v_sqrt_f32_e32 v214, v82
	v_fma_f32 v72, -v73, v73, 1.0
	s_waitcnt lgkmcnt(0)
	v_mul_f32_e32 v216, v86, v80
	v_mov_b32_e32 v217, v84
	v_mul_f32_e32 v80, v215, v84
	v_sqrt_f32_e32 v72, v72
	v_pk_fma_f32 v[216:217], v[214:215], v[216:217], v[80:81] op_sel_hi:[1,1,0]
	v_add_f32_e32 v80, v195, v83
	v_mul_f32_e32 v80, 0xbfb8aa3b, v80
	v_exp_f32_e32 v80, v80
	v_mul_f32_e32 v212, v74, v81
	v_mov_b32_e32 v213, v76
	v_mul_f32_e32 v74, v73, v76
	v_pk_fma_f32 v[212:213], v[72:73], v[212:213], v[74:75] op_sel_hi:[1,1,0]
	v_add_f32_e32 v72, v196, v75
	v_mul_f32_e32 v72, 0xbfb8aa3b, v72
	v_exp_f32_e32 v72, v72
	v_add_f32_e32 v80, 1.0, v80
	v_rcp_f32_e32 v80, v80
	v_mul_f32_e32 v78, v73, v77
	v_add_f32_e32 v73, v200, v79
	v_add_f32_e32 v82, v199, v87
	v_add_f32_e32 v72, 1.0, v72
	v_mul_f32_e32 v73, 0xbfb8aa3b, v73
	v_mul_f32_e32 v82, 0xbfb8aa3b, v82
	v_rcp_f32_e32 v72, v72
	v_exp_f32_e32 v73, v73
	v_exp_f32_e32 v82, v82
	v_mul_f32_e32 v80, v203, v80
	v_exp_f32_e32 v83, v80
	v_add_f32_e32 v73, 1.0, v73
	v_mul_f32_e32 v72, v204, v72
	v_mul_f32_e32 v95, v215, v85
	ds_read2_b32 v[214:215], v191 offset0:236 offset1:252
	v_add_f32_e32 v82, 1.0, v82
	v_rcp_f32_e32 v74, v73
	v_exp_f32_e32 v73, v72
	v_rcp_f32_e32 v86, v82
	v_fma_f32 v80, -v83, v83, 1.0
	v_sqrt_f32_e32 v82, v80
	v_fma_f32 v72, -v73, v73, 1.0
	s_waitcnt lgkmcnt(0)
	v_mul_f32_e32 v86, v86, v214
	v_mov_b32_e32 v87, v216
	v_sqrt_f32_e32 v72, v72
	v_pk_mul_f32 v[86:87], v[82:83], v[86:87]
	v_mul_f32_e32 v183, v83, v95
	v_add_f32_e32 v99, v86, v87
	v_mov_b32_e32 v83, v183
	v_mov_b32_e32 v86, v183
	v_mov_b32_e32 v87, v99
	v_mov_b32_e32 v80, v99
	v_mul_f32_e32 v74, v74, v215
	v_mov_b32_e32 v75, v212
	v_permlane16_swap_b32_e32 v83, v86
	v_permlane16_swap_b32_e32 v87, v80
	v_pk_mul_f32 v[74:75], v[72:73], v[74:75]
	v_mul_f32_e32 v82, v83, v86
	v_fmac_f32_e32 v80, v86, v87
	v_add_f32_e32 v72, v74, v75
	v_mul_f32_e32 v73, v73, v78
	v_mov_b32_e32 v86, v82
	v_mov_b32_e32 v206, v80
	v_mov_b32_e32 v74, v73
	v_mov_b32_e32 v75, v73
	v_mov_b32_e32 v79, v72
	v_mov_b32_e32 v81, v72
	v_permlane32_swap_b32_e32 v82, v86
	v_permlane32_swap_b32_e32 v80, v206
	v_permlane16_swap_b32_e32 v74, v75
	v_permlane16_swap_b32_e32 v79, v81
	v_cndmask_b32_e64 v187, v83, 1.0, s[6:7]
	v_cndmask_b32_e64 v209, v87, 0, s[6:7]
	v_mul_f32_e32 v83, v74, v75
	v_fmac_f32_e32 v81, v75, v79
	v_cndmask_b32_e64 v75, v79, 0, s[6:7]
	v_cndmask_b32_e64 v79, v82, 1.0, s[8:9]
	v_cndmask_b32_e64 v91, v80, 0, s[8:9]
	v_mov_b32_e32 v87, v83
	v_mov_b32_e32 v207, v81
	v_mul_f32_e32 v79, v187, v79
	v_fmac_f32_e32 v209, v187, v91
	v_permlane32_swap_b32_e32 v83, v87
	v_permlane32_swap_b32_e32 v81, v207
	v_fmac_f32_e32 v209, v176, v79
	v_cndmask_b32_e64 v74, v74, 1.0, s[6:7]
	v_fmac_f32_e32 v84, v85, v209
	v_cndmask_b32_e64 v79, v83, 1.0, s[8:9]
	v_cndmask_b32_e64 v85, v81, 0, s[8:9]
	v_mul_f32_e32 v79, v74, v79
	v_fmac_f32_e32 v75, v74, v85
	v_fmac_f32_e32 v75, v177, v79
	v_fmac_f32_e32 v210, v208, v209
	v_fmac_f32_e32 v216, v95, v209
	v_fmac_f32_e32 v99, v183, v209
	v_fmac_f32_e32 v220, v218, v75
	v_fmac_f32_e32 v76, v77, v75
	v_fmac_f32_e32 v212, v78, v75
	v_fmac_f32_e32 v72, v73, v75
	ds_write2_b32 v191, v94, v182 offset1:16
	ds_write2_b32 v191, v98, v184 offset0:68 offset1:84
	ds_write2_b32 v191, v180, v186 offset0:136 offset1:152
	ds_write2_b32 v191, v181, v185 offset0:204 offset1:220
	ds_write2_b32 v191, v210, v220 offset0:32 offset1:48
	ds_write2_b32 v191, v84, v76 offset0:100 offset1:116
	ds_write2_b32 v191, v216, v212 offset0:168 offset1:184
	ds_write2_b32 v191, v99, v72 offset0:236 offset1:252
	ds_read_b128 v[72:75], v190
	ds_read_b128 v[76:79], v190 offset:16
	s_waitcnt vmcnt(1)
	v_lshlrev_b32_e32 v84, 16, v68
	v_and_b32_e32 v85, 0xffff0000, v68
	s_waitcnt lgkmcnt(1)
	v_pk_mul_f32 v[72:73], v[72:73], v[84:85]
	s_nop 0
	v_cvt_pk_bf16_f32 v68, v72, v73
	v_lshlrev_b32_e32 v72, 16, v69
	v_and_b32_e32 v73, 0xffff0000, v69
	v_pk_mul_f32 v[72:73], v[74:75], v[72:73]
	s_nop 0
	v_cvt_pk_bf16_f32 v69, v72, v73
	v_lshlrev_b32_e32 v72, 16, v70
	v_and_b32_e32 v73, 0xffff0000, v70
	s_waitcnt lgkmcnt(0)
	v_pk_mul_f32 v[72:73], v[76:77], v[72:73]
	v_add_co_u32_e32 v76, vcc, s26, v92
	v_cvt_pk_bf16_f32 v70, v72, v73
	v_lshlrev_b32_e32 v72, 16, v71
	v_and_b32_e32 v73, 0xffff0000, v71
	v_pk_mul_f32 v[72:73], v[78:79], v[72:73]
	v_addc_co_u32_e32 v77, vcc, 0, v93, vcc
	v_cvt_pk_bf16_f32 v71, v72, v73
	global_store_dwordx4 v[76:77], v[68:71], off sc1
	ds_read_b128 v[68:71], v190 offset:128
	ds_read_b128 v[72:75], v190 offset:144
	s_waitcnt vmcnt(1)
	v_lshlrev_b32_e32 v78, 16, v64
	v_and_b32_e32 v79, 0xffff0000, v64
	s_waitcnt lgkmcnt(1)
	v_pk_mul_f32 v[68:69], v[68:69], v[78:79]
	s_nop 0
	v_cvt_pk_bf16_f32 v64, v68, v69
	v_lshlrev_b32_e32 v68, 16, v65
	v_and_b32_e32 v69, 0xffff0000, v65
	v_pk_mul_f32 v[68:69], v[70:71], v[68:69]
	v_pk_fma_f32 v[70:71], v[86:87], v[80:81], v[206:207]
	v_cvt_pk_bf16_f32 v65, v68, v69
	v_lshlrev_b32_e32 v68, 16, v66
	v_and_b32_e32 v69, 0xffff0000, v66
	s_waitcnt lgkmcnt(0)
	v_pk_mul_f32 v[68:69], v[72:73], v[68:69]
	s_nop 0
	v_cvt_pk_bf16_f32 v66, v68, v69
	v_lshlrev_b32_e32 v68, 16, v67
	v_and_b32_e32 v69, 0xffff0000, v67
	v_pk_mul_f32 v[68:69], v[74:75], v[68:69]
	s_nop 0
	v_cvt_pk_bf16_f32 v67, v68, v69
	global_store_dwordx4 v[76:77], v[64:67], off offset:64 sc1
	v_pk_fma_f32 v[68:69], v[170:171], v[96:97], v[174:175]
	s_nop 0
	v_pk_mul_f32 v[64:65], v[170:171], v[172:173]
	v_pk_mul_f32 v[66:67], v[86:87], v[82:83]
	v_pk_fma_f32 v[178:179], v[178:179], v[64:65], v[68:69]
	v_pk_fma_f32 v[176:177], v[176:177], v[66:67], v[70:71]
	s_cbranch_scc1 .LBB0_1266
	s_or_b32 s24, s56, 1
	s_ashr_i32 s25, s24, 31
	s_lshl_b32 s28, s24, 6
	s_lshl_b64 s[26:27], s[24:25], 6
	s_sub_i32 s29, 2, s28
	s_add_u32 s24, s26, s57
	v_cmp_lt_i32_e32 vcc, s29, v116
	s_addc_u32 s25, s27, s71
	s_and_b64 s[30:31], s[0:1], vcc
	v_mov_b32_e32 v64, 0
	v_mov_b32_e32 v68, 0
	v_mov_b32_e32 v69, 0
	v_mov_b32_e32 v70, 0
	v_mov_b32_e32 v71, 0
	s_and_saveexec_b64 s[26:27], s[30:31]
	s_cbranch_execz .LBB0_1269
	v_lshl_add_u64 v[0:1], s[24:25], 0, v[116:117]
	s_movk_i32 s33, 0x600
	v_mad_u64_u32 v[2:3], s[30:31], v0, s33, v[106:107]
	v_mad_i32_i24 v3, v1, s33, v3
	global_load_dwordx4 v[68:71], v[2:3], off

.LBB0_1296:
	ds_read_b128 v[64:67], v188 offset:5376
	ds_read_b128 v[68:71], v188 offset:5392
	ds_read_b128 v[96:99], v188 offset:4352
	ds_read_b128 v[100:103], v188 offset:4368
	ds_read_b128 v[88:91], v188 offset:4608
	ds_read_b128 v[92:95], v188 offset:4624
	ds_read_b128 v[80:83], v188 offset:4864
	ds_read_b128 v[84:87], v188 offset:4880
	ds_read_b128 v[72:75], v188 offset:5120
	ds_read_b128 v[76:79], v188 offset:5136
	ds_read_b128 v[104:107], v188 offset:5504
	ds_read_b128 v[108:111], v188 offset:5520
	ds_read_b128 v[160:163], v189
	ds_read_b128 v[148:151], v189 offset:64
	ds_read_b128 v[136:139], v188 offset:4480
	ds_read_b128 v[140:143], v188 offset:4496
	ds_read_b128 v[164:167], v189 offset:144
	ds_read_b128 v[152:155], v189 offset:208
	ds_read_b128 v[132:135], v188 offset:4736
	ds_read_b128 v[128:131], v188 offset:4752
	ds_read_b128 v[168:171], v189 offset:288
	ds_read_b128 v[156:159], v189 offset:352
	ds_read_b128 v[120:123], v188 offset:4992
	ds_read_b128 v[124:127], v188 offset:5008
	ds_read_b128 v[172:175], v189 offset:432
	ds_read_b128 v[144:147], v189 offset:496
	ds_read_b128 v[112:115], v188 offset:5248
	ds_read_b128 v[116:119], v188 offset:5264
	s_waitcnt lgkmcnt(14)
	v_and_b32_e32 v209, 0xffff0000, v160
	v_lshlrev_b32_e32 v208, 16, v160
	s_waitcnt lgkmcnt(11)
	v_and_b32_e32 v211, 0xffff0000, v164
	v_lshlrev_b32_e32 v210, 16, v164
	s_waitcnt lgkmcnt(7)
	v_and_b32_e32 v213, 0xffff0000, v168
	v_lshlrev_b32_e32 v212, 16, v168
	s_waitcnt lgkmcnt(3)
	v_and_b32_e32 v215, 0xffff0000, v172
	v_lshlrev_b32_e32 v214, 16, v172
	v_and_b32_e32 v217, 0xffff0000, v162
	v_lshlrev_b32_e32 v216, 16, v162
	v_and_b32_e32 v225, 0xffff0000, v161
	v_lshlrev_b32_e32 v224, 16, v161
	v_and_b32_e32 v161, 0xffff0000, v165
	v_lshlrev_b32_e32 v160, 16, v165
	v_and_b32_e32 v165, 0xffff0000, v169
	v_lshlrev_b32_e32 v164, 16, v169
	v_and_b32_e32 v169, 0xffff0000, v173
	v_lshlrev_b32_e32 v168, 16, v173
	v_and_b32_e32 v173, 0xffff0000, v163
	v_lshlrev_b32_e32 v172, 16, v163
	v_and_b32_e32 v219, 0xffff0000, v166
	v_lshlrev_b32_e32 v218, 16, v166
	v_and_b32_e32 v163, 0xffff0000, v167
	v_lshlrev_b32_e32 v162, 16, v167
	v_pk_fma_f32 v[64:65], v[96:97], v[208:209], v[64:65]
	v_pk_fma_f32 v[68:69], v[100:101], v[216:217], v[68:69]
	v_pk_fma_f32 v[66:67], v[98:99], v[224:225], v[66:67]
	v_pk_fma_f32 v[70:71], v[102:103], v[172:173], v[70:71]
	v_and_b32_e32 v221, 0xffff0000, v170
	v_lshlrev_b32_e32 v220, 16, v170
	v_and_b32_e32 v167, 0xffff0000, v171
	v_lshlrev_b32_e32 v166, 16, v171
	v_pk_fma_f32 v[64:65], v[88:89], v[210:211], v[64:65]
	v_pk_fma_f32 v[68:69], v[92:93], v[218:219], v[68:69]
	v_pk_fma_f32 v[66:67], v[90:91], v[160:161], v[66:67]
	v_pk_fma_f32 v[70:71], v[94:95], v[162:163], v[70:71]
	v_and_b32_e32 v223, 0xffff0000, v174
	v_lshlrev_b32_e32 v222, 16, v174
	v_and_b32_e32 v171, 0xffff0000, v175
	v_lshlrev_b32_e32 v170, 16, v175
	v_pk_fma_f32 v[64:65], v[80:81], v[212:213], v[64:65]
	v_pk_fma_f32 v[68:69], v[84:85], v[220:221], v[68:69]
	v_pk_fma_f32 v[66:67], v[82:83], v[164:165], v[66:67]
	v_pk_fma_f32 v[70:71], v[86:87], v[166:167], v[70:71]
	v_and_b32_e32 v175, 0xffff0000, v148
	v_lshlrev_b32_e32 v174, 16, v148
	v_and_b32_e32 v227, 0xffff0000, v152
	v_lshlrev_b32_e32 v226, 16, v152
	v_and_b32_e32 v229, 0xffff0000, v156
	v_lshlrev_b32_e32 v228, 16, v156
	s_waitcnt lgkmcnt(2)
	v_and_b32_e32 v231, 0xffff0000, v144
	v_lshlrev_b32_e32 v230, 16, v144
	v_and_b32_e32 v233, 0xffff0000, v150
	v_lshlrev_b32_e32 v232, 16, v150
	v_and_b32_e32 v241, 0xffff0000, v149
	v_lshlrev_b32_e32 v240, 16, v149
	v_and_b32_e32 v149, 0xffff0000, v153
	v_lshlrev_b32_e32 v148, 16, v153
	v_and_b32_e32 v153, 0xffff0000, v157
	v_lshlrev_b32_e32 v152, 16, v157
	v_and_b32_e32 v157, 0xffff0000, v145
	v_lshlrev_b32_e32 v156, 16, v145
	v_and_b32_e32 v145, 0xffff0000, v151
	v_lshlrev_b32_e32 v144, 16, v151
	v_pk_fma_f32 v[72:73], v[72:73], v[214:215], v[64:65]
	v_pk_fma_f32 v[76:77], v[76:77], v[222:223], v[68:69]
	v_pk_fma_f32 v[74:75], v[74:75], v[168:169], v[66:67]
	v_pk_fma_f32 v[78:79], v[78:79], v[170:171], v[70:71]
	v_and_b32_e32 v235, 0xffff0000, v154
	v_lshlrev_b32_e32 v234, 16, v154
	v_and_b32_e32 v151, 0xffff0000, v155
	v_lshlrev_b32_e32 v150, 16, v155
	v_cvt_pk_bf16_f32 v64, v72, v73
	v_cvt_pk_bf16_f32 v65, v74, v75
	v_cvt_pk_bf16_f32 v66, v76, v77
	v_cvt_pk_bf16_f32 v67, v78, v79
	v_pk_fma_f32 v[88:89], v[136:137], v[174:175], v[104:105]
	v_pk_fma_f32 v[90:91], v[140:141], v[232:233], v[108:109]
	v_pk_fma_f32 v[92:93], v[138:139], v[240:241], v[106:107]
	v_pk_fma_f32 v[94:95], v[142:143], v[144:145], v[110:111]
	v_and_b32_e32 v237, 0xffff0000, v158
	v_lshlrev_b32_e32 v236, 16, v158
	v_and_b32_e32 v155, 0xffff0000, v159
	v_lshlrev_b32_e32 v154, 16, v159
	v_pk_fma_f32 v[96:97], v[132:133], v[226:227], v[88:89]
	v_pk_fma_f32 v[98:99], v[128:129], v[234:235], v[90:91]
	v_pk_fma_f32 v[100:101], v[134:135], v[148:149], v[92:93]
	v_pk_fma_f32 v[102:103], v[130:131], v[150:151], v[94:95]
	v_and_b32_e32 v239, 0xffff0000, v146
	v_lshlrev_b32_e32 v238, 16, v146
	v_and_b32_e32 v159, 0xffff0000, v147
	v_lshlrev_b32_e32 v158, 16, v147
	v_pk_fma_f32 v[96:97], v[120:121], v[228:229], v[96:97]
	v_pk_fma_f32 v[98:99], v[124:125], v[236:237], v[98:99]
	v_pk_fma_f32 v[106:107], v[122:123], v[152:153], v[100:101]
	v_pk_fma_f32 v[108:109], v[126:127], v[154:155], v[102:103]
	s_waitcnt lgkmcnt(1)
	v_pk_fma_f32 v[96:97], v[112:113], v[230:231], v[96:97]
	s_waitcnt lgkmcnt(0)
	v_pk_fma_f32 v[104:105], v[116:117], v[238:239], v[98:99]
	v_pk_fma_f32 v[98:99], v[114:115], v[156:157], v[106:107]
	v_pk_fma_f32 v[106:107], v[118:119], v[158:159], v[108:109]
	v_cvt_pk_bf16_f32 v112, v96, v97
	v_cvt_pk_bf16_f32 v113, v98, v99
	v_cvt_pk_bf16_f32 v114, v104, v105
	v_cvt_pk_bf16_f32 v115, v106, v107
	s_waitcnt vmcnt(15)
	v_mfma_f32_16x16x32_bf16 v[68:71], v[64:67], v[0:3], 0
	v_lshl_add_u64 v[184:185], v[180:181], 0, s[2:3]
	v_add_co_u32_e32 v206, vcc, 0xb000000, v184
	s_waitcnt vmcnt(13)
	v_mfma_f32_16x16x32_bf16 v[80:83], v[64:67], v[8:11], 0
	v_addc_co_u32_e32 v207, vcc, 0, v185, vcc
	s_add_u32 s2, s2, 0x8000
	s_waitcnt vmcnt(11)
	v_mfma_f32_16x16x32_bf16 v[84:87], v[64:67], v[16:19], 0
	v_add_co_u32_e64 v186, s[0:1], s4, v184
	s_addc_u32 s3, s3, 0
	s_waitcnt vmcnt(9)
	v_mfma_f32_16x16x32_bf16 v[88:91], v[64:67], v[24:27], 0
	v_add_u32_e32 v189, 0x900, v189
	v_addc_co_u32_e64 v187, s[0:1], 0, v185, s[0:1]
	s_waitcnt vmcnt(7)
	v_mfma_f32_16x16x32_bf16 v[92:95], v[64:67], v[32:35], 0
	s_cmp_eq_u32 s2, 0x20000
	s_waitcnt vmcnt(5)
	v_mfma_f32_16x16x32_bf16 v[100:103], v[64:67], v[40:43], 0
	s_waitcnt vmcnt(3)
	v_mfma_f32_16x16x32_bf16 v[108:111], v[64:67], v[48:51], 0
	s_waitcnt vmcnt(1)
	v_mfma_f32_16x16x32_bf16 v[116:119], v[64:67], v[56:59], 0
	v_mfma_f32_16x16x32_bf16 v[120:123], v[112:115], v[4:7], v[68:71]
	s_nop 2
	global_load_dwordx4 v[68:71], v[206:207], off
	global_load_dwordx4 v[64:67], v[206:207], off offset:64
	ds_write_b128 v190, v[72:75]
	ds_write_b128 v190, v[76:79] offset:16
	ds_write_b128 v190, v[96:99] offset:128
	ds_write_b128 v190, v[104:107] offset:144
	v_mfma_f32_16x16x32_bf16 v[96:99], v[112:115], v[52:55], v[108:111]
	ds_read2_b32 v[74:75], v191 offset1:16
	ds_read2_b32 v[104:105], v191 offset0:68 offset1:84
	ds_read2_b32 v[106:107], v191 offset0:136 offset1:152
	ds_read2_b32 v[124:125], v191 offset0:204 offset1:220
	ds_read2_b32 v[72:73], v191 offset0:32 offset1:48
	ds_read2_b32 v[108:109], v191 offset0:100 offset1:116
	ds_read2_b32 v[110:111], v191 offset0:168 offset1:184
	ds_read2_b32 v[126:127], v191 offset0:236 offset1:252
	v_mfma_f32_16x16x32_bf16 v[80:83], v[112:115], v[12:15], v[80:83]
	v_add_f32_e32 v98, v199, v98
	v_mul_f32_e32 v98, 0xbfb8aa3b, v98
	v_add_f32_e32 v96, v199, v96
	v_mfma_f32_16x16x32_bf16 v[84:87], v[112:115], v[20:23], v[84:87]
	v_add_f32_e32 v97, v199, v97
	s_nop 2
	v_add_f32_e32 v80, v194, v80
	v_add_f32_e32 v81, v194, v81
	v_mfma_f32_16x16x32_bf16 v[76:79], v[112:115], v[36:39], v[92:95]
	v_add_f32_e32 v82, v194, v82
	v_add_f32_e32 v84, v195, v84
	v_add_f32_e32 v85, v195, v85
	v_mfma_f32_16x16x32_bf16 v[92:95], v[112:115], v[44:47], v[100:103]
	v_add_f32_e32 v86, v195, v86
	s_nop 2
	v_add_f32_e32 v76, v197, v76
	v_add_f32_e32 v77, v197, v77
	s_waitcnt vmcnt(2)
	v_mfma_f32_16x16x32_bf16 v[100:103], v[112:115], v[60:63], v[116:119]
	v_add_f32_e32 v78, v197, v78
	v_add_f32_e32 v79, v197, v79
	v_add_f32_e32 v92, v198, v92
	v_mfma_f32_16x16x32_bf16 v[88:91], v[112:115], v[28:31], v[88:91]
	v_add_f32_e32 v112, v193, v120
	v_mul_f32_e32 v112, 0xbfb8aa3b, v112
	v_add_f32_e32 v114, v193, v122
	v_add_f32_e32 v93, v198, v93
	v_add_f32_e32 v94, v198, v94
	v_add_f32_e32 v95, v198, v95
	v_exp_f32_e32 v112, v112
	v_add_f32_e32 v113, v193, v121
	v_add_f32_e32 v100, v200, v100
	v_add_f32_e32 v101, v200, v101
	v_add_f32_e32 v102, v200, v102
	v_mul_f32_e32 v76, 0xbfb8aa3b, v76
	v_mul_f32_e32 v77, 0xbfb8aa3b, v77
	v_mul_f32_e32 v114, 0xbfb8aa3b, v114
	v_mul_f32_e32 v78, 0xbfb8aa3b, v78
	v_mul_f32_e32 v79, 0xbfb8aa3b, v79
	v_mul_f32_e32 v80, 0xbfb8aa3b, v80
	v_mul_f32_e32 v92, 0xbfb8aa3b, v92
	v_mul_f32_e32 v81, 0xbfb8aa3b, v81
	v_mul_f32_e32 v93, 0xbfb8aa3b, v93
	v_mul_f32_e32 v82, 0xbfb8aa3b, v82
	v_mul_f32_e32 v94, 0xbfb8aa3b, v94
	v_mul_f32_e32 v95, 0xbfb8aa3b, v95
	v_mul_f32_e32 v84, 0xbfb8aa3b, v84
	v_mul_f32_e32 v85, 0xbfb8aa3b, v85
	v_exp_f32_e32 v98, v98
	v_add_f32_e32 v83, v194, v83
	v_add_f32_e32 v87, v195, v87
	v_add_f32_e32 v99, v199, v99
	v_add_f32_e32 v88, v196, v88
	v_add_f32_e32 v89, v196, v89
	v_add_f32_e32 v90, v196, v90
	v_mul_f32_e32 v113, 0xbfb8aa3b, v113
	v_mul_f32_e32 v96, 0xbfb8aa3b, v96
	v_mul_f32_e32 v97, 0xbfb8aa3b, v97
	v_mul_f32_e32 v86, 0xbfb8aa3b, v86
	v_mul_f32_e32 v100, 0xbfb8aa3b, v100
	v_mul_f32_e32 v101, 0xbfb8aa3b, v101
	v_mul_f32_e32 v102, 0xbfb8aa3b, v102
	v_exp_f32_e32 v76, v76
	v_exp_f32_e32 v77, v77
	v_exp_f32_e32 v114, v114
	v_exp_f32_e32 v78, v78
	v_exp_f32_e32 v79, v79
	v_exp_f32_e32 v80, v80
	v_exp_f32_e32 v92, v92
	v_exp_f32_e32 v81, v81
	v_exp_f32_e32 v93, v93
	v_exp_f32_e32 v82, v82
	v_exp_f32_e32 v94, v94
	v_exp_f32_e32 v95, v95
	v_exp_f32_e32 v84, v84
	v_exp_f32_e32 v85, v85
	v_add_f32_e32 v103, v200, v103
	v_mul_f32_e32 v83, 0xbfb8aa3b, v83
	v_mul_f32_e32 v87, 0xbfb8aa3b, v87
	v_mul_f32_e32 v99, 0xbfb8aa3b, v99
	v_mul_f32_e32 v88, 0xbfb8aa3b, v88
	v_mul_f32_e32 v89, 0xbfb8aa3b, v89
	v_mul_f32_e32 v90, 0xbfb8aa3b, v90
	v_exp_f32_e32 v113, v113
	v_exp_f32_e32 v96, v96
	v_exp_f32_e32 v97, v97
	v_exp_f32_e32 v86, v86
	v_exp_f32_e32 v100, v100
	v_exp_f32_e32 v101, v101
	v_exp_f32_e32 v102, v102
	v_add_f32_e32 v115, v193, v123
	v_add_f32_e32 v91, v196, v91
	v_mul_f32_e32 v103, 0xbfb8aa3b, v103
	v_exp_f32_e32 v83, v83
	v_exp_f32_e32 v87, v87
	v_exp_f32_e32 v99, v99
	v_exp_f32_e32 v88, v88
	v_exp_f32_e32 v89, v89
	v_exp_f32_e32 v90, v90
	v_add_f32_e32 v112, 1.0, v112
	v_mul_f32_e32 v115, 0xbfb8aa3b, v115
	v_mul_f32_e32 v91, 0xbfb8aa3b, v91
	v_exp_f32_e32 v103, v103
	v_add_f32_e32 v98, 1.0, v98
	v_rcp_f32_e32 v112, v112
	v_exp_f32_e32 v115, v115
	v_exp_f32_e32 v91, v91
	v_add_f32_e32 v76, 1.0, v76
	v_add_f32_e32 v77, 1.0, v77
	v_add_f32_e32 v114, 1.0, v114
	v_add_f32_e32 v78, 1.0, v78
	v_add_f32_e32 v79, 1.0, v79
	v_add_f32_e32 v80, 1.0, v80
	v_add_f32_e32 v92, 1.0, v92
	v_add_f32_e32 v81, 1.0, v81
	v_add_f32_e32 v93, 1.0, v93
	v_add_f32_e32 v82, 1.0, v82
	v_add_f32_e32 v94, 1.0, v94
	v_add_f32_e32 v95, 1.0, v95
	v_add_f32_e32 v84, 1.0, v84
	v_add_f32_e32 v85, 1.0, v85
	v_rcp_f32_e32 v98, v98
	v_add_f32_e32 v113, 1.0, v113
	v_add_f32_e32 v96, 1.0, v96
	v_add_f32_e32 v97, 1.0, v97
	v_add_f32_e32 v86, 1.0, v86
	v_add_f32_e32 v100, 1.0, v100
	v_add_f32_e32 v101, 1.0, v101
	v_add_f32_e32 v102, 1.0, v102
	v_rcp_f32_e32 v76, v76
	v_rcp_f32_e32 v77, v77
	v_rcp_f32_e32 v114, v114
	v_rcp_f32_e32 v78, v78
	v_rcp_f32_e32 v79, v79
	v_rcp_f32_e32 v80, v80
	v_rcp_f32_e32 v137, v92
	v_rcp_f32_e32 v81, v81
	v_rcp_f32_e32 v92, v93
	v_rcp_f32_e32 v82, v82
	v_rcp_f32_e32 v93, v94
	v_rcp_f32_e32 v94, v95
	v_rcp_f32_e32 v95, v84
	v_rcp_f32_e32 v85, v85
	v_add_f32_e32 v83, 1.0, v83
	v_add_f32_e32 v87, 1.0, v87
	v_add_f32_e32 v99, 1.0, v99
	v_add_f32_e32 v88, 1.0, v88
	v_add_f32_e32 v89, 1.0, v89
	v_add_f32_e32 v90, 1.0, v90
	v_rcp_f32_e32 v113, v113
	v_rcp_f32_e32 v141, v96
	v_rcp_f32_e32 v96, v97
	v_rcp_f32_e32 v97, v86
	v_rcp_f32_e32 v143, v100
	v_rcp_f32_e32 v100, v101
	v_rcp_f32_e32 v102, v102
	v_add_f32_e32 v103, 1.0, v103
	v_rcp_f32_e32 v83, v83
	v_rcp_f32_e32 v87, v87
	v_rcp_f32_e32 v99, v99
	v_rcp_f32_e32 v116, v88
	v_rcp_f32_e32 v89, v89
	v_rcp_f32_e32 v101, v90
	v_mul_f32_e32 v112, v201, v112
	v_add_f32_e32 v115, 1.0, v115
	v_add_f32_e32 v91, 1.0, v91
	v_rcp_f32_e32 v103, v103
	s_waitcnt lgkmcnt(1)
	v_mul_f32_e32 v88, v98, v110
	v_exp_f32_e32 v98, v112
	v_rcp_f32_e32 v115, v115
	v_rcp_f32_e32 v91, v91
	v_mul_f32_e32 v183, v76, v74
	v_mul_f32_e32 v74, v77, v104
	v_mul_f32_e32 v77, v201, v114
	v_mul_f32_e32 v76, v78, v106
	v_mul_f32_e32 v78, v79, v124
	v_mul_f32_e32 v79, v202, v80
	v_mul_f32_e32 v81, v202, v81
	v_mul_f32_e32 v114, v202, v82
	v_mul_f32_e32 v82, v93, v107
	v_mul_f32_e32 v93, v203, v95
	v_mul_f32_e32 v85, v203, v85
	v_mul_f32_e32 v113, v201, v113
	v_mul_f32_e32 v80, v92, v105
	v_mul_f32_e32 v84, v94, v125
	v_mul_f32_e32 v95, v203, v97
	v_mul_f32_e32 v92, v100, v109
	v_mul_f32_e32 v94, v102, v111
	v_exp_f32_e32 v106, v79
	v_exp_f32_e32 v109, v81
	v_exp_f32_e32 v111, v114
	v_exp_f32_e32 v114, v93
	v_exp_f32_e32 v117, v85
	v_mul_f32_e32 v83, v202, v83
	v_mul_f32_e32 v87, v203, v87
	s_waitcnt lgkmcnt(0)
	v_mul_f32_e32 v90, v99, v126
	v_mul_f32_e32 v97, v204, v116
	v_mul_f32_e32 v89, v204, v89
	v_mul_f32_e32 v99, v204, v101
	v_exp_f32_e32 v101, v113
	v_exp_f32_e32 v119, v95
	v_mul_f32_e32 v86, v96, v108
	v_mul_f32_e32 v96, v103, v127
	v_exp_f32_e32 v103, v77
	v_exp_f32_e32 v113, v83
	v_exp_f32_e32 v121, v87
	v_exp_f32_e32 v122, v97
	v_exp_f32_e32 v125, v89
	v_fma_f32 v77, -v98, v98, 1.0
	v_mul_f32_e32 v104, v201, v115
	v_mul_f32_e32 v91, v204, v91
	v_exp_f32_e32 v127, v99
	v_sqrt_f32_e32 v99, v77
	v_exp_f32_e32 v105, v104
	v_exp_f32_e32 v129, v91
	v_fma_f32 v85, -v106, v106, 1.0
	v_mul_f32_e32 v145, v106, v109
	v_mul_f32_e32 v146, v114, v117
	v_fma_f32 v79, -v101, v101, 1.0
	v_sqrt_f32_e32 v107, v85
	v_mul_f32_e32 v149, v111, v145
	v_mul_f32_e32 v150, v119, v146
	v_mul_f32_e32 v144, v98, v101
	v_fma_f32 v81, -v103, v103, 1.0
	v_fma_f32 v93, -v114, v114, 1.0
	v_mul_f32_e32 v147, v122, v125
	v_sqrt_f32_e32 v100, v79
	v_mul_f32_e32 v153, v113, v149
	v_mul_f32_e32 v154, v121, v150
	v_fma_f32 v87, -v109, v109, 1.0
	v_sqrt_f32_e32 v102, v81
	v_mul_f32_e32 v148, v103, v144
	v_sqrt_f32_e32 v115, v93
	v_mul_f32_e32 v151, v127, v147
	v_mov_b32_e32 v79, v153
	v_mov_b32_e32 v156, v153
	v_mov_b32_e32 v81, v154
	v_mov_b32_e32 v157, v154
	v_mul_f32_e32 v130, v99, v183
	v_fma_f32 v83, -v105, v105, 1.0
	v_fma_f32 v97, -v119, v119, 1.0
	v_fma_f32 v123, -v122, v122, 1.0
	v_sqrt_f32_e32 v108, v87
	v_mul_f32_e32 v152, v105, v148
	v_mul_f32_e32 v155, v129, v151
	v_permlane16_swap_b32_e32 v79, v156
	v_permlane16_swap_b32_e32 v81, v157
	v_pk_fma_f32 v[130:131], v[98:99], v[182:183], v[130:131] op_sel_hi:[1,1,0]
	v_mul_f32_e32 v183, v137, v75
	v_fma_f32 v89, -v111, v111, 1.0
	v_fma_f32 v95, -v117, v117, 1.0
	v_sqrt_f32_e32 v104, v83
	v_sqrt_f32_e32 v118, v97
	v_sqrt_f32_e32 v123, v123
	v_mov_b32_e32 v77, v152
	v_mov_b32_e32 v97, v152
	v_mov_b32_e32 v83, v155
	v_mov_b32_e32 v158, v155
	v_mul_f32_e32 v133, v79, v156
	v_mul_f32_e32 v134, v81, v157
	v_mov_b32_e32 v75, v130
	v_mul_f32_e32 v140, v101, v130
	v_mul_f32_e32 v142, v107, v183
	v_sqrt_f32_e32 v110, v89
	v_sqrt_f32_e32 v116, v95
	v_permlane16_swap_b32_e32 v77, v97
	v_permlane16_swap_b32_e32 v83, v158
	v_mov_b32_e32 v137, v133
	v_mov_b32_e32 v138, v134
	v_pk_fma_f32 v[74:75], v[100:101], v[74:75], v[140:141] op_sel_hi:[1,1,0]
	v_pk_fma_f32 v[100:101], v[106:107], v[182:183], v[142:143] op_sel_hi:[1,1,0]
	v_mul_f32_e32 v183, v141, v72
	v_fma_f32 v91, -v113, v113, 1.0
	v_fma_f32 v124, -v125, v125, 1.0
	v_mul_f32_e32 v132, v77, v97
	v_cndmask_b32_e64 v159, v77, 1.0, s[6:7]
	v_cndmask_b32_e64 v161, v81, 1.0, s[6:7]
	v_mul_f32_e32 v135, v83, v158
	v_permlane32_swap_b32_e32 v133, v137
	v_permlane32_swap_b32_e32 v134, v138
	v_mov_b32_e32 v77, v74
	v_mul_f32_e32 v72, v103, v74
	v_mov_b32_e32 v81, v100
	v_mul_f32_e32 v140, v109, v100
	v_mul_f32_e32 v142, v115, v183
	v_sqrt_f32_e32 v112, v91
	v_sqrt_f32_e32 v124, v124
	v_cndmask_b32_e64 v160, v79, 1.0, s[6:7]
	v_cndmask_b32_e64 v162, v83, 1.0, s[6:7]
	v_mov_b32_e32 v139, v135
	v_cndmask_b32_e64 v79, v133, 1.0, s[8:9]
	v_cndmask_b32_e64 v83, v134, 1.0, s[8:9]
	v_pk_fma_f32 v[76:77], v[102:103], v[76:77], v[72:73] op_sel_hi:[1,1,0]
	v_pk_fma_f32 v[80:81], v[108:109], v[80:81], v[140:141] op_sel_hi:[1,1,0]
	v_pk_fma_f32 v[102:103], v[114:115], v[182:183], v[142:143] op_sel_hi:[1,1,0]
	v_mul_f32_e32 v183, v143, v73
	v_fma_f32 v126, -v127, v127, 1.0
	v_permlane32_swap_b32_e32 v135, v139
	v_mul_f32_e32 v99, v160, v79
	v_mul_f32_e32 v101, v161, v83
	v_mov_b32_e32 v79, v76
	v_mov_b32_e32 v83, v80
	v_mul_f32_e32 v72, v111, v80
	v_mov_b32_e32 v87, v102
	v_mul_f32_e32 v108, v117, v102
	v_mul_f32_e32 v140, v123, v183
	v_fma_f32 v120, -v121, v121, 1.0
	v_sqrt_f32_e32 v126, v126
	v_cndmask_b32_e64 v85, v135, 1.0, s[8:9]
	v_pk_mul_f32 v[78:79], v[104:105], v[78:79]
	v_pk_fma_f32 v[72:73], v[110:111], v[82:83], v[72:73] op_sel_hi:[1,1,0]
	v_pk_fma_f32 v[82:83], v[116:117], v[86:87], v[108:109] op_sel_hi:[1,1,0]
	v_pk_fma_f32 v[86:87], v[122:123], v[182:183], v[140:141] op_sel_hi:[1,1,0]
	v_fma_f32 v128, -v129, v129, 1.0
	v_sqrt_f32_e32 v120, v120
	v_mul_f32_e32 v107, v162, v85
	v_add_f32_e32 v73, v78, v79
	v_mov_b32_e32 v85, v72
	v_mov_b32_e32 v89, v82
	v_mul_f32_e32 v78, v119, v82
	v_mov_b32_e32 v93, v86
	v_mul_f32_e32 v104, v125, v86
	v_sqrt_f32_e32 v128, v128
	v_mov_b32_e32 v77, v73
	v_mov_b32_e32 v108, v73
	v_pk_mul_f32 v[84:85], v[112:113], v[84:85]
	v_pk_fma_f32 v[78:79], v[118:119], v[88:89], v[78:79] op_sel_hi:[1,1,0]
	v_pk_fma_f32 v[88:89], v[124:125], v[92:93], v[104:105] op_sel_hi:[1,1,0]
	v_permlane16_swap_b32_e32 v77, v108
	v_add_f32_e32 v79, v84, v85
	v_mov_b32_e32 v95, v88
	v_mul_f32_e32 v84, v127, v88
	v_mov_b32_e32 v91, v78
	v_fmac_f32_e32 v108, v97, v77
	v_pk_fma_f32 v[84:85], v[126:127], v[94:95], v[84:85] op_sel_hi:[1,1,0]
	v_pk_mul_f32 v[90:91], v[120:121], v[90:91]
	v_mov_b32_e32 v92, v108
	v_mov_b32_e32 v97, v84
	v_add_f32_e32 v83, v90, v91
	v_permlane32_swap_b32_e32 v108, v92
	v_pk_mul_f32 v[94:95], v[128:129], v[96:97]
	v_mov_b32_e32 v136, v132
	v_cndmask_b32_e64 v77, v77, 0, s[6:7]
	v_mov_b32_e32 v81, v79
	v_mov_b32_e32 v109, v79
	v_mov_b32_e32 v85, v83
	v_mov_b32_e32 v90, v83
	v_cndmask_b32_e64 v87, v108, 0, s[8:9]
	v_add_f32_e32 v89, v94, v95
	v_permlane32_swap_b32_e32 v132, v136
	v_permlane16_swap_b32_e32 v81, v109
	v_permlane16_swap_b32_e32 v85, v90
	v_fmac_f32_e32 v77, v159, v87
	v_mov_b32_e32 v87, v89
	v_mov_b32_e32 v91, v89
	v_cndmask_b32_e64 v75, v132, 1.0, s[8:9]
	v_fmac_f32_e32 v109, v156, v81
	v_fmac_f32_e32 v90, v157, v85
	v_permlane16_swap_b32_e32 v87, v91
	v_mul_f32_e32 v75, v159, v75
	v_mov_b32_e32 v93, v109
	v_mov_b32_e32 v94, v90
	v_fmac_f32_e32 v91, v158, v87
	v_permlane32_swap_b32_e32 v109, v93
	v_fmac_f32_e32 v77, v178, v75
	v_permlane32_swap_b32_e32 v90, v94
	v_mov_b32_e32 v95, v91
	v_cndmask_b32_e64 v81, v81, 0, s[6:7]
	v_cndmask_b32_e64 v85, v85, 0, s[6:7]
	v_cndmask_b32_e64 v75, v109, 0, s[8:9]
	v_fmac_f32_e32 v130, v98, v77
	v_fmac_f32_e32 v74, v144, v77
	v_fmac_f32_e32 v76, v148, v77
	v_fmac_f32_e32 v73, v152, v77
	v_cndmask_b32_e64 v77, v90, 0, s[8:9]
	v_permlane32_swap_b32_e32 v91, v95
	v_fmac_f32_e32 v81, v160, v75
	v_cndmask_b32_e64 v75, v87, 0, s[6:7]
	v_fmac_f32_e32 v85, v161, v77
	v_cndmask_b32_e64 v77, v91, 0, s[8:9]
	v_fmac_f32_e32 v75, v162, v77
	v_fmac_f32_e32 v81, v179, v99
	v_fmac_f32_e32 v85, v176, v101
	v_fmac_f32_e32 v75, v177, v107
	v_fmac_f32_e32 v100, v106, v81
	v_fmac_f32_e32 v72, v149, v81
	v_fmac_f32_e32 v102, v114, v85
	v_fmac_f32_e32 v86, v122, v75
	v_pk_mul_f32 v[134:135], v[138:139], v[134:135]
	v_fmac_f32_e32 v80, v145, v81
	v_fmac_f32_e32 v79, v153, v81
	ds_write2_b32 v191, v130, v100 offset1:16
	ds_write2_b32 v191, v74, v80 offset0:68 offset1:84
	ds_write2_b32 v191, v76, v72 offset0:136 offset1:152
	ds_write2_b32 v191, v73, v79 offset0:204 offset1:220
	v_pk_fma_f32 v[72:73], v[138:139], v[90:91], v[94:95]
	v_fmac_f32_e32 v82, v146, v85
	v_fmac_f32_e32 v78, v150, v85
	v_fmac_f32_e32 v83, v154, v85
	v_fmac_f32_e32 v88, v147, v75
	v_fmac_f32_e32 v84, v151, v75
	v_fmac_f32_e32 v89, v155, v75
	ds_write2_b32 v191, v102, v86 offset0:32 offset1:48
	ds_write2_b32 v191, v82, v88 offset0:100 offset1:116
	ds_write2_b32 v191, v78, v84 offset0:168 offset1:184
	ds_write2_b32 v191, v83, v89 offset0:236 offset1:252
	v_pk_fma_f32 v[176:177], v[176:177], v[134:135], v[72:73]
	ds_read_b128 v[72:75], v190
	ds_read_b128 v[76:79], v190 offset:16
	ds_read_b128 v[80:83], v190 offset:128
	ds_read_b128 v[84:87], v190 offset:144
	v_pk_mul_f32 v[132:133], v[136:137], v[132:133]
	v_pk_fma_f32 v[92:93], v[136:137], v[108:109], v[92:93]
	s_waitcnt vmcnt(1)
	v_lshlrev_b32_e32 v88, 16, v68
	v_and_b32_e32 v89, 0xffff0000, v68
	v_lshlrev_b32_e32 v68, 16, v69
	v_and_b32_e32 v69, 0xffff0000, v69
	v_lshlrev_b32_e32 v90, 16, v70
	v_and_b32_e32 v91, 0xffff0000, v70
	v_lshlrev_b32_e32 v70, 16, v71
	v_and_b32_e32 v71, 0xffff0000, v71
	v_pk_fma_f32 v[178:179], v[178:179], v[132:133], v[92:93]
	s_waitcnt vmcnt(0)
	v_lshlrev_b32_e32 v92, 16, v64
	v_and_b32_e32 v93, 0xffff0000, v64
	v_lshlrev_b32_e32 v64, 16, v65
	v_and_b32_e32 v65, 0xffff0000, v65
	v_lshlrev_b32_e32 v94, 16, v66
	v_and_b32_e32 v95, 0xffff0000, v66
	v_lshlrev_b32_e32 v66, 16, v67
	v_and_b32_e32 v67, 0xffff0000, v67
	s_waitcnt lgkmcnt(3)
	v_pk_mul_f32 v[72:73], v[72:73], v[88:89]
	v_pk_mul_f32 v[68:69], v[74:75], v[68:69]
	s_waitcnt lgkmcnt(2)
	v_pk_mul_f32 v[74:75], v[76:77], v[90:91]
	v_pk_mul_f32 v[70:71], v[78:79], v[70:71]
	s_waitcnt lgkmcnt(1)
	v_pk_mul_f32 v[76:77], v[80:81], v[92:93]
	v_pk_mul_f32 v[78:79], v[82:83], v[64:65]
	s_waitcnt lgkmcnt(0)
	v_pk_mul_f32 v[80:81], v[84:85], v[94:95]
	v_pk_mul_f32 v[82:83], v[86:87], v[66:67]
	v_cvt_pk_bf16_f32 v64, v72, v73
	v_cvt_pk_bf16_f32 v65, v68, v69
	v_cvt_pk_bf16_f32 v66, v74, v75
	v_cvt_pk_bf16_f32 v67, v70, v71
	v_cvt_pk_bf16_f32 v68, v76, v77
	v_cvt_pk_bf16_f32 v69, v78, v79
	v_cvt_pk_bf16_f32 v70, v80, v81
	v_cvt_pk_bf16_f32 v71, v82, v83
	global_store_dwordx4 v[186:187], v[64:67], off sc1
	global_store_dwordx4 v[186:187], v[68:71], off offset:64 sc1
	s_cbranch_scc0 .LBB0_1296
